# GEMM K loops: set-up mid MFMA block + merged waits + static priority for waves 4-7, combined
# baseline (speedup 1.0000x reference)
; #define STAGE(bufoff, gbase, voff) do { _Pragma("unroll") for (int _i = 0; _i < 2; ++_i) \
;     __builtin_amdgcn_global_load_lds((const unsigned*)((const char*)(gbase) + (voff)[_i]), (LAS unsigned*)(lds + (bufoff) + ldsw + _i * 8192), 16, 0, 0); } while (0)
; #define LDA(dst, b, h) do { _Pragma("unroll") for (int m = 0; m < 4; ++m) _Pragma("unroll") for (int k = 0; k < 2; ++k) dst[m][k] = *(const LAS half8*)(lds + SA(b, h) + aoff + m * 2048 + k * 1024); } while (0)
; #define LDB(dst, b, h) do { _Pragma("unroll") for (int n = 0; n < 2; ++n) _Pragma("unroll") for (int k = 0; k < 2; ++k) dst[n][k] = *(const LAS half8*)(lds + SB(b, h) + boff + n * 2048 + k * 1024); } while (0)
; #define MMA(ai, bj, At_, Bt_) do { __builtin_amdgcn_s_setprio(1); \
;     _Pragma("unroll") for (int m = 0; m < 4; ++m) _Pragma("unroll") for (int n = 0; n < 2; ++n) _Pragma("unroll") for (int k = 0; k < 2; ++k) \
;       acc[ai][bj][m][n] = MFMA16(Bt_[n][k], At_[m][k], acc[ai][bj][m][n]); \
;     __builtin_amdgcn_s_setprio(0); } while (0)
; #define WAIT_V(n) asm volatile("s_waitcnt vmcnt(" #n ")" ::: "memory")
; #define WAIT_L(n) asm volatile("s_waitcnt lgkmcnt(" #n ")" ::: "memory")
; #define BAR __builtin_amdgcn_s_barrier()
; template <int EPI>
; DI void gemm_phase(const int wid_s, const h16* __restrict__ A, const h16* __restrict__ Bt, const int N, const int K, const EpiArgs ea) {
;     ...
;     const int Ln = L + (int)gridDim.x;
;     const bool has_next = Ln < nwg;
;     int nbrow = brow, nbcol = bcol;
;     if (has_next) TILE_RC(Ln, nbrow, nbcol);
;     const char* nA = (const char*)A + (size_t)nbrow * K * 2;
;     const char* nB = (const char*)Bt + (size_t)nbcol * K * 2;
;     for (int t = 0; t < nt; t += 2) {
;       const bool last = (t == nt - 2);
;       const char* a1 = cA + (size_t)(t + 1) * kstep;
;       const char* a2 = last ? nA : cA + (size_t)(t + 2) * kstep; const char* b2 = last ? nB : cB + (size_t)(t + 2) * kstep;
;       const char* a3 = a2 + kstep; const char* b3 = b2 + kstep;
;       LDB(B0, 0, 0); LDB(B1, 0, 1); SCHED; LDA(At, 0, 0); STAGE(SA(1, 1), a1 + hstep, voffA);
;       WAIT_V(8); WAIT_L(0); BAR; MMA(0, 0, At, B0); MMA(0, 1, At, B1); BAR; SCHED;
;       LDA(At, 0, 1); STAGE(SB(0, 0), b2, voffB); STAGE(SB(0, 1), b2 + hstep, voffB); STAGE(SA(0, 0), a2, voffA);
;       WAIT_V(8); WAIT_L(0); BAR; MMA(1, 0, At, B0); MMA(1, 1, At, B1); BAR; SCHED;
.LBB0_121:
	s_mul_i32 s8, s31, 0x1600
	s_mul_hi_i32 s9, s31, 0x1600
	s_add_u32 s8, s28, s8
	s_addc_u32 s9, s29, s9
	s_mul_i32 s10, s38, 0x1600
	v_readlane_b32 s16, v250, 58
	s_mul_hi_i32 s11, s38, 0x1600
	s_add_u32 s41, s16, s10
	v_readlane_b32 s16, v250, 61
	s_addc_u32 s42, s16, s11
	v_readlane_b32 s16, v249, 21
	s_add_u32 s43, s16, s14
	v_readlane_b32 s14, v249, 22
	v_mov_b32_e32 v6, 0
	s_addc_u32 s44, s14, s15
	s_mov_b32 s45, -2
	s_add_u32 s14, s12, 0x100
	s_addc_u32 s15, s13, 0
	s_add_i32 s46, 0, 0x10000
	s_cmp_eq_u32 s45, 40
	s_cselect_b32 s19, s9, s15
	s_cselect_b32 s18, s8, s14
	v_add_u32_e32 v177, s46, v148
	s_cselect_b32 s17, s42, s44
	s_cselect_b32 s16, s41, s43
	s_add_i32 s47, 0, 0x14000
	ds_read_b128 v[144:147], v177
	ds_read_b128 v[152:155], v177 offset:1024
	ds_read_b128 v[178:181], v177 offset:2048
	ds_read_b128 v[182:185], v177 offset:3072
	v_add_u32_e32 v177, s47, v148
	ds_read_b128 v[186:189], v177
	ds_read_b128 v[190:193], v177 offset:1024
	ds_read_b128 v[194:197], v177 offset:2048
	ds_read_b128 v[198:201], v177 offset:3072
	v_lshl_add_u64 v[234:235], s[12:13], 0, v[142:143]
	s_add_i32 m0, s22, 0xc000
	ds_read_b128 v[202:205], v151
	ds_read_b128 v[206:209], v151 offset:1024
	ds_read_b128 v[210:213], v151 offset:2048
	ds_read_b128 v[214:217], v151 offset:3072
	ds_read_b128 v[218:221], v151 offset:4096
	ds_read_b128 v[222:225], v151 offset:5120
	ds_read_b128 v[226:229], v151 offset:6144
	ds_read_b128 v[230:233], v151 offset:7168
	global_load_lds_dwordx4 v[234:235], off
	v_lshl_add_u64 v[234:235], s[12:13], 0, v[140:141]
	s_add_i32 m0, s22, 0xe000
	s_nop 0
	global_load_lds_dwordx4 v[234:235], off
	s_waitcnt vmcnt(8) lgkmcnt(0)
	s_barrier
	v_mfma_f32_16x16x32_f16 v[130:133], v[144:147], v[202:205], 0
	v_mfma_f32_16x16x32_f16 v[126:129], v[178:181], v[202:205], 0
	v_mfma_f32_16x16x32_f16 v[114:117], v[144:147], v[210:213], 0
	v_mfma_f32_16x16x32_f16 v[110:113], v[178:181], v[210:213], 0
	v_mfma_f32_16x16x32_f16 v[98:101], v[144:147], v[218:221], 0
	v_mfma_f32_16x16x32_f16 v[94:97], v[178:181], v[218:221], 0
	v_mfma_f32_16x16x32_f16 v[82:85], v[144:147], v[226:229], 0
	v_mfma_f32_16x16x32_f16 v[78:81], v[178:181], v[226:229], 0
	v_mfma_f32_16x16x32_f16 v[130:133], v[152:155], v[206:209], v[130:133]
	v_mfma_f32_16x16x32_f16 v[126:129], v[182:185], v[206:209], v[126:129]
	v_mfma_f32_16x16x32_f16 v[114:117], v[152:155], v[214:217], v[114:117]
	v_mfma_f32_16x16x32_f16 v[110:113], v[182:185], v[214:217], v[110:113]
	v_mfma_f32_16x16x32_f16 v[98:101], v[152:155], v[222:225], v[98:101]
	v_mfma_f32_16x16x32_f16 v[94:97], v[182:185], v[222:225], v[94:97]
	v_mfma_f32_16x16x32_f16 v[82:85], v[152:155], v[230:233], v[82:85]
	v_mfma_f32_16x16x32_f16 v[78:81], v[182:185], v[230:233], v[78:81]
	s_add_i32 s12, s46, s21
	v_lshl_add_u64 v[234:235], s[16:17], 0, v[0:1]
	s_mov_b32 m0, s12
	v_mfma_f32_16x16x32_f16 v[122:125], v[186:189], v[202:205], 0
	v_mfma_f32_16x16x32_f16 v[118:121], v[194:197], v[202:205], 0
	v_mfma_f32_16x16x32_f16 v[106:109], v[186:189], v[210:213], 0
	v_mfma_f32_16x16x32_f16 v[102:105], v[194:197], v[210:213], 0
	v_mfma_f32_16x16x32_f16 v[90:93], v[186:189], v[218:221], 0
	v_mfma_f32_16x16x32_f16 v[86:89], v[194:197], v[218:221], 0
	v_mfma_f32_16x16x32_f16 v[74:77], v[186:189], v[226:229], 0
	v_mfma_f32_16x16x32_f16 v[70:73], v[194:197], v[226:229], 0
	v_mfma_f32_16x16x32_f16 v[122:125], v[190:193], v[206:209], v[122:125]
	v_mfma_f32_16x16x32_f16 v[118:121], v[198:201], v[206:209], v[118:121]
	v_mfma_f32_16x16x32_f16 v[106:109], v[190:193], v[214:217], v[106:109]
	v_mfma_f32_16x16x32_f16 v[102:105], v[198:201], v[214:217], v[102:105]
	v_mfma_f32_16x16x32_f16 v[90:93], v[190:193], v[222:225], v[90:93]
	v_mfma_f32_16x16x32_f16 v[86:89], v[198:201], v[222:225], v[86:89]
	v_mfma_f32_16x16x32_f16 v[74:77], v[190:193], v[230:233], v[74:77]
	v_mfma_f32_16x16x32_f16 v[70:73], v[198:201], v[230:233], v[70:73]
	s_barrier
	ds_read_b128 v[202:205], v151 offset:16384
	ds_read_b128 v[206:209], v151 offset:17408
	ds_read_b128 v[210:213], v151 offset:18432
	ds_read_b128 v[214:217], v151 offset:19456
	ds_read_b128 v[218:221], v151 offset:20480
	ds_read_b128 v[222:225], v151 offset:21504
	ds_read_b128 v[226:229], v151 offset:22528
	ds_read_b128 v[230:233], v151 offset:23552
	global_load_lds_dwordx4 v[234:235], off
	s_add_i32 m0, s12, 0x2000
	s_add_u32 s12, s16, 0xb0000
	v_lshl_add_u64 v[236:237], s[16:17], 0, v[138:139]
	s_addc_u32 s13, s17, 0
	s_add_i32 s46, s47, s21
	global_load_lds_dwordx4 v[236:237], off
	v_lshl_add_u64 v[238:239], s[12:13], 0, v[0:1]
	s_mov_b32 m0, s46
	v_lshl_add_u64 v[240:241], s[18:19], 0, v[134:135]
	global_load_lds_dwordx4 v[238:239], off
	v_lshl_add_u64 v[238:239], s[12:13], 0, v[138:139]
	s_add_i32 m0, s46, 0x2000
	s_nop 0
	global_load_lds_dwordx4 v[238:239], off
	v_lshl_add_u64 v[238:239], s[18:19], 0, v[2:3]
	s_mov_b32 m0, s22
	s_nop 0
	global_load_lds_dwordx4 v[238:239], off
	s_mov_b32 m0, s23
	s_nop 0
	global_load_lds_dwordx4 v[240:241], off
	s_waitcnt vmcnt(8) lgkmcnt(0)
	s_barrier
; #define STAGE(bufoff, gbase, voff) do { _Pragma("unroll") for (int _i = 0; _i < 2; ++_i) \
;     __builtin_amdgcn_global_load_lds((const unsigned*)((const char*)(gbase) + (voff)[_i]), (LAS unsigned*)(lds + (bufoff) + ldsw + _i * 8192), 16, 0, 0); } while (0)
; #define LDA(dst, b, h) do { _Pragma("unroll") for (int m = 0; m < 4; ++m) _Pragma("unroll") for (int k = 0; k < 2; ++k) dst[m][k] = *(const LAS half8*)(lds + SA(b, h) + aoff + m * 2048 + k * 1024); } while (0)
; #define LDB(dst, b, h) do { _Pragma("unroll") for (int n = 0; n < 2; ++n) _Pragma("unroll") for (int k = 0; k < 2; ++k) dst[n][k] = *(const LAS half8*)(lds + SB(b, h) + boff + n * 2048 + k * 1024); } while (0)
; #define MMA(ai, bj, At_, Bt_) do { __builtin_amdgcn_s_setprio(1); \
;     _Pragma("unroll") for (int m = 0; m < 4; ++m) _Pragma("unroll") for (int n = 0; n < 2; ++n) _Pragma("unroll") for (int k = 0; k < 2; ++k) \
;       acc[ai][bj][m][n] = MFMA16(Bt_[n][k], At_[m][k], acc[ai][bj][m][n]); \
;     __builtin_amdgcn_s_setprio(0); } while (0)
; #define WAIT_V(n) asm volatile("s_waitcnt vmcnt(" #n ")" ::: "memory")
; #define WAIT_L(n) asm volatile("s_waitcnt lgkmcnt(" #n ")" ::: "memory")
; #define BAR __builtin_amdgcn_s_barrier()
; #define SCHED __builtin_amdgcn_sched_barrier(0)
; template <int EPI>
; DI void gemm_phase(const int wid_s, const h16* __restrict__ A, const h16* __restrict__ Bt, const int N, const int K, const EpiArgs ea) {
;     ...
;       LDB(B0, 0, 0); LDB(B1, 0, 1); SCHED; LDA(At, 0, 0); STAGE(SA(1, 1), a1 + hstep, voffA);
;       WAIT_V(8); WAIT_L(0); BAR; MMA(0, 0, At, B0); MMA(0, 1, At, B1); BAR; SCHED;
;       LDA(At, 0, 1); STAGE(SB(0, 0), b2, voffB); STAGE(SB(0, 1), b2 + hstep, voffB); STAGE(SA(0, 0), a2, voffA);
;       WAIT_V(8); WAIT_L(0); BAR; MMA(1, 0, At, B0); MMA(1, 1, At, B1); BAR; SCHED;
;       LDB(B0, 1, 0); LDB(B1, 1, 1); SCHED; LDA(At, 1, 0); STAGE(SA(0, 1), a2 + hstep, voffA);
;       WAIT_V(8); WAIT_L(0); BAR; MMA(0, 0, At, B0); MMA(0, 1, At, B1); BAR; SCHED;
	v_mfma_f32_16x16x32_f16 v[66:69], v[144:147], v[202:205], 0
	v_mfma_f32_16x16x32_f16 v[62:65], v[178:181], v[202:205], 0
	v_mfma_f32_16x16x32_f16 v[50:53], v[144:147], v[210:213], 0
	v_mfma_f32_16x16x32_f16 v[46:49], v[178:181], v[210:213], 0
	v_mfma_f32_16x16x32_f16 v[34:37], v[144:147], v[218:221], 0
	v_mfma_f32_16x16x32_f16 v[30:33], v[178:181], v[218:221], 0
	v_mfma_f32_16x16x32_f16 v[18:21], v[144:147], v[226:229], 0
	v_mfma_f32_16x16x32_f16 v[14:17], v[178:181], v[226:229], 0
	v_mfma_f32_16x16x32_f16 v[66:69], v[152:155], v[206:209], v[66:69]
	v_mfma_f32_16x16x32_f16 v[62:65], v[182:185], v[206:209], v[62:65]
	v_mfma_f32_16x16x32_f16 v[50:53], v[152:155], v[214:217], v[50:53]
	v_mfma_f32_16x16x32_f16 v[46:49], v[182:185], v[214:217], v[46:49]
	v_mfma_f32_16x16x32_f16 v[34:37], v[152:155], v[222:225], v[34:37]
	v_mfma_f32_16x16x32_f16 v[30:33], v[182:185], v[222:225], v[30:33]
	v_mfma_f32_16x16x32_f16 v[18:21], v[152:155], v[230:233], v[18:21]
	v_mfma_f32_16x16x32_f16 v[14:17], v[182:185], v[230:233], v[14:17]
	s_add_i32 s46, 0, 0x18000
	v_add_u32_e32 v177, s46, v148
	s_add_i32 s47, 0, 0x1c000
	v_mfma_f32_16x16x32_f16 v[58:61], v[186:189], v[202:205], 0
	v_mfma_f32_16x16x32_f16 v[54:57], v[194:197], v[202:205], 0
	v_mfma_f32_16x16x32_f16 v[42:45], v[186:189], v[210:213], 0
	v_mfma_f32_16x16x32_f16 v[38:41], v[194:197], v[210:213], 0
	v_mfma_f32_16x16x32_f16 v[26:29], v[186:189], v[218:221], 0
	v_mfma_f32_16x16x32_f16 v[22:25], v[194:197], v[218:221], 0
	v_mfma_f32_16x16x32_f16 v[10:13], v[186:189], v[226:229], 0
	v_mfma_f32_16x16x32_f16 v[6:9], v[194:197], v[226:229], 0
	v_mfma_f32_16x16x32_f16 v[58:61], v[190:193], v[206:209], v[58:61]
	v_mfma_f32_16x16x32_f16 v[54:57], v[198:201], v[206:209], v[54:57]
	v_mfma_f32_16x16x32_f16 v[42:45], v[190:193], v[214:217], v[42:45]
	v_mfma_f32_16x16x32_f16 v[38:41], v[198:201], v[214:217], v[38:41]
	v_mfma_f32_16x16x32_f16 v[26:29], v[190:193], v[222:225], v[26:29]
	v_mfma_f32_16x16x32_f16 v[22:25], v[198:201], v[222:225], v[22:25]
	v_mfma_f32_16x16x32_f16 v[10:13], v[190:193], v[230:233], v[10:13]
	v_mfma_f32_16x16x32_f16 v[6:9], v[198:201], v[230:233], v[6:9]
	s_barrier
	ds_read_b128 v[144:147], v177
	ds_read_b128 v[152:155], v177 offset:1024
	ds_read_b128 v[178:181], v177 offset:2048
	ds_read_b128 v[182:185], v177 offset:3072
	v_add_u32_e32 v177, s47, v148
	ds_read_b128 v[186:189], v177
	ds_read_b128 v[190:193], v177 offset:1024
	ds_read_b128 v[194:197], v177 offset:2048
	ds_read_b128 v[198:201], v177 offset:3072
	s_add_u32 s12, s18, 0xb0000
	s_addc_u32 s13, s19, 0
	s_mov_b32 m0, s24
	v_lshl_add_u64 v[242:243], s[12:13], 0, v[2:3]
	ds_read_b128 v[202:205], v151 offset:32768
	ds_read_b128 v[206:209], v151 offset:33792
	ds_read_b128 v[210:213], v151 offset:34816
	ds_read_b128 v[214:217], v151 offset:35840
	ds_read_b128 v[218:221], v151 offset:36864
	ds_read_b128 v[222:225], v151 offset:37888
	ds_read_b128 v[226:229], v151 offset:38912
	ds_read_b128 v[230:233], v151 offset:39936
	global_load_lds_dwordx4 v[242:243], off
	v_lshl_add_u64 v[242:243], s[12:13], 0, v[134:135]
	s_mov_b32 m0, s26
	s_nop 0
	global_load_lds_dwordx4 v[242:243], off
	s_waitcnt vmcnt(8) lgkmcnt(0)
	s_barrier
	v_mfma_f32_16x16x32_f16 v[130:133], v[144:147], v[202:205], v[130:133]
	v_mfma_f32_16x16x32_f16 v[126:129], v[178:181], v[202:205], v[126:129]
	v_mfma_f32_16x16x32_f16 v[114:117], v[144:147], v[210:213], v[114:117]
	v_mfma_f32_16x16x32_f16 v[110:113], v[178:181], v[210:213], v[110:113]
	v_mfma_f32_16x16x32_f16 v[98:101], v[144:147], v[218:221], v[98:101]
	v_mfma_f32_16x16x32_f16 v[94:97], v[178:181], v[218:221], v[94:97]
	v_mfma_f32_16x16x32_f16 v[82:85], v[144:147], v[226:229], v[82:85]
	v_mfma_f32_16x16x32_f16 v[78:81], v[178:181], v[226:229], v[78:81]
	v_mfma_f32_16x16x32_f16 v[130:133], v[152:155], v[206:209], v[130:133]
	v_mfma_f32_16x16x32_f16 v[126:129], v[182:185], v[206:209], v[126:129]
	v_mfma_f32_16x16x32_f16 v[114:117], v[152:155], v[214:217], v[114:117]
	v_mfma_f32_16x16x32_f16 v[110:113], v[182:185], v[214:217], v[110:113]
	v_mfma_f32_16x16x32_f16 v[98:101], v[152:155], v[222:225], v[98:101]
	v_mfma_f32_16x16x32_f16 v[94:97], v[182:185], v[222:225], v[94:97]
	v_mfma_f32_16x16x32_f16 v[82:85], v[152:155], v[230:233], v[82:85]
	v_mfma_f32_16x16x32_f16 v[78:81], v[182:185], v[230:233], v[78:81]
	s_add_i32 s12, s46, s21
	v_lshl_add_u64 v[234:235], v[234:235], 0, s[36:37]
	s_mov_b32 m0, s12
	v_mfma_f32_16x16x32_f16 v[122:125], v[186:189], v[202:205], v[122:125]
	v_mfma_f32_16x16x32_f16 v[118:121], v[194:197], v[202:205], v[118:121]
	v_mfma_f32_16x16x32_f16 v[106:109], v[186:189], v[210:213], v[106:109]
	v_mfma_f32_16x16x32_f16 v[102:105], v[194:197], v[210:213], v[102:105]
	v_mfma_f32_16x16x32_f16 v[90:93], v[186:189], v[218:221], v[90:93]
	v_mfma_f32_16x16x32_f16 v[86:89], v[194:197], v[218:221], v[86:89]
	v_mfma_f32_16x16x32_f16 v[74:77], v[186:189], v[226:229], v[74:77]
	v_mfma_f32_16x16x32_f16 v[70:73], v[194:197], v[226:229], v[70:73]
	v_mfma_f32_16x16x32_f16 v[122:125], v[190:193], v[206:209], v[122:125]
	v_mfma_f32_16x16x32_f16 v[118:121], v[198:201], v[206:209], v[118:121]
	v_mfma_f32_16x16x32_f16 v[106:109], v[190:193], v[214:217], v[106:109]
	v_mfma_f32_16x16x32_f16 v[102:105], v[198:201], v[214:217], v[102:105]
	v_mfma_f32_16x16x32_f16 v[90:93], v[190:193], v[222:225], v[90:93]
	v_mfma_f32_16x16x32_f16 v[86:89], v[198:201], v[222:225], v[86:89]
	v_mfma_f32_16x16x32_f16 v[74:77], v[190:193], v[230:233], v[74:77]
	v_mfma_f32_16x16x32_f16 v[70:73], v[198:201], v[230:233], v[70:73]
	s_barrier
; #define STAGE(bufoff, gbase, voff) do { _Pragma("unroll") for (int _i = 0; _i < 2; ++_i) \
;     __builtin_amdgcn_global_load_lds((const unsigned*)((const char*)(gbase) + (voff)[_i]), (LAS unsigned*)(lds + (bufoff) + ldsw + _i * 8192), 16, 0, 0); } while (0)
; #define LDA(dst, b, h) do { _Pragma("unroll") for (int m = 0; m < 4; ++m) _Pragma("unroll") for (int k = 0; k < 2; ++k) dst[m][k] = *(const LAS half8*)(lds + SA(b, h) + aoff + m * 2048 + k * 1024); } while (0)
; #define LDB(dst, b, h) do { _Pragma("unroll") for (int n = 0; n < 2; ++n) _Pragma("unroll") for (int k = 0; k < 2; ++k) dst[n][k] = *(const LAS half8*)(lds + SB(b, h) + boff + n * 2048 + k * 1024); } while (0)
; #define MMA(ai, bj, At_, Bt_) do { __builtin_amdgcn_s_setprio(1); \
;     _Pragma("unroll") for (int m = 0; m < 4; ++m) _Pragma("unroll") for (int n = 0; n < 2; ++n) _Pragma("unroll") for (int k = 0; k < 2; ++k) \
;       acc[ai][bj][m][n] = MFMA16(Bt_[n][k], At_[m][k], acc[ai][bj][m][n]); \
;     __builtin_amdgcn_s_setprio(0); } while (0)
; #define WAIT_V(n) asm volatile("s_waitcnt vmcnt(" #n ")" ::: "memory")
; #define BAR __builtin_amdgcn_s_barrier()
; template <int EPI>
; DI void gemm_phase(const int wid_s, const h16* __restrict__ A, const h16* __restrict__ Bt, const int N, const int K, const EpiArgs ea) {
;     ...
;     for (int t = 0; t < nt; t += 2) {
;       const bool last = (t == nt - 2);
;       const char* a1 = cA + (size_t)(t + 1) * kstep;
;       const char* a2 = last ? nA : cA + (size_t)(t + 2) * kstep; const char* b2 = last ? nB : cB + (size_t)(t + 2) * kstep;
;       const char* a3 = a2 + kstep; const char* b3 = b2 + kstep;
;       LDB(B0, 0, 0); LDB(B1, 0, 1); SCHED; LDA(At, 0, 0); STAGE(SA(1, 1), a1 + hstep, voffA);
;       WAIT_V(8); WAIT_L(0); BAR; MMA(0, 0, At, B0); MMA(0, 1, At, B1); BAR; SCHED;
;       LDA(At, 0, 1); STAGE(SB(0, 0), b2, voffB); STAGE(SB(0, 1), b2 + hstep, voffB); STAGE(SA(0, 0), a2, voffA);
;       WAIT_V(8); WAIT_L(0); BAR; MMA(1, 0, At, B0); MMA(1, 1, At, B1); BAR; SCHED;
;       LDB(B0, 1, 0); LDB(B1, 1, 1); SCHED; LDA(At, 1, 0); STAGE(SA(0, 1), a2 + hstep, voffA);
;       WAIT_V(8); WAIT_L(0); BAR; MMA(0, 0, At, B0); MMA(0, 1, At, B1); BAR; SCHED;
;       LDA(At, 1, 1); STAGE(SB(1, 0), b3, voffB); STAGE(SB(1, 1), b3 + hstep, voffB); STAGE(SA(1, 0), a3, voffA);
;       WAIT_V(8); WAIT_L(0); BAR; MMA(1, 0, At, B0); MMA(1, 1, At, B1); BAR; SCHED;
	ds_read_b128 v[202:205], v151 offset:49152
	ds_read_b128 v[206:209], v151 offset:50176
	ds_read_b128 v[210:213], v151 offset:51200
	ds_read_b128 v[214:217], v151 offset:52224
	ds_read_b128 v[218:221], v151 offset:53248
	ds_read_b128 v[222:225], v151 offset:54272
	ds_read_b128 v[226:229], v151 offset:55296
	ds_read_b128 v[230:233], v151 offset:56320
	global_load_lds_dwordx4 v[234:235], off
	s_add_i32 m0, s12, 0x2000
	s_add_u32 s12, s16, 0xb0080
	v_lshl_add_u64 v[234:235], v[236:237], 0, s[36:37]
	s_addc_u32 s13, s17, 0
	s_add_i32 s16, s47, s21
	global_load_lds_dwordx4 v[234:235], off
	v_lshl_add_u64 v[234:235], s[12:13], 0, v[0:1]
	s_mov_b32 m0, s16
	s_nop 0
	global_load_lds_dwordx4 v[234:235], off
	v_lshl_add_u64 v[234:235], s[12:13], 0, v[138:139]
	s_add_i32 m0, s16, 0x2000
	s_nop 0
	global_load_lds_dwordx4 v[234:235], off
	v_lshl_add_u64 v[234:235], v[238:239], 0, s[36:37]
	s_mov_b32 m0, s27
	s_nop 0
	global_load_lds_dwordx4 v[234:235], off
	v_lshl_add_u64 v[234:235], v[240:241], 0, s[36:37]
	s_mov_b32 m0, s30
	s_nop 0
	global_load_lds_dwordx4 v[234:235], off
	s_waitcnt vmcnt(8) lgkmcnt(0)
	s_barrier
	v_mfma_f32_16x16x32_f16 v[66:69], v[144:147], v[202:205], v[66:69]
	v_mfma_f32_16x16x32_f16 v[62:65], v[178:181], v[202:205], v[62:65]
	v_mfma_f32_16x16x32_f16 v[50:53], v[144:147], v[210:213], v[50:53]
	v_mfma_f32_16x16x32_f16 v[46:49], v[178:181], v[210:213], v[46:49]
	v_mfma_f32_16x16x32_f16 v[34:37], v[144:147], v[218:221], v[34:37]
	v_mfma_f32_16x16x32_f16 v[30:33], v[178:181], v[218:221], v[30:33]
	v_mfma_f32_16x16x32_f16 v[18:21], v[144:147], v[226:229], v[18:21]
	v_mfma_f32_16x16x32_f16 v[14:17], v[178:181], v[226:229], v[14:17]
	v_mfma_f32_16x16x32_f16 v[66:69], v[152:155], v[206:209], v[66:69]
	v_mfma_f32_16x16x32_f16 v[62:65], v[182:185], v[206:209], v[62:65]
	v_mfma_f32_16x16x32_f16 v[50:53], v[152:155], v[214:217], v[50:53]
	v_mfma_f32_16x16x32_f16 v[46:49], v[182:185], v[214:217], v[46:49]
	v_mfma_f32_16x16x32_f16 v[34:37], v[152:155], v[222:225], v[34:37]
	v_mfma_f32_16x16x32_f16 v[30:33], v[182:185], v[222:225], v[30:33]
	v_mfma_f32_16x16x32_f16 v[18:21], v[152:155], v[230:233], v[18:21]
	v_mfma_f32_16x16x32_f16 v[14:17], v[182:185], v[230:233], v[14:17]
	v_mfma_f32_16x16x32_f16 v[58:61], v[186:189], v[202:205], v[58:61]
	v_mfma_f32_16x16x32_f16 v[54:57], v[194:197], v[202:205], v[54:57]
	v_mfma_f32_16x16x32_f16 v[42:45], v[186:189], v[210:213], v[42:45]
	v_mfma_f32_16x16x32_f16 v[38:41], v[194:197], v[210:213], v[38:41]
	v_mfma_f32_16x16x32_f16 v[26:29], v[186:189], v[218:221], v[26:29]
	v_mfma_f32_16x16x32_f16 v[22:25], v[194:197], v[218:221], v[22:25]
	v_mfma_f32_16x16x32_f16 v[10:13], v[186:189], v[226:229], v[10:13]
	v_mfma_f32_16x16x32_f16 v[6:9], v[194:197], v[226:229], v[6:9]
	v_mfma_f32_16x16x32_f16 v[58:61], v[190:193], v[206:209], v[58:61]
	v_mfma_f32_16x16x32_f16 v[54:57], v[198:201], v[206:209], v[54:57]
	v_mfma_f32_16x16x32_f16 v[42:45], v[190:193], v[214:217], v[42:45]
	v_mfma_f32_16x16x32_f16 v[38:41], v[198:201], v[214:217], v[38:41]
	v_mfma_f32_16x16x32_f16 v[26:29], v[190:193], v[222:225], v[26:29]
	v_mfma_f32_16x16x32_f16 v[22:25], v[198:201], v[222:225], v[22:25]
	v_mfma_f32_16x16x32_f16 v[10:13], v[190:193], v[230:233], v[10:13]
	v_mfma_f32_16x16x32_f16 v[6:9], v[198:201], v[230:233], v[6:9]
	s_barrier
	s_add_i32 s45, s45, 2
	s_add_u32 s43, s43, 0x100
	s_addc_u32 s44, s44, 0
	s_cmp_gt_u32 s45, 41
	s_mov_b64 s[12:13], s[14:15]
.LBB0_122:
	s_add_u32 s14, s12, 0x100
	s_addc_u32 s15, s13, 0
	s_add_i32 s46, 0, 0x10000
	s_cmp_eq_u32 s45, 40
	s_cselect_b32 s19, s9, s15
	s_cselect_b32 s18, s8, s14
	v_add_u32_e32 v177, s46, v148
	s_cselect_b32 s17, s42, s44
	s_cselect_b32 s16, s41, s43
	s_add_i32 s47, 0, 0x14000
	ds_read_b128 v[144:147], v177
	ds_read_b128 v[152:155], v177 offset:1024
	ds_read_b128 v[178:181], v177 offset:2048
	ds_read_b128 v[182:185], v177 offset:3072
	v_add_u32_e32 v177, s47, v148
	ds_read_b128 v[186:189], v177
	ds_read_b128 v[190:193], v177 offset:1024
	ds_read_b128 v[194:197], v177 offset:2048
	ds_read_b128 v[198:201], v177 offset:3072
	v_lshl_add_u64 v[234:235], s[12:13], 0, v[142:143]
	s_add_i32 m0, s22, 0xc000
	ds_read_b128 v[202:205], v151
	ds_read_b128 v[206:209], v151 offset:1024
	ds_read_b128 v[210:213], v151 offset:2048
	ds_read_b128 v[214:217], v151 offset:3072
	ds_read_b128 v[218:221], v151 offset:4096
	ds_read_b128 v[222:225], v151 offset:5120
	ds_read_b128 v[226:229], v151 offset:6144
	ds_read_b128 v[230:233], v151 offset:7168
	global_load_lds_dwordx4 v[234:235], off
	v_lshl_add_u64 v[234:235], s[12:13], 0, v[140:141]
	s_add_i32 m0, s22, 0xe000
	s_nop 0
	global_load_lds_dwordx4 v[234:235], off
	s_waitcnt vmcnt(8) lgkmcnt(0)
	s_barrier
; #define STAGE(bufoff, gbase, voff) do { _Pragma("unroll") for (int _i = 0; _i < 2; ++_i) \
;     __builtin_amdgcn_global_load_lds((const unsigned*)((const char*)(gbase) + (voff)[_i]), (LAS unsigned*)(lds + (bufoff) + ldsw + _i * 8192), 16, 0, 0); } while (0)
; #define LDA(dst, b, h) do { _Pragma("unroll") for (int m = 0; m < 4; ++m) _Pragma("unroll") for (int k = 0; k < 2; ++k) dst[m][k] = *(const LAS half8*)(lds + SA(b, h) + aoff + m * 2048 + k * 1024); } while (0)
; #define MMA(ai, bj, At_, Bt_) do { __builtin_amdgcn_s_setprio(1); \
;     _Pragma("unroll") for (int m = 0; m < 4; ++m) _Pragma("unroll") for (int n = 0; n < 2; ++n) _Pragma("unroll") for (int k = 0; k < 2; ++k) \
;       acc[ai][bj][m][n] = MFMA16(Bt_[n][k], At_[m][k], acc[ai][bj][m][n]); \
;     __builtin_amdgcn_s_setprio(0); } while (0)
; #define WAIT_V(n) asm volatile("s_waitcnt vmcnt(" #n ")" ::: "memory")
; #define WAIT_L(n) asm volatile("s_waitcnt lgkmcnt(" #n ")" ::: "memory")
; #define BAR __builtin_amdgcn_s_barrier()
; #define SCHED __builtin_amdgcn_sched_barrier(0)
; template <int EPI>
; DI void gemm_phase(const int wid_s, const h16* __restrict__ A, const h16* __restrict__ Bt, const int N, const int K, const EpiArgs ea) {
;     ...
;       WAIT_V(8); WAIT_L(0); BAR; MMA(0, 0, At, B0); MMA(0, 1, At, B1); BAR; SCHED;
;       LDA(At, 0, 1); STAGE(SB(0, 0), b2, voffB); STAGE(SB(0, 1), b2 + hstep, voffB); STAGE(SA(0, 0), a2, voffA);
;       WAIT_V(8); WAIT_L(0); BAR; MMA(1, 0, At, B0); MMA(1, 1, At, B1); BAR; SCHED;
	v_mfma_f32_16x16x32_f16 v[130:133], v[144:147], v[202:205], v[130:133]
	v_mfma_f32_16x16x32_f16 v[126:129], v[178:181], v[202:205], v[126:129]
	v_mfma_f32_16x16x32_f16 v[114:117], v[144:147], v[210:213], v[114:117]
	v_mfma_f32_16x16x32_f16 v[110:113], v[178:181], v[210:213], v[110:113]
	v_mfma_f32_16x16x32_f16 v[98:101], v[144:147], v[218:221], v[98:101]
	v_mfma_f32_16x16x32_f16 v[94:97], v[178:181], v[218:221], v[94:97]
	v_mfma_f32_16x16x32_f16 v[82:85], v[144:147], v[226:229], v[82:85]
	v_mfma_f32_16x16x32_f16 v[78:81], v[178:181], v[226:229], v[78:81]
	v_mfma_f32_16x16x32_f16 v[130:133], v[152:155], v[206:209], v[130:133]
	v_mfma_f32_16x16x32_f16 v[126:129], v[182:185], v[206:209], v[126:129]
	v_mfma_f32_16x16x32_f16 v[114:117], v[152:155], v[214:217], v[114:117]
	v_mfma_f32_16x16x32_f16 v[110:113], v[182:185], v[214:217], v[110:113]
	v_mfma_f32_16x16x32_f16 v[98:101], v[152:155], v[222:225], v[98:101]
	v_mfma_f32_16x16x32_f16 v[94:97], v[182:185], v[222:225], v[94:97]
	v_mfma_f32_16x16x32_f16 v[82:85], v[152:155], v[230:233], v[82:85]
	v_mfma_f32_16x16x32_f16 v[78:81], v[182:185], v[230:233], v[78:81]
	s_add_i32 s12, s46, s21
	v_lshl_add_u64 v[234:235], s[16:17], 0, v[0:1]
	s_mov_b32 m0, s12
	v_mfma_f32_16x16x32_f16 v[122:125], v[186:189], v[202:205], v[122:125]
	v_mfma_f32_16x16x32_f16 v[118:121], v[194:197], v[202:205], v[118:121]
	v_mfma_f32_16x16x32_f16 v[106:109], v[186:189], v[210:213], v[106:109]
	v_mfma_f32_16x16x32_f16 v[102:105], v[194:197], v[210:213], v[102:105]
	v_mfma_f32_16x16x32_f16 v[90:93], v[186:189], v[218:221], v[90:93]
	v_mfma_f32_16x16x32_f16 v[86:89], v[194:197], v[218:221], v[86:89]
	v_mfma_f32_16x16x32_f16 v[74:77], v[186:189], v[226:229], v[74:77]
	v_mfma_f32_16x16x32_f16 v[70:73], v[194:197], v[226:229], v[70:73]
	v_mfma_f32_16x16x32_f16 v[122:125], v[190:193], v[206:209], v[122:125]
	v_mfma_f32_16x16x32_f16 v[118:121], v[198:201], v[206:209], v[118:121]
	v_mfma_f32_16x16x32_f16 v[106:109], v[190:193], v[214:217], v[106:109]
	v_mfma_f32_16x16x32_f16 v[102:105], v[198:201], v[214:217], v[102:105]
	v_mfma_f32_16x16x32_f16 v[90:93], v[190:193], v[222:225], v[90:93]
	v_mfma_f32_16x16x32_f16 v[86:89], v[198:201], v[222:225], v[86:89]
	v_mfma_f32_16x16x32_f16 v[74:77], v[190:193], v[230:233], v[74:77]
	v_mfma_f32_16x16x32_f16 v[70:73], v[198:201], v[230:233], v[70:73]
	s_barrier
	ds_read_b128 v[202:205], v151 offset:16384
	ds_read_b128 v[206:209], v151 offset:17408
	ds_read_b128 v[210:213], v151 offset:18432
	ds_read_b128 v[214:217], v151 offset:19456
	ds_read_b128 v[218:221], v151 offset:20480
	ds_read_b128 v[222:225], v151 offset:21504
	ds_read_b128 v[226:229], v151 offset:22528
	ds_read_b128 v[230:233], v151 offset:23552
	global_load_lds_dwordx4 v[234:235], off
	s_add_i32 m0, s12, 0x2000
	s_add_u32 s12, s16, 0xb0000
	v_lshl_add_u64 v[236:237], s[16:17], 0, v[138:139]
	s_addc_u32 s13, s17, 0
	s_add_i32 s46, s47, s21
	global_load_lds_dwordx4 v[236:237], off
	v_lshl_add_u64 v[238:239], s[12:13], 0, v[0:1]
	s_mov_b32 m0, s46
	v_lshl_add_u64 v[240:241], s[18:19], 0, v[134:135]
	global_load_lds_dwordx4 v[238:239], off
	v_lshl_add_u64 v[238:239], s[12:13], 0, v[138:139]
	s_add_i32 m0, s46, 0x2000
	s_nop 0
	global_load_lds_dwordx4 v[238:239], off
	v_lshl_add_u64 v[238:239], s[18:19], 0, v[2:3]
	s_mov_b32 m0, s22
	s_nop 0
	global_load_lds_dwordx4 v[238:239], off
	s_mov_b32 m0, s23
	s_nop 0
	global_load_lds_dwordx4 v[240:241], off
	s_waitcnt vmcnt(8) lgkmcnt(0)
	s_barrier
	v_mfma_f32_16x16x32_f16 v[66:69], v[144:147], v[202:205], v[66:69]
	v_mfma_f32_16x16x32_f16 v[62:65], v[178:181], v[202:205], v[62:65]
	v_mfma_f32_16x16x32_f16 v[50:53], v[144:147], v[210:213], v[50:53]
	v_mfma_f32_16x16x32_f16 v[46:49], v[178:181], v[210:213], v[46:49]
	v_mfma_f32_16x16x32_f16 v[34:37], v[144:147], v[218:221], v[34:37]
	v_mfma_f32_16x16x32_f16 v[30:33], v[178:181], v[218:221], v[30:33]
	v_mfma_f32_16x16x32_f16 v[18:21], v[144:147], v[226:229], v[18:21]
	v_mfma_f32_16x16x32_f16 v[14:17], v[178:181], v[226:229], v[14:17]
	v_mfma_f32_16x16x32_f16 v[66:69], v[152:155], v[206:209], v[66:69]
	v_mfma_f32_16x16x32_f16 v[62:65], v[182:185], v[206:209], v[62:65]
	v_mfma_f32_16x16x32_f16 v[50:53], v[152:155], v[214:217], v[50:53]
	v_mfma_f32_16x16x32_f16 v[46:49], v[182:185], v[214:217], v[46:49]
	v_mfma_f32_16x16x32_f16 v[34:37], v[152:155], v[222:225], v[34:37]
	v_mfma_f32_16x16x32_f16 v[30:33], v[182:185], v[222:225], v[30:33]
	v_mfma_f32_16x16x32_f16 v[18:21], v[152:155], v[230:233], v[18:21]
	v_mfma_f32_16x16x32_f16 v[14:17], v[182:185], v[230:233], v[14:17]
	s_add_i32 s46, 0, 0x18000
	v_add_u32_e32 v177, s46, v148
	s_add_i32 s47, 0, 0x1c000
	v_mfma_f32_16x16x32_f16 v[58:61], v[186:189], v[202:205], v[58:61]
	v_mfma_f32_16x16x32_f16 v[54:57], v[194:197], v[202:205], v[54:57]
	v_mfma_f32_16x16x32_f16 v[42:45], v[186:189], v[210:213], v[42:45]
	v_mfma_f32_16x16x32_f16 v[38:41], v[194:197], v[210:213], v[38:41]
	v_mfma_f32_16x16x32_f16 v[26:29], v[186:189], v[218:221], v[26:29]
	v_mfma_f32_16x16x32_f16 v[22:25], v[194:197], v[218:221], v[22:25]
	v_mfma_f32_16x16x32_f16 v[10:13], v[186:189], v[226:229], v[10:13]
	v_mfma_f32_16x16x32_f16 v[6:9], v[194:197], v[226:229], v[6:9]
	v_mfma_f32_16x16x32_f16 v[58:61], v[190:193], v[206:209], v[58:61]
	v_mfma_f32_16x16x32_f16 v[54:57], v[198:201], v[206:209], v[54:57]
	v_mfma_f32_16x16x32_f16 v[42:45], v[190:193], v[214:217], v[42:45]
	v_mfma_f32_16x16x32_f16 v[38:41], v[198:201], v[214:217], v[38:41]
	v_mfma_f32_16x16x32_f16 v[26:29], v[190:193], v[222:225], v[26:29]
	v_mfma_f32_16x16x32_f16 v[22:25], v[198:201], v[222:225], v[22:25]
	v_mfma_f32_16x16x32_f16 v[10:13], v[190:193], v[230:233], v[10:13]
	v_mfma_f32_16x16x32_f16 v[6:9], v[198:201], v[230:233], v[6:9]
	s_barrier
; #define STAGE(bufoff, gbase, voff) do { _Pragma("unroll") for (int _i = 0; _i < 2; ++_i) \
;     __builtin_amdgcn_global_load_lds((const unsigned*)((const char*)(gbase) + (voff)[_i]), (LAS unsigned*)(lds + (bufoff) + ldsw + _i * 8192), 16, 0, 0); } while (0)
; #define LDA(dst, b, h) do { _Pragma("unroll") for (int m = 0; m < 4; ++m) _Pragma("unroll") for (int k = 0; k < 2; ++k) dst[m][k] = *(const LAS half8*)(lds + SA(b, h) + aoff + m * 2048 + k * 1024); } while (0)
; #define LDB(dst, b, h) do { _Pragma("unroll") for (int n = 0; n < 2; ++n) _Pragma("unroll") for (int k = 0; k < 2; ++k) dst[n][k] = *(const LAS half8*)(lds + SB(b, h) + boff + n * 2048 + k * 1024); } while (0)
; #define MMA(ai, bj, At_, Bt_) do { __builtin_amdgcn_s_setprio(1); \
;     _Pragma("unroll") for (int m = 0; m < 4; ++m) _Pragma("unroll") for (int n = 0; n < 2; ++n) _Pragma("unroll") for (int k = 0; k < 2; ++k) \
;       acc[ai][bj][m][n] = MFMA16(Bt_[n][k], At_[m][k], acc[ai][bj][m][n]); \
;     __builtin_amdgcn_s_setprio(0); } while (0)
; #define WAIT_V(n) asm volatile("s_waitcnt vmcnt(" #n ")" ::: "memory")
; #define WAIT_L(n) asm volatile("s_waitcnt lgkmcnt(" #n ")" ::: "memory")
; #define BAR __builtin_amdgcn_s_barrier()
; #define SCHED __builtin_amdgcn_sched_barrier(0)
; template <int EPI>
; DI void gemm_phase(const int wid_s, const h16* __restrict__ A, const h16* __restrict__ Bt, const int N, const int K, const EpiArgs ea) {
;     ...
;       LDB(B0, 1, 0); LDB(B1, 1, 1); SCHED; LDA(At, 1, 0); STAGE(SA(0, 1), a2 + hstep, voffA);
;       WAIT_V(8); WAIT_L(0); BAR; MMA(0, 0, At, B0); MMA(0, 1, At, B1); BAR; SCHED;
;       LDA(At, 1, 1); STAGE(SB(1, 0), b3, voffB); STAGE(SB(1, 1), b3 + hstep, voffB); STAGE(SA(1, 0), a3, voffA);
;       WAIT_V(8); WAIT_L(0); BAR; MMA(1, 0, At, B0); MMA(1, 1, At, B1); BAR; SCHED;
;     }
;     if (wr == 0) BAR;
	ds_read_b128 v[144:147], v177
	ds_read_b128 v[152:155], v177 offset:1024
	ds_read_b128 v[178:181], v177 offset:2048
	ds_read_b128 v[182:185], v177 offset:3072
	v_add_u32_e32 v177, s47, v148
	ds_read_b128 v[186:189], v177
	ds_read_b128 v[190:193], v177 offset:1024
	ds_read_b128 v[194:197], v177 offset:2048
	ds_read_b128 v[198:201], v177 offset:3072
	s_add_u32 s12, s18, 0xb0000
	s_addc_u32 s13, s19, 0
	s_mov_b32 m0, s24
	v_lshl_add_u64 v[242:243], s[12:13], 0, v[2:3]
	ds_read_b128 v[202:205], v151 offset:32768
	ds_read_b128 v[206:209], v151 offset:33792
	ds_read_b128 v[210:213], v151 offset:34816
	ds_read_b128 v[214:217], v151 offset:35840
	ds_read_b128 v[218:221], v151 offset:36864
	ds_read_b128 v[222:225], v151 offset:37888
	ds_read_b128 v[226:229], v151 offset:38912
	ds_read_b128 v[230:233], v151 offset:39936
	global_load_lds_dwordx4 v[242:243], off
	v_lshl_add_u64 v[242:243], s[12:13], 0, v[134:135]
	s_mov_b32 m0, s26
	s_nop 0
	global_load_lds_dwordx4 v[242:243], off
	s_waitcnt vmcnt(8) lgkmcnt(0)
	s_barrier
	v_mfma_f32_16x16x32_f16 v[130:133], v[144:147], v[202:205], v[130:133]
	v_mfma_f32_16x16x32_f16 v[126:129], v[178:181], v[202:205], v[126:129]
	v_mfma_f32_16x16x32_f16 v[114:117], v[144:147], v[210:213], v[114:117]
	v_mfma_f32_16x16x32_f16 v[110:113], v[178:181], v[210:213], v[110:113]
	v_mfma_f32_16x16x32_f16 v[98:101], v[144:147], v[218:221], v[98:101]
	v_mfma_f32_16x16x32_f16 v[94:97], v[178:181], v[218:221], v[94:97]
	v_mfma_f32_16x16x32_f16 v[82:85], v[144:147], v[226:229], v[82:85]
	v_mfma_f32_16x16x32_f16 v[78:81], v[178:181], v[226:229], v[78:81]
	v_mfma_f32_16x16x32_f16 v[130:133], v[152:155], v[206:209], v[130:133]
	v_mfma_f32_16x16x32_f16 v[126:129], v[182:185], v[206:209], v[126:129]
	v_mfma_f32_16x16x32_f16 v[114:117], v[152:155], v[214:217], v[114:117]
	v_mfma_f32_16x16x32_f16 v[110:113], v[182:185], v[214:217], v[110:113]
	v_mfma_f32_16x16x32_f16 v[98:101], v[152:155], v[222:225], v[98:101]
	v_mfma_f32_16x16x32_f16 v[94:97], v[182:185], v[222:225], v[94:97]
	v_mfma_f32_16x16x32_f16 v[82:85], v[152:155], v[230:233], v[82:85]
	v_mfma_f32_16x16x32_f16 v[78:81], v[182:185], v[230:233], v[78:81]
	s_add_i32 s12, s46, s21
	v_lshl_add_u64 v[234:235], v[234:235], 0, s[36:37]
	s_mov_b32 m0, s12
	v_mfma_f32_16x16x32_f16 v[122:125], v[186:189], v[202:205], v[122:125]
	v_mfma_f32_16x16x32_f16 v[118:121], v[194:197], v[202:205], v[118:121]
	v_mfma_f32_16x16x32_f16 v[106:109], v[186:189], v[210:213], v[106:109]
	v_mfma_f32_16x16x32_f16 v[102:105], v[194:197], v[210:213], v[102:105]
	v_mfma_f32_16x16x32_f16 v[90:93], v[186:189], v[218:221], v[90:93]
	v_mfma_f32_16x16x32_f16 v[86:89], v[194:197], v[218:221], v[86:89]
	v_mfma_f32_16x16x32_f16 v[74:77], v[186:189], v[226:229], v[74:77]
	v_mfma_f32_16x16x32_f16 v[70:73], v[194:197], v[226:229], v[70:73]
	v_mfma_f32_16x16x32_f16 v[122:125], v[190:193], v[206:209], v[122:125]
	v_mfma_f32_16x16x32_f16 v[118:121], v[198:201], v[206:209], v[118:121]
	v_mfma_f32_16x16x32_f16 v[106:109], v[190:193], v[214:217], v[106:109]
	v_mfma_f32_16x16x32_f16 v[102:105], v[198:201], v[214:217], v[102:105]
	v_mfma_f32_16x16x32_f16 v[90:93], v[190:193], v[222:225], v[90:93]
	v_mfma_f32_16x16x32_f16 v[86:89], v[198:201], v[222:225], v[86:89]
	v_mfma_f32_16x16x32_f16 v[74:77], v[190:193], v[230:233], v[74:77]
	v_mfma_f32_16x16x32_f16 v[70:73], v[198:201], v[230:233], v[70:73]
	s_barrier
	ds_read_b128 v[202:205], v151 offset:49152
	ds_read_b128 v[206:209], v151 offset:50176
	ds_read_b128 v[210:213], v151 offset:51200
	ds_read_b128 v[214:217], v151 offset:52224
	ds_read_b128 v[218:221], v151 offset:53248
	ds_read_b128 v[222:225], v151 offset:54272
	ds_read_b128 v[226:229], v151 offset:55296
	ds_read_b128 v[230:233], v151 offset:56320
	global_load_lds_dwordx4 v[234:235], off
	s_add_i32 m0, s12, 0x2000
	s_add_u32 s12, s16, 0xb0080
	v_lshl_add_u64 v[234:235], v[236:237], 0, s[36:37]
	s_addc_u32 s13, s17, 0
	s_add_i32 s16, s47, s21
	global_load_lds_dwordx4 v[234:235], off
	v_lshl_add_u64 v[234:235], s[12:13], 0, v[0:1]
	s_mov_b32 m0, s16
	s_nop 0
	global_load_lds_dwordx4 v[234:235], off
	v_lshl_add_u64 v[234:235], s[12:13], 0, v[138:139]
	s_add_i32 m0, s16, 0x2000
	s_nop 0
	global_load_lds_dwordx4 v[234:235], off
	v_lshl_add_u64 v[234:235], v[238:239], 0, s[36:37]
	s_mov_b32 m0, s27
	s_nop 0
	global_load_lds_dwordx4 v[234:235], off
	v_lshl_add_u64 v[234:235], v[240:241], 0, s[36:37]
	s_mov_b32 m0, s30
	s_nop 0
	global_load_lds_dwordx4 v[234:235], off
	s_waitcnt vmcnt(8) lgkmcnt(0)
	s_barrier
	v_mfma_f32_16x16x32_f16 v[66:69], v[144:147], v[202:205], v[66:69]
	v_mfma_f32_16x16x32_f16 v[62:65], v[178:181], v[202:205], v[62:65]
	v_mfma_f32_16x16x32_f16 v[50:53], v[144:147], v[210:213], v[50:53]
	v_mfma_f32_16x16x32_f16 v[46:49], v[178:181], v[210:213], v[46:49]
	v_mfma_f32_16x16x32_f16 v[34:37], v[144:147], v[218:221], v[34:37]
	v_mfma_f32_16x16x32_f16 v[30:33], v[178:181], v[218:221], v[30:33]
	v_mfma_f32_16x16x32_f16 v[18:21], v[144:147], v[226:229], v[18:21]
	v_mfma_f32_16x16x32_f16 v[14:17], v[178:181], v[226:229], v[14:17]
	v_mfma_f32_16x16x32_f16 v[66:69], v[152:155], v[206:209], v[66:69]
	v_mfma_f32_16x16x32_f16 v[62:65], v[182:185], v[206:209], v[62:65]
	v_mfma_f32_16x16x32_f16 v[50:53], v[152:155], v[214:217], v[50:53]
	v_mfma_f32_16x16x32_f16 v[46:49], v[182:185], v[214:217], v[46:49]
	v_mfma_f32_16x16x32_f16 v[34:37], v[152:155], v[222:225], v[34:37]
	v_mfma_f32_16x16x32_f16 v[30:33], v[182:185], v[222:225], v[30:33]
	v_mfma_f32_16x16x32_f16 v[18:21], v[152:155], v[230:233], v[18:21]
	v_mfma_f32_16x16x32_f16 v[14:17], v[182:185], v[230:233], v[14:17]
	v_mfma_f32_16x16x32_f16 v[58:61], v[186:189], v[202:205], v[58:61]
	v_mfma_f32_16x16x32_f16 v[54:57], v[194:197], v[202:205], v[54:57]
	v_mfma_f32_16x16x32_f16 v[42:45], v[186:189], v[210:213], v[42:45]
	v_mfma_f32_16x16x32_f16 v[38:41], v[194:197], v[210:213], v[38:41]
	v_mfma_f32_16x16x32_f16 v[26:29], v[186:189], v[218:221], v[26:29]
	v_mfma_f32_16x16x32_f16 v[22:25], v[194:197], v[218:221], v[22:25]
	v_mfma_f32_16x16x32_f16 v[10:13], v[186:189], v[226:229], v[10:13]
	v_mfma_f32_16x16x32_f16 v[6:9], v[194:197], v[226:229], v[6:9]
	v_mfma_f32_16x16x32_f16 v[58:61], v[190:193], v[206:209], v[58:61]
	v_mfma_f32_16x16x32_f16 v[54:57], v[198:201], v[206:209], v[54:57]
	v_mfma_f32_16x16x32_f16 v[42:45], v[190:193], v[214:217], v[42:45]
	v_mfma_f32_16x16x32_f16 v[38:41], v[198:201], v[214:217], v[38:41]
	v_mfma_f32_16x16x32_f16 v[26:29], v[190:193], v[222:225], v[26:29]
	v_mfma_f32_16x16x32_f16 v[22:25], v[198:201], v[222:225], v[22:25]
	v_mfma_f32_16x16x32_f16 v[10:13], v[190:193], v[230:233], v[10:13]
	v_mfma_f32_16x16x32_f16 v[6:9], v[198:201], v[230:233], v[6:9]
	s_barrier
	s_add_i32 s45, s45, 2
	s_add_u32 s43, s43, 0x100
	s_addc_u32 s44, s44, 0
	s_cmp_gt_u32 s45, 41
	s_mov_b64 s[12:13], s[14:15]
	s_cbranch_scc0 .LBB0_122
	s_and_b64 vcc, exec, s[4:5]
	s_cbranch_vccz .LBB0_125
	s_barrier

; #define STAGE(bufoff, gbase, voff) do { _Pragma("unroll") for (int _i = 0; _i < 2; ++_i) \
;     __builtin_amdgcn_global_load_lds((const unsigned*)((const char*)(gbase) + (voff)[_i]), (LAS unsigned*)(lds + (bufoff) + ldsw + _i * 8192), 16, 0, 0); } while (0)
; #define LDA(dst, b, h) do { _Pragma("unroll") for (int m = 0; m < 4; ++m) _Pragma("unroll") for (int k = 0; k < 2; ++k) dst[m][k] = *(const LAS half8*)(lds + SA(b, h) + aoff + m * 2048 + k * 1024); } while (0)
; #define LDB(dst, b, h) do { _Pragma("unroll") for (int n = 0; n < 2; ++n) _Pragma("unroll") for (int k = 0; k < 2; ++k) dst[n][k] = *(const LAS half8*)(lds + SB(b, h) + boff + n * 2048 + k * 1024); } while (0)
; #define MMA(ai, bj, At_, Bt_) do { __builtin_amdgcn_s_setprio(1); \
;     _Pragma("unroll") for (int m = 0; m < 4; ++m) _Pragma("unroll") for (int n = 0; n < 2; ++n) _Pragma("unroll") for (int k = 0; k < 2; ++k) \
;       acc[ai][bj][m][n] = MFMA16(Bt_[n][k], At_[m][k], acc[ai][bj][m][n]); \
;     __builtin_amdgcn_s_setprio(0); } while (0)
; #define WAIT_V(n) asm volatile("s_waitcnt vmcnt(" #n ")" ::: "memory")
; #define WAIT_L(n) asm volatile("s_waitcnt lgkmcnt(" #n ")" ::: "memory")
; #define BAR __builtin_amdgcn_s_barrier()
; template <int EPI>
; DI void gemm_phase(const int wid_s, const h16* __restrict__ A, const h16* __restrict__ Bt, const int N, const int K, const EpiArgs ea) {
;     ...
;     const int Ln = L + (int)gridDim.x;
;     const bool has_next = Ln < nwg;
;     int nbrow = brow, nbcol = bcol;
;     if (has_next) TILE_RC(Ln, nbrow, nbcol);
;     const char* nA = (const char*)A + (size_t)nbrow * K * 2;
;     const char* nB = (const char*)Bt + (size_t)nbcol * K * 2;
;     for (int t = 0; t < nt; t += 2) {
;       const bool last = (t == nt - 2);
;       const char* a1 = cA + (size_t)(t + 1) * kstep;
;       const char* a2 = last ? nA : cA + (size_t)(t + 2) * kstep; const char* b2 = last ? nB : cB + (size_t)(t + 2) * kstep;
;       const char* a3 = a2 + kstep; const char* b3 = b2 + kstep;
;       LDB(B0, 0, 0); LDB(B1, 0, 1); SCHED; LDA(At, 0, 0); STAGE(SA(1, 1), a1 + hstep, voffA);
;       WAIT_V(8); WAIT_L(0); BAR; MMA(0, 0, At, B0); MMA(0, 1, At, B1); BAR; SCHED;
;       LDA(At, 0, 1); STAGE(SB(0, 0), b2, voffB); STAGE(SB(0, 1), b2 + hstep, voffB); STAGE(SA(0, 0), a2, voffA);
;       WAIT_V(8); WAIT_L(0); BAR; MMA(1, 0, At, B0); MMA(1, 1, At, B1); BAR; SCHED;
.LBB0_140:
	s_ashr_i32 s9, s8, 31
	s_lshl_b64 s[12:13], s[8:9], 11
	s_add_u32 s9, s92, s12
	s_addc_u32 s42, s93, s13
	s_ashr_i32 s11, s10, 31
	s_lshl_b64 s[14:15], s[10:11], 11
	v_readlane_b32 s11, v250, 62
	s_add_u32 s11, s11, s14
	v_readlane_b32 s26, v249, 1
	s_addc_u32 s43, s26, s15
	v_readlane_b32 s26, v249, 23
	s_add_u32 s44, s26, s22
	v_readlane_b32 s22, v249, 24
	s_addc_u32 s45, s22, s23
	s_add_u32 s46, s86, s20
	v_mov_b32_e32 v6, 0
	v_lshl_add_u64 v[144:145], v[140:141], 0, s[20:21]
	v_lshl_add_u64 v[146:147], v[142:143], 0, s[20:21]
	s_addc_u32 s47, s87, s21
	s_mov_b32 s48, -2
	s_mov_b64 s[20:21], 0
	s_add_u32 s22, s46, s20
	s_addc_u32 s23, s47, s21
	s_add_u32 s22, s22, 0x520e100
	s_addc_u32 s23, s23, 0
	s_add_u32 s49, s44, s20
	s_addc_u32 s50, s45, s21
	s_add_i32 s51, 0, 0x10000
	s_cmpk_eq_i32 s20, 0x700
	s_cselect_b32 s27, s42, s23
	s_cselect_b32 s26, s9, s22
	v_add_u32_e32 v177, s51, v148
	s_cselect_b32 s23, s43, s50
	s_cselect_b32 s22, s11, s49
	s_add_i32 s49, 0, 0x14000
	ds_read_b128 v[152:155], v177
	ds_read_b128 v[178:181], v177 offset:1024
	ds_read_b128 v[182:185], v177 offset:2048
	ds_read_b128 v[186:189], v177 offset:3072
	v_add_u32_e32 v177, s49, v148
	ds_read_b128 v[190:193], v177
	ds_read_b128 v[194:197], v177 offset:1024
	ds_read_b128 v[198:201], v177 offset:2048
	ds_read_b128 v[202:205], v177 offset:3072
	v_lshl_add_u64 v[238:239], v[146:147], 0, s[20:21]
	s_add_i32 m0, s17, 0xc000
	ds_read_b128 v[206:209], v151
	ds_read_b128 v[210:213], v151 offset:1024
	ds_read_b128 v[214:217], v151 offset:2048
	ds_read_b128 v[218:221], v151 offset:3072
	ds_read_b128 v[222:225], v151 offset:4096
	ds_read_b128 v[226:229], v151 offset:5120
	ds_read_b128 v[230:233], v151 offset:6144
	ds_read_b128 v[234:237], v151 offset:7168
	global_load_lds_dwordx4 v[238:239], off
	v_lshl_add_u64 v[238:239], v[144:145], 0, s[20:21]
	s_add_i32 m0, s17, 0xe000
	s_nop 0
	global_load_lds_dwordx4 v[238:239], off
	s_waitcnt vmcnt(8) lgkmcnt(0)
	s_barrier
	v_mfma_f32_16x16x32_f16 v[130:133], v[152:155], v[206:209], 0
	v_mfma_f32_16x16x32_f16 v[126:129], v[182:185], v[206:209], 0
	v_mfma_f32_16x16x32_f16 v[114:117], v[152:155], v[214:217], 0
	v_mfma_f32_16x16x32_f16 v[110:113], v[182:185], v[214:217], 0
	v_mfma_f32_16x16x32_f16 v[98:101], v[152:155], v[222:225], 0
	v_mfma_f32_16x16x32_f16 v[94:97], v[182:185], v[222:225], 0
	v_mfma_f32_16x16x32_f16 v[82:85], v[152:155], v[230:233], 0
	v_mfma_f32_16x16x32_f16 v[78:81], v[182:185], v[230:233], 0
	v_mfma_f32_16x16x32_f16 v[130:133], v[178:181], v[210:213], v[130:133]
	v_mfma_f32_16x16x32_f16 v[126:129], v[186:189], v[210:213], v[126:129]
	v_mfma_f32_16x16x32_f16 v[114:117], v[178:181], v[218:221], v[114:117]
	v_mfma_f32_16x16x32_f16 v[110:113], v[186:189], v[218:221], v[110:113]
	v_mfma_f32_16x16x32_f16 v[98:101], v[178:181], v[226:229], v[98:101]
	v_mfma_f32_16x16x32_f16 v[94:97], v[186:189], v[226:229], v[94:97]
	v_mfma_f32_16x16x32_f16 v[82:85], v[178:181], v[234:237], v[82:85]
	v_mfma_f32_16x16x32_f16 v[78:81], v[186:189], v[234:237], v[78:81]
	s_add_i32 s50, s51, s30
	v_lshl_add_u64 v[238:239], s[22:23], 0, v[0:1]
	s_mov_b32 m0, s50
	v_mfma_f32_16x16x32_f16 v[122:125], v[190:193], v[206:209], 0
	v_mfma_f32_16x16x32_f16 v[118:121], v[198:201], v[206:209], 0
	v_mfma_f32_16x16x32_f16 v[106:109], v[190:193], v[214:217], 0
	v_mfma_f32_16x16x32_f16 v[102:105], v[198:201], v[214:217], 0
	v_mfma_f32_16x16x32_f16 v[90:93], v[190:193], v[222:225], 0
	v_mfma_f32_16x16x32_f16 v[86:89], v[198:201], v[222:225], 0
	v_mfma_f32_16x16x32_f16 v[74:77], v[190:193], v[230:233], 0
	v_mfma_f32_16x16x32_f16 v[70:73], v[198:201], v[230:233], 0
	v_mfma_f32_16x16x32_f16 v[122:125], v[194:197], v[210:213], v[122:125]
	v_mfma_f32_16x16x32_f16 v[118:121], v[202:205], v[210:213], v[118:121]
	v_mfma_f32_16x16x32_f16 v[106:109], v[194:197], v[218:221], v[106:109]
	v_mfma_f32_16x16x32_f16 v[102:105], v[202:205], v[218:221], v[102:105]
	v_mfma_f32_16x16x32_f16 v[90:93], v[194:197], v[226:229], v[90:93]
	v_mfma_f32_16x16x32_f16 v[86:89], v[202:205], v[226:229], v[86:89]
	v_mfma_f32_16x16x32_f16 v[74:77], v[194:197], v[234:237], v[74:77]
	v_mfma_f32_16x16x32_f16 v[70:73], v[202:205], v[234:237], v[70:73]
	s_barrier
	ds_read_b128 v[206:209], v151 offset:16384
	ds_read_b128 v[210:213], v151 offset:17408
	ds_read_b128 v[214:217], v151 offset:18432
	ds_read_b128 v[218:221], v151 offset:19456
	ds_read_b128 v[222:225], v151 offset:20480
	ds_read_b128 v[226:229], v151 offset:21504
	ds_read_b128 v[230:233], v151 offset:22528
	ds_read_b128 v[234:237], v151 offset:23552
	global_load_lds_dwordx4 v[238:239], off
	s_add_i32 m0, s50, 0x2000
	s_add_u32 s50, s22, 0x40000
	v_lshl_add_u64 v[240:241], s[22:23], 0, v[2:3]
	s_addc_u32 s51, s23, 0
	s_add_i32 s49, s49, s30
	global_load_lds_dwordx4 v[240:241], off
	v_lshl_add_u64 v[242:243], s[50:51], 0, v[0:1]
	s_mov_b32 m0, s49
	v_lshl_add_u64 v[244:245], s[26:27], 0, v[134:135]
	global_load_lds_dwordx4 v[242:243], off
	v_lshl_add_u64 v[242:243], s[50:51], 0, v[2:3]
	s_add_i32 m0, s49, 0x2000
	s_nop 0
	global_load_lds_dwordx4 v[242:243], off
	v_lshl_add_u64 v[242:243], s[26:27], 0, v[138:139]
	s_mov_b32 m0, s17
	s_nop 0
	global_load_lds_dwordx4 v[242:243], off
	s_mov_b32 m0, s19
	s_nop 0
	global_load_lds_dwordx4 v[244:245], off
	s_waitcnt vmcnt(8) lgkmcnt(0)
	s_barrier
; #define STAGE(bufoff, gbase, voff) do { _Pragma("unroll") for (int _i = 0; _i < 2; ++_i) \
;     __builtin_amdgcn_global_load_lds((const unsigned*)((const char*)(gbase) + (voff)[_i]), (LAS unsigned*)(lds + (bufoff) + ldsw + _i * 8192), 16, 0, 0); } while (0)
; #define LDA(dst, b, h) do { _Pragma("unroll") for (int m = 0; m < 4; ++m) _Pragma("unroll") for (int k = 0; k < 2; ++k) dst[m][k] = *(const LAS half8*)(lds + SA(b, h) + aoff + m * 2048 + k * 1024); } while (0)
; #define LDB(dst, b, h) do { _Pragma("unroll") for (int n = 0; n < 2; ++n) _Pragma("unroll") for (int k = 0; k < 2; ++k) dst[n][k] = *(const LAS half8*)(lds + SB(b, h) + boff + n * 2048 + k * 1024); } while (0)
; #define MMA(ai, bj, At_, Bt_) do { __builtin_amdgcn_s_setprio(1); \
;     _Pragma("unroll") for (int m = 0; m < 4; ++m) _Pragma("unroll") for (int n = 0; n < 2; ++n) _Pragma("unroll") for (int k = 0; k < 2; ++k) \
;       acc[ai][bj][m][n] = MFMA16(Bt_[n][k], At_[m][k], acc[ai][bj][m][n]); \
;     __builtin_amdgcn_s_setprio(0); } while (0)
; #define WAIT_V(n) asm volatile("s_waitcnt vmcnt(" #n ")" ::: "memory")
; #define WAIT_L(n) asm volatile("s_waitcnt lgkmcnt(" #n ")" ::: "memory")
; #define BAR __builtin_amdgcn_s_barrier()
; #define SCHED __builtin_amdgcn_sched_barrier(0)
; template <int EPI>
; DI void gemm_phase(const int wid_s, const h16* __restrict__ A, const h16* __restrict__ Bt, const int N, const int K, const EpiArgs ea) {
;     ...
;       LDB(B0, 0, 0); LDB(B1, 0, 1); SCHED; LDA(At, 0, 0); STAGE(SA(1, 1), a1 + hstep, voffA);
;       WAIT_V(8); WAIT_L(0); BAR; MMA(0, 0, At, B0); MMA(0, 1, At, B1); BAR; SCHED;
;       LDA(At, 0, 1); STAGE(SB(0, 0), b2, voffB); STAGE(SB(0, 1), b2 + hstep, voffB); STAGE(SA(0, 0), a2, voffA);
;       WAIT_V(8); WAIT_L(0); BAR; MMA(1, 0, At, B0); MMA(1, 1, At, B1); BAR; SCHED;
;       LDB(B0, 1, 0); LDB(B1, 1, 1); SCHED; LDA(At, 1, 0); STAGE(SA(0, 1), a2 + hstep, voffA);
;       WAIT_V(8); WAIT_L(0); BAR; MMA(0, 0, At, B0); MMA(0, 1, At, B1); BAR; SCHED;
	v_mfma_f32_16x16x32_f16 v[66:69], v[152:155], v[206:209], 0
	v_mfma_f32_16x16x32_f16 v[62:65], v[182:185], v[206:209], 0
	v_mfma_f32_16x16x32_f16 v[50:53], v[152:155], v[214:217], 0
	v_mfma_f32_16x16x32_f16 v[46:49], v[182:185], v[214:217], 0
	v_mfma_f32_16x16x32_f16 v[34:37], v[152:155], v[222:225], 0
	v_mfma_f32_16x16x32_f16 v[30:33], v[182:185], v[222:225], 0
	v_mfma_f32_16x16x32_f16 v[18:21], v[152:155], v[230:233], 0
	v_mfma_f32_16x16x32_f16 v[14:17], v[182:185], v[230:233], 0
	v_mfma_f32_16x16x32_f16 v[66:69], v[178:181], v[210:213], v[66:69]
	v_mfma_f32_16x16x32_f16 v[62:65], v[186:189], v[210:213], v[62:65]
	v_mfma_f32_16x16x32_f16 v[50:53], v[178:181], v[218:221], v[50:53]
	v_mfma_f32_16x16x32_f16 v[46:49], v[186:189], v[218:221], v[46:49]
	v_mfma_f32_16x16x32_f16 v[34:37], v[178:181], v[226:229], v[34:37]
	v_mfma_f32_16x16x32_f16 v[30:33], v[186:189], v[226:229], v[30:33]
	v_mfma_f32_16x16x32_f16 v[18:21], v[178:181], v[234:237], v[18:21]
	v_mfma_f32_16x16x32_f16 v[14:17], v[186:189], v[234:237], v[14:17]
	s_add_i32 s49, 0, 0x18000
	v_add_u32_e32 v177, s49, v148
	s_add_i32 s50, 0, 0x1c000
	v_mfma_f32_16x16x32_f16 v[58:61], v[190:193], v[206:209], 0
	v_mfma_f32_16x16x32_f16 v[54:57], v[198:201], v[206:209], 0
	v_mfma_f32_16x16x32_f16 v[42:45], v[190:193], v[214:217], 0
	v_mfma_f32_16x16x32_f16 v[38:41], v[198:201], v[214:217], 0
	v_mfma_f32_16x16x32_f16 v[26:29], v[190:193], v[222:225], 0
	v_mfma_f32_16x16x32_f16 v[22:25], v[198:201], v[222:225], 0
	v_mfma_f32_16x16x32_f16 v[10:13], v[190:193], v[230:233], 0
	v_mfma_f32_16x16x32_f16 v[6:9], v[198:201], v[230:233], 0
	v_mfma_f32_16x16x32_f16 v[58:61], v[194:197], v[210:213], v[58:61]
	v_mfma_f32_16x16x32_f16 v[54:57], v[202:205], v[210:213], v[54:57]
	v_mfma_f32_16x16x32_f16 v[42:45], v[194:197], v[218:221], v[42:45]
	v_mfma_f32_16x16x32_f16 v[38:41], v[202:205], v[218:221], v[38:41]
	v_mfma_f32_16x16x32_f16 v[26:29], v[194:197], v[226:229], v[26:29]
	v_mfma_f32_16x16x32_f16 v[22:25], v[202:205], v[226:229], v[22:25]
	v_mfma_f32_16x16x32_f16 v[10:13], v[194:197], v[234:237], v[10:13]
	v_mfma_f32_16x16x32_f16 v[6:9], v[202:205], v[234:237], v[6:9]
	s_barrier
	ds_read_b128 v[152:155], v177
	ds_read_b128 v[178:181], v177 offset:1024
	ds_read_b128 v[182:185], v177 offset:2048
	ds_read_b128 v[186:189], v177 offset:3072
	v_add_u32_e32 v177, s50, v148
	ds_read_b128 v[190:193], v177
	ds_read_b128 v[194:197], v177 offset:1024
	ds_read_b128 v[198:201], v177 offset:2048
	ds_read_b128 v[202:205], v177 offset:3072
	s_add_u32 s26, s26, 0x40000
	s_addc_u32 s27, s27, 0
	s_mov_b32 m0, s31
	v_lshl_add_u64 v[246:247], s[26:27], 0, v[138:139]
	ds_read_b128 v[206:209], v151 offset:32768
	ds_read_b128 v[210:213], v151 offset:33792
	ds_read_b128 v[214:217], v151 offset:34816
	ds_read_b128 v[218:221], v151 offset:35840
	ds_read_b128 v[222:225], v151 offset:36864
	ds_read_b128 v[226:229], v151 offset:37888
	ds_read_b128 v[230:233], v151 offset:38912
	ds_read_b128 v[234:237], v151 offset:39936
	global_load_lds_dwordx4 v[246:247], off
	v_lshl_add_u64 v[246:247], s[26:27], 0, v[134:135]
	s_mov_b32 m0, s38
	s_nop 0
	global_load_lds_dwordx4 v[246:247], off
	s_waitcnt vmcnt(8) lgkmcnt(0)
	s_barrier
	v_mfma_f32_16x16x32_f16 v[130:133], v[152:155], v[206:209], v[130:133]
	v_mfma_f32_16x16x32_f16 v[126:129], v[182:185], v[206:209], v[126:129]
	v_mfma_f32_16x16x32_f16 v[114:117], v[152:155], v[214:217], v[114:117]
	v_mfma_f32_16x16x32_f16 v[110:113], v[182:185], v[214:217], v[110:113]
	v_mfma_f32_16x16x32_f16 v[98:101], v[152:155], v[222:225], v[98:101]
	v_mfma_f32_16x16x32_f16 v[94:97], v[182:185], v[222:225], v[94:97]
	v_mfma_f32_16x16x32_f16 v[82:85], v[152:155], v[230:233], v[82:85]
	v_mfma_f32_16x16x32_f16 v[78:81], v[182:185], v[230:233], v[78:81]
	v_mfma_f32_16x16x32_f16 v[130:133], v[178:181], v[210:213], v[130:133]
	v_mfma_f32_16x16x32_f16 v[126:129], v[186:189], v[210:213], v[126:129]
	v_mfma_f32_16x16x32_f16 v[114:117], v[178:181], v[218:221], v[114:117]
	v_mfma_f32_16x16x32_f16 v[110:113], v[186:189], v[218:221], v[110:113]
	v_mfma_f32_16x16x32_f16 v[98:101], v[178:181], v[226:229], v[98:101]
	v_mfma_f32_16x16x32_f16 v[94:97], v[186:189], v[226:229], v[94:97]
	v_mfma_f32_16x16x32_f16 v[82:85], v[178:181], v[234:237], v[82:85]
	v_mfma_f32_16x16x32_f16 v[78:81], v[186:189], v[234:237], v[78:81]
	s_add_i32 s26, s49, s30
	v_lshl_add_u64 v[238:239], v[238:239], 0, s[36:37]
	s_mov_b32 m0, s26
	v_mfma_f32_16x16x32_f16 v[122:125], v[190:193], v[206:209], v[122:125]
	v_mfma_f32_16x16x32_f16 v[118:121], v[198:201], v[206:209], v[118:121]
	v_mfma_f32_16x16x32_f16 v[106:109], v[190:193], v[214:217], v[106:109]
	v_mfma_f32_16x16x32_f16 v[102:105], v[198:201], v[214:217], v[102:105]
	v_mfma_f32_16x16x32_f16 v[90:93], v[190:193], v[222:225], v[90:93]
	v_mfma_f32_16x16x32_f16 v[86:89], v[198:201], v[222:225], v[86:89]
	v_mfma_f32_16x16x32_f16 v[74:77], v[190:193], v[230:233], v[74:77]
	v_mfma_f32_16x16x32_f16 v[70:73], v[198:201], v[230:233], v[70:73]
	v_mfma_f32_16x16x32_f16 v[122:125], v[194:197], v[210:213], v[122:125]
	v_mfma_f32_16x16x32_f16 v[118:121], v[202:205], v[210:213], v[118:121]
	v_mfma_f32_16x16x32_f16 v[106:109], v[194:197], v[218:221], v[106:109]
	v_mfma_f32_16x16x32_f16 v[102:105], v[202:205], v[218:221], v[102:105]
	v_mfma_f32_16x16x32_f16 v[90:93], v[194:197], v[226:229], v[90:93]
	v_mfma_f32_16x16x32_f16 v[86:89], v[202:205], v[226:229], v[86:89]
	v_mfma_f32_16x16x32_f16 v[74:77], v[194:197], v[234:237], v[74:77]
	v_mfma_f32_16x16x32_f16 v[70:73], v[202:205], v[234:237], v[70:73]
	s_barrier
; #define STAGE(bufoff, gbase, voff) do { _Pragma("unroll") for (int _i = 0; _i < 2; ++_i) \
;     __builtin_amdgcn_global_load_lds((const unsigned*)((const char*)(gbase) + (voff)[_i]), (LAS unsigned*)(lds + (bufoff) + ldsw + _i * 8192), 16, 0, 0); } while (0)
; #define LDA(dst, b, h) do { _Pragma("unroll") for (int m = 0; m < 4; ++m) _Pragma("unroll") for (int k = 0; k < 2; ++k) dst[m][k] = *(const LAS half8*)(lds + SA(b, h) + aoff + m * 2048 + k * 1024); } while (0)
; #define LDB(dst, b, h) do { _Pragma("unroll") for (int n = 0; n < 2; ++n) _Pragma("unroll") for (int k = 0; k < 2; ++k) dst[n][k] = *(const LAS half8*)(lds + SB(b, h) + boff + n * 2048 + k * 1024); } while (0)
; #define MMA(ai, bj, At_, Bt_) do { __builtin_amdgcn_s_setprio(1); \
;     _Pragma("unroll") for (int m = 0; m < 4; ++m) _Pragma("unroll") for (int n = 0; n < 2; ++n) _Pragma("unroll") for (int k = 0; k < 2; ++k) \
;       acc[ai][bj][m][n] = MFMA16(Bt_[n][k], At_[m][k], acc[ai][bj][m][n]); \
;     __builtin_amdgcn_s_setprio(0); } while (0)
; #define WAIT_V(n) asm volatile("s_waitcnt vmcnt(" #n ")" ::: "memory")
; #define BAR __builtin_amdgcn_s_barrier()
; template <int EPI>
; DI void gemm_phase(const int wid_s, const h16* __restrict__ A, const h16* __restrict__ Bt, const int N, const int K, const EpiArgs ea) {
;     ...
;     for (int t = 0; t < nt; t += 2) {
;       const bool last = (t == nt - 2);
;       const char* a1 = cA + (size_t)(t + 1) * kstep;
;       const char* a2 = last ? nA : cA + (size_t)(t + 2) * kstep; const char* b2 = last ? nB : cB + (size_t)(t + 2) * kstep;
;       const char* a3 = a2 + kstep; const char* b3 = b2 + kstep;
;       LDB(B0, 0, 0); LDB(B1, 0, 1); SCHED; LDA(At, 0, 0); STAGE(SA(1, 1), a1 + hstep, voffA);
;       WAIT_V(8); WAIT_L(0); BAR; MMA(0, 0, At, B0); MMA(0, 1, At, B1); BAR; SCHED;
;       LDA(At, 0, 1); STAGE(SB(0, 0), b2, voffB); STAGE(SB(0, 1), b2 + hstep, voffB); STAGE(SA(0, 0), a2, voffA);
;       WAIT_V(8); WAIT_L(0); BAR; MMA(1, 0, At, B0); MMA(1, 1, At, B1); BAR; SCHED;
;       LDB(B0, 1, 0); LDB(B1, 1, 1); SCHED; LDA(At, 1, 0); STAGE(SA(0, 1), a2 + hstep, voffA);
;       WAIT_V(8); WAIT_L(0); BAR; MMA(0, 0, At, B0); MMA(0, 1, At, B1); BAR; SCHED;
;       LDA(At, 1, 1); STAGE(SB(1, 0), b3, voffB); STAGE(SB(1, 1), b3 + hstep, voffB); STAGE(SA(1, 0), a3, voffA);
;       WAIT_V(8); WAIT_L(0); BAR; MMA(1, 0, At, B0); MMA(1, 1, At, B1); BAR; SCHED;
	ds_read_b128 v[206:209], v151 offset:49152
	ds_read_b128 v[210:213], v151 offset:50176
	ds_read_b128 v[214:217], v151 offset:51200
	ds_read_b128 v[218:221], v151 offset:52224
	ds_read_b128 v[222:225], v151 offset:53248
	ds_read_b128 v[226:229], v151 offset:54272
	ds_read_b128 v[230:233], v151 offset:55296
	ds_read_b128 v[234:237], v151 offset:56320
	global_load_lds_dwordx4 v[238:239], off
	s_add_i32 m0, s26, 0x2000
	s_add_u32 s22, s22, 0x40080
	v_lshl_add_u64 v[238:239], v[240:241], 0, s[36:37]
	s_addc_u32 s23, s23, 0
	s_add_i32 s26, s50, s30
	global_load_lds_dwordx4 v[238:239], off
	v_lshl_add_u64 v[238:239], s[22:23], 0, v[0:1]
	s_mov_b32 m0, s26
	s_nop 0
	global_load_lds_dwordx4 v[238:239], off
	v_lshl_add_u64 v[238:239], s[22:23], 0, v[2:3]
	s_add_i32 m0, s26, 0x2000
	s_nop 0
	global_load_lds_dwordx4 v[238:239], off
	v_lshl_add_u64 v[238:239], v[242:243], 0, s[36:37]
	s_mov_b32 m0, s40
	s_nop 0
	global_load_lds_dwordx4 v[238:239], off
	v_lshl_add_u64 v[238:239], v[244:245], 0, s[36:37]
	s_mov_b32 m0, s41
	s_nop 0
	global_load_lds_dwordx4 v[238:239], off
	s_waitcnt vmcnt(8) lgkmcnt(0)
	s_barrier
	v_mfma_f32_16x16x32_f16 v[66:69], v[152:155], v[206:209], v[66:69]
	v_mfma_f32_16x16x32_f16 v[62:65], v[182:185], v[206:209], v[62:65]
	v_mfma_f32_16x16x32_f16 v[50:53], v[152:155], v[214:217], v[50:53]
	v_mfma_f32_16x16x32_f16 v[46:49], v[182:185], v[214:217], v[46:49]
	v_mfma_f32_16x16x32_f16 v[34:37], v[152:155], v[222:225], v[34:37]
	v_mfma_f32_16x16x32_f16 v[30:33], v[182:185], v[222:225], v[30:33]
	v_mfma_f32_16x16x32_f16 v[18:21], v[152:155], v[230:233], v[18:21]
	v_mfma_f32_16x16x32_f16 v[14:17], v[182:185], v[230:233], v[14:17]
	v_mfma_f32_16x16x32_f16 v[66:69], v[178:181], v[210:213], v[66:69]
	v_mfma_f32_16x16x32_f16 v[62:65], v[186:189], v[210:213], v[62:65]
	v_mfma_f32_16x16x32_f16 v[50:53], v[178:181], v[218:221], v[50:53]
	v_mfma_f32_16x16x32_f16 v[46:49], v[186:189], v[218:221], v[46:49]
	v_mfma_f32_16x16x32_f16 v[34:37], v[178:181], v[226:229], v[34:37]
	v_mfma_f32_16x16x32_f16 v[30:33], v[186:189], v[226:229], v[30:33]
	v_mfma_f32_16x16x32_f16 v[18:21], v[178:181], v[234:237], v[18:21]
	v_mfma_f32_16x16x32_f16 v[14:17], v[186:189], v[234:237], v[14:17]
	v_mfma_f32_16x16x32_f16 v[58:61], v[190:193], v[206:209], v[58:61]
	v_mfma_f32_16x16x32_f16 v[54:57], v[198:201], v[206:209], v[54:57]
	v_mfma_f32_16x16x32_f16 v[42:45], v[190:193], v[214:217], v[42:45]
	v_mfma_f32_16x16x32_f16 v[38:41], v[198:201], v[214:217], v[38:41]
	v_mfma_f32_16x16x32_f16 v[26:29], v[190:193], v[222:225], v[26:29]
	v_mfma_f32_16x16x32_f16 v[22:25], v[198:201], v[222:225], v[22:25]
	v_mfma_f32_16x16x32_f16 v[10:13], v[190:193], v[230:233], v[10:13]
	v_mfma_f32_16x16x32_f16 v[6:9], v[198:201], v[230:233], v[6:9]
	v_mfma_f32_16x16x32_f16 v[58:61], v[194:197], v[210:213], v[58:61]
	v_mfma_f32_16x16x32_f16 v[54:57], v[202:205], v[210:213], v[54:57]
	v_mfma_f32_16x16x32_f16 v[42:45], v[194:197], v[218:221], v[42:45]
	v_mfma_f32_16x16x32_f16 v[38:41], v[202:205], v[218:221], v[38:41]
	v_mfma_f32_16x16x32_f16 v[26:29], v[194:197], v[226:229], v[26:29]
	v_mfma_f32_16x16x32_f16 v[22:25], v[202:205], v[226:229], v[22:25]
	v_mfma_f32_16x16x32_f16 v[10:13], v[194:197], v[234:237], v[10:13]
	v_mfma_f32_16x16x32_f16 v[6:9], v[202:205], v[234:237], v[6:9]
	s_barrier
	s_add_i32 s48, s48, 2
	s_add_u32 s20, s20, 0x100
	s_addc_u32 s21, s21, 0
	s_cmp_gt_u32 s48, 13
.LBB0_141:
	s_add_u32 s22, s46, s20
	s_addc_u32 s23, s47, s21
	s_add_u32 s22, s22, 0x520e100
	s_addc_u32 s23, s23, 0
	s_add_u32 s49, s44, s20
	s_addc_u32 s50, s45, s21
	s_add_i32 s51, 0, 0x10000
	s_cmpk_eq_i32 s20, 0x700
	s_cselect_b32 s27, s42, s23
	s_cselect_b32 s26, s9, s22
	v_add_u32_e32 v177, s51, v148
	s_cselect_b32 s23, s43, s50
	s_cselect_b32 s22, s11, s49
	s_add_i32 s49, 0, 0x14000
	ds_read_b128 v[152:155], v177
	ds_read_b128 v[178:181], v177 offset:1024
	ds_read_b128 v[182:185], v177 offset:2048
	ds_read_b128 v[186:189], v177 offset:3072
	v_add_u32_e32 v177, s49, v148
	ds_read_b128 v[190:193], v177
	ds_read_b128 v[194:197], v177 offset:1024
	ds_read_b128 v[198:201], v177 offset:2048
	ds_read_b128 v[202:205], v177 offset:3072
	v_lshl_add_u64 v[238:239], v[146:147], 0, s[20:21]
	s_add_i32 m0, s17, 0xc000
	ds_read_b128 v[206:209], v151
	ds_read_b128 v[210:213], v151 offset:1024
	ds_read_b128 v[214:217], v151 offset:2048
	ds_read_b128 v[218:221], v151 offset:3072
	ds_read_b128 v[222:225], v151 offset:4096
	ds_read_b128 v[226:229], v151 offset:5120
	ds_read_b128 v[230:233], v151 offset:6144
	ds_read_b128 v[234:237], v151 offset:7168
	global_load_lds_dwordx4 v[238:239], off
	v_lshl_add_u64 v[238:239], v[144:145], 0, s[20:21]
	s_add_i32 m0, s17, 0xe000
	s_nop 0
	global_load_lds_dwordx4 v[238:239], off
	s_waitcnt vmcnt(8) lgkmcnt(0)
	s_barrier
; #define STAGE(bufoff, gbase, voff) do { _Pragma("unroll") for (int _i = 0; _i < 2; ++_i) \
;     __builtin_amdgcn_global_load_lds((const unsigned*)((const char*)(gbase) + (voff)[_i]), (LAS unsigned*)(lds + (bufoff) + ldsw + _i * 8192), 16, 0, 0); } while (0)
; #define LDA(dst, b, h) do { _Pragma("unroll") for (int m = 0; m < 4; ++m) _Pragma("unroll") for (int k = 0; k < 2; ++k) dst[m][k] = *(const LAS half8*)(lds + SA(b, h) + aoff + m * 2048 + k * 1024); } while (0)
; #define MMA(ai, bj, At_, Bt_) do { __builtin_amdgcn_s_setprio(1); \
;     _Pragma("unroll") for (int m = 0; m < 4; ++m) _Pragma("unroll") for (int n = 0; n < 2; ++n) _Pragma("unroll") for (int k = 0; k < 2; ++k) \
;       acc[ai][bj][m][n] = MFMA16(Bt_[n][k], At_[m][k], acc[ai][bj][m][n]); \
;     __builtin_amdgcn_s_setprio(0); } while (0)
; #define WAIT_V(n) asm volatile("s_waitcnt vmcnt(" #n ")" ::: "memory")
; #define WAIT_L(n) asm volatile("s_waitcnt lgkmcnt(" #n ")" ::: "memory")
; #define BAR __builtin_amdgcn_s_barrier()
; #define SCHED __builtin_amdgcn_sched_barrier(0)
; template <int EPI>
; DI void gemm_phase(const int wid_s, const h16* __restrict__ A, const h16* __restrict__ Bt, const int N, const int K, const EpiArgs ea) {
;     ...
;       WAIT_V(8); WAIT_L(0); BAR; MMA(0, 0, At, B0); MMA(0, 1, At, B1); BAR; SCHED;
;       LDA(At, 0, 1); STAGE(SB(0, 0), b2, voffB); STAGE(SB(0, 1), b2 + hstep, voffB); STAGE(SA(0, 0), a2, voffA);
;       WAIT_V(8); WAIT_L(0); BAR; MMA(1, 0, At, B0); MMA(1, 1, At, B1); BAR; SCHED;
	v_mfma_f32_16x16x32_f16 v[130:133], v[152:155], v[206:209], v[130:133]
	v_mfma_f32_16x16x32_f16 v[126:129], v[182:185], v[206:209], v[126:129]
	v_mfma_f32_16x16x32_f16 v[114:117], v[152:155], v[214:217], v[114:117]
	v_mfma_f32_16x16x32_f16 v[110:113], v[182:185], v[214:217], v[110:113]
	v_mfma_f32_16x16x32_f16 v[98:101], v[152:155], v[222:225], v[98:101]
	v_mfma_f32_16x16x32_f16 v[94:97], v[182:185], v[222:225], v[94:97]
	v_mfma_f32_16x16x32_f16 v[82:85], v[152:155], v[230:233], v[82:85]
	v_mfma_f32_16x16x32_f16 v[78:81], v[182:185], v[230:233], v[78:81]
	v_mfma_f32_16x16x32_f16 v[130:133], v[178:181], v[210:213], v[130:133]
	v_mfma_f32_16x16x32_f16 v[126:129], v[186:189], v[210:213], v[126:129]
	v_mfma_f32_16x16x32_f16 v[114:117], v[178:181], v[218:221], v[114:117]
	v_mfma_f32_16x16x32_f16 v[110:113], v[186:189], v[218:221], v[110:113]
	v_mfma_f32_16x16x32_f16 v[98:101], v[178:181], v[226:229], v[98:101]
	v_mfma_f32_16x16x32_f16 v[94:97], v[186:189], v[226:229], v[94:97]
	v_mfma_f32_16x16x32_f16 v[82:85], v[178:181], v[234:237], v[82:85]
	v_mfma_f32_16x16x32_f16 v[78:81], v[186:189], v[234:237], v[78:81]
	s_add_i32 s50, s51, s30
	v_lshl_add_u64 v[238:239], s[22:23], 0, v[0:1]
	s_mov_b32 m0, s50
	v_mfma_f32_16x16x32_f16 v[122:125], v[190:193], v[206:209], v[122:125]
	v_mfma_f32_16x16x32_f16 v[118:121], v[198:201], v[206:209], v[118:121]
	v_mfma_f32_16x16x32_f16 v[106:109], v[190:193], v[214:217], v[106:109]
	v_mfma_f32_16x16x32_f16 v[102:105], v[198:201], v[214:217], v[102:105]
	v_mfma_f32_16x16x32_f16 v[90:93], v[190:193], v[222:225], v[90:93]
	v_mfma_f32_16x16x32_f16 v[86:89], v[198:201], v[222:225], v[86:89]
	v_mfma_f32_16x16x32_f16 v[74:77], v[190:193], v[230:233], v[74:77]
	v_mfma_f32_16x16x32_f16 v[70:73], v[198:201], v[230:233], v[70:73]
	v_mfma_f32_16x16x32_f16 v[122:125], v[194:197], v[210:213], v[122:125]
	v_mfma_f32_16x16x32_f16 v[118:121], v[202:205], v[210:213], v[118:121]
	v_mfma_f32_16x16x32_f16 v[106:109], v[194:197], v[218:221], v[106:109]
	v_mfma_f32_16x16x32_f16 v[102:105], v[202:205], v[218:221], v[102:105]
	v_mfma_f32_16x16x32_f16 v[90:93], v[194:197], v[226:229], v[90:93]
	v_mfma_f32_16x16x32_f16 v[86:89], v[202:205], v[226:229], v[86:89]
	v_mfma_f32_16x16x32_f16 v[74:77], v[194:197], v[234:237], v[74:77]
	v_mfma_f32_16x16x32_f16 v[70:73], v[202:205], v[234:237], v[70:73]
	s_barrier
	ds_read_b128 v[206:209], v151 offset:16384
	ds_read_b128 v[210:213], v151 offset:17408
	ds_read_b128 v[214:217], v151 offset:18432
	ds_read_b128 v[218:221], v151 offset:19456
	ds_read_b128 v[222:225], v151 offset:20480
	ds_read_b128 v[226:229], v151 offset:21504
	ds_read_b128 v[230:233], v151 offset:22528
	ds_read_b128 v[234:237], v151 offset:23552
	global_load_lds_dwordx4 v[238:239], off
	s_add_i32 m0, s50, 0x2000
	s_add_u32 s50, s22, 0x40000
	v_lshl_add_u64 v[240:241], s[22:23], 0, v[2:3]
	s_addc_u32 s51, s23, 0
	s_add_i32 s49, s49, s30
	global_load_lds_dwordx4 v[240:241], off
	v_lshl_add_u64 v[242:243], s[50:51], 0, v[0:1]
	s_mov_b32 m0, s49
	v_lshl_add_u64 v[244:245], s[26:27], 0, v[134:135]
	global_load_lds_dwordx4 v[242:243], off
	v_lshl_add_u64 v[242:243], s[50:51], 0, v[2:3]
	s_add_i32 m0, s49, 0x2000
	s_nop 0
	global_load_lds_dwordx4 v[242:243], off
	v_lshl_add_u64 v[242:243], s[26:27], 0, v[138:139]
	s_mov_b32 m0, s17
	s_nop 0
	global_load_lds_dwordx4 v[242:243], off
	s_mov_b32 m0, s19
	s_nop 0
	global_load_lds_dwordx4 v[244:245], off
	s_waitcnt vmcnt(8) lgkmcnt(0)
	s_barrier
	v_mfma_f32_16x16x32_f16 v[66:69], v[152:155], v[206:209], v[66:69]
	v_mfma_f32_16x16x32_f16 v[62:65], v[182:185], v[206:209], v[62:65]
	v_mfma_f32_16x16x32_f16 v[50:53], v[152:155], v[214:217], v[50:53]
	v_mfma_f32_16x16x32_f16 v[46:49], v[182:185], v[214:217], v[46:49]
	v_mfma_f32_16x16x32_f16 v[34:37], v[152:155], v[222:225], v[34:37]
	v_mfma_f32_16x16x32_f16 v[30:33], v[182:185], v[222:225], v[30:33]
	v_mfma_f32_16x16x32_f16 v[18:21], v[152:155], v[230:233], v[18:21]
	v_mfma_f32_16x16x32_f16 v[14:17], v[182:185], v[230:233], v[14:17]
	v_mfma_f32_16x16x32_f16 v[66:69], v[178:181], v[210:213], v[66:69]
	v_mfma_f32_16x16x32_f16 v[62:65], v[186:189], v[210:213], v[62:65]
	v_mfma_f32_16x16x32_f16 v[50:53], v[178:181], v[218:221], v[50:53]
	v_mfma_f32_16x16x32_f16 v[46:49], v[186:189], v[218:221], v[46:49]
	v_mfma_f32_16x16x32_f16 v[34:37], v[178:181], v[226:229], v[34:37]
	v_mfma_f32_16x16x32_f16 v[30:33], v[186:189], v[226:229], v[30:33]
	v_mfma_f32_16x16x32_f16 v[18:21], v[178:181], v[234:237], v[18:21]
	v_mfma_f32_16x16x32_f16 v[14:17], v[186:189], v[234:237], v[14:17]
	s_add_i32 s49, 0, 0x18000
	v_add_u32_e32 v177, s49, v148
	s_add_i32 s50, 0, 0x1c000
	v_mfma_f32_16x16x32_f16 v[58:61], v[190:193], v[206:209], v[58:61]
	v_mfma_f32_16x16x32_f16 v[54:57], v[198:201], v[206:209], v[54:57]
	v_mfma_f32_16x16x32_f16 v[42:45], v[190:193], v[214:217], v[42:45]
	v_mfma_f32_16x16x32_f16 v[38:41], v[198:201], v[214:217], v[38:41]
	v_mfma_f32_16x16x32_f16 v[26:29], v[190:193], v[222:225], v[26:29]
	v_mfma_f32_16x16x32_f16 v[22:25], v[198:201], v[222:225], v[22:25]
	v_mfma_f32_16x16x32_f16 v[10:13], v[190:193], v[230:233], v[10:13]
	v_mfma_f32_16x16x32_f16 v[6:9], v[198:201], v[230:233], v[6:9]
	v_mfma_f32_16x16x32_f16 v[58:61], v[194:197], v[210:213], v[58:61]
	v_mfma_f32_16x16x32_f16 v[54:57], v[202:205], v[210:213], v[54:57]
	v_mfma_f32_16x16x32_f16 v[42:45], v[194:197], v[218:221], v[42:45]
	v_mfma_f32_16x16x32_f16 v[38:41], v[202:205], v[218:221], v[38:41]
	v_mfma_f32_16x16x32_f16 v[26:29], v[194:197], v[226:229], v[26:29]
	v_mfma_f32_16x16x32_f16 v[22:25], v[202:205], v[226:229], v[22:25]
	v_mfma_f32_16x16x32_f16 v[10:13], v[194:197], v[234:237], v[10:13]
	v_mfma_f32_16x16x32_f16 v[6:9], v[202:205], v[234:237], v[6:9]
	s_barrier
; #define STAGE(bufoff, gbase, voff) do { _Pragma("unroll") for (int _i = 0; _i < 2; ++_i) \
;     __builtin_amdgcn_global_load_lds((const unsigned*)((const char*)(gbase) + (voff)[_i]), (LAS unsigned*)(lds + (bufoff) + ldsw + _i * 8192), 16, 0, 0); } while (0)
; #define LDA(dst, b, h) do { _Pragma("unroll") for (int m = 0; m < 4; ++m) _Pragma("unroll") for (int k = 0; k < 2; ++k) dst[m][k] = *(const LAS half8*)(lds + SA(b, h) + aoff + m * 2048 + k * 1024); } while (0)
; #define LDB(dst, b, h) do { _Pragma("unroll") for (int n = 0; n < 2; ++n) _Pragma("unroll") for (int k = 0; k < 2; ++k) dst[n][k] = *(const LAS half8*)(lds + SB(b, h) + boff + n * 2048 + k * 1024); } while (0)
; #define MMA(ai, bj, At_, Bt_) do { __builtin_amdgcn_s_setprio(1); \
;     _Pragma("unroll") for (int m = 0; m < 4; ++m) _Pragma("unroll") for (int n = 0; n < 2; ++n) _Pragma("unroll") for (int k = 0; k < 2; ++k) \
;       acc[ai][bj][m][n] = MFMA16(Bt_[n][k], At_[m][k], acc[ai][bj][m][n]); \
;     __builtin_amdgcn_s_setprio(0); } while (0)
; #define WAIT_V(n) asm volatile("s_waitcnt vmcnt(" #n ")" ::: "memory")
; #define WAIT_L(n) asm volatile("s_waitcnt lgkmcnt(" #n ")" ::: "memory")
; #define BAR __builtin_amdgcn_s_barrier()
; #define SCHED __builtin_amdgcn_sched_barrier(0)
; template <int EPI>
; DI void gemm_phase(const int wid_s, const h16* __restrict__ A, const h16* __restrict__ Bt, const int N, const int K, const EpiArgs ea) {
;     ...
;       LDB(B0, 1, 0); LDB(B1, 1, 1); SCHED; LDA(At, 1, 0); STAGE(SA(0, 1), a2 + hstep, voffA);
;       WAIT_V(8); WAIT_L(0); BAR; MMA(0, 0, At, B0); MMA(0, 1, At, B1); BAR; SCHED;
;       LDA(At, 1, 1); STAGE(SB(1, 0), b3, voffB); STAGE(SB(1, 1), b3 + hstep, voffB); STAGE(SA(1, 0), a3, voffA);
;       WAIT_V(8); WAIT_L(0); BAR; MMA(1, 0, At, B0); MMA(1, 1, At, B1); BAR; SCHED;
;     }
;     if (wr == 0) BAR;
	ds_read_b128 v[152:155], v177
	ds_read_b128 v[178:181], v177 offset:1024
	ds_read_b128 v[182:185], v177 offset:2048
	ds_read_b128 v[186:189], v177 offset:3072
	v_add_u32_e32 v177, s50, v148
	ds_read_b128 v[190:193], v177
	ds_read_b128 v[194:197], v177 offset:1024
	ds_read_b128 v[198:201], v177 offset:2048
	ds_read_b128 v[202:205], v177 offset:3072
	s_add_u32 s26, s26, 0x40000
	s_addc_u32 s27, s27, 0
	s_mov_b32 m0, s31
	v_lshl_add_u64 v[246:247], s[26:27], 0, v[138:139]
	ds_read_b128 v[206:209], v151 offset:32768
	ds_read_b128 v[210:213], v151 offset:33792
	ds_read_b128 v[214:217], v151 offset:34816
	ds_read_b128 v[218:221], v151 offset:35840
	ds_read_b128 v[222:225], v151 offset:36864
	ds_read_b128 v[226:229], v151 offset:37888
	ds_read_b128 v[230:233], v151 offset:38912
	ds_read_b128 v[234:237], v151 offset:39936
	global_load_lds_dwordx4 v[246:247], off
	v_lshl_add_u64 v[246:247], s[26:27], 0, v[134:135]
	s_mov_b32 m0, s38
	s_nop 0
	global_load_lds_dwordx4 v[246:247], off
	s_waitcnt vmcnt(8) lgkmcnt(0)
	s_barrier
	v_mfma_f32_16x16x32_f16 v[130:133], v[152:155], v[206:209], v[130:133]
	v_mfma_f32_16x16x32_f16 v[126:129], v[182:185], v[206:209], v[126:129]
	v_mfma_f32_16x16x32_f16 v[114:117], v[152:155], v[214:217], v[114:117]
	v_mfma_f32_16x16x32_f16 v[110:113], v[182:185], v[214:217], v[110:113]
	v_mfma_f32_16x16x32_f16 v[98:101], v[152:155], v[222:225], v[98:101]
	v_mfma_f32_16x16x32_f16 v[94:97], v[182:185], v[222:225], v[94:97]
	v_mfma_f32_16x16x32_f16 v[82:85], v[152:155], v[230:233], v[82:85]
	v_mfma_f32_16x16x32_f16 v[78:81], v[182:185], v[230:233], v[78:81]
	v_mfma_f32_16x16x32_f16 v[130:133], v[178:181], v[210:213], v[130:133]
	v_mfma_f32_16x16x32_f16 v[126:129], v[186:189], v[210:213], v[126:129]
	v_mfma_f32_16x16x32_f16 v[114:117], v[178:181], v[218:221], v[114:117]
	v_mfma_f32_16x16x32_f16 v[110:113], v[186:189], v[218:221], v[110:113]
	v_mfma_f32_16x16x32_f16 v[98:101], v[178:181], v[226:229], v[98:101]
	v_mfma_f32_16x16x32_f16 v[94:97], v[186:189], v[226:229], v[94:97]
	v_mfma_f32_16x16x32_f16 v[82:85], v[178:181], v[234:237], v[82:85]
	v_mfma_f32_16x16x32_f16 v[78:81], v[186:189], v[234:237], v[78:81]
	s_add_i32 s26, s49, s30
	v_lshl_add_u64 v[238:239], v[238:239], 0, s[36:37]
	s_mov_b32 m0, s26
	v_mfma_f32_16x16x32_f16 v[122:125], v[190:193], v[206:209], v[122:125]
	v_mfma_f32_16x16x32_f16 v[118:121], v[198:201], v[206:209], v[118:121]
	v_mfma_f32_16x16x32_f16 v[106:109], v[190:193], v[214:217], v[106:109]
	v_mfma_f32_16x16x32_f16 v[102:105], v[198:201], v[214:217], v[102:105]
	v_mfma_f32_16x16x32_f16 v[90:93], v[190:193], v[222:225], v[90:93]
	v_mfma_f32_16x16x32_f16 v[86:89], v[198:201], v[222:225], v[86:89]
	v_mfma_f32_16x16x32_f16 v[74:77], v[190:193], v[230:233], v[74:77]
	v_mfma_f32_16x16x32_f16 v[70:73], v[198:201], v[230:233], v[70:73]
	v_mfma_f32_16x16x32_f16 v[122:125], v[194:197], v[210:213], v[122:125]
	v_mfma_f32_16x16x32_f16 v[118:121], v[202:205], v[210:213], v[118:121]
	v_mfma_f32_16x16x32_f16 v[106:109], v[194:197], v[218:221], v[106:109]
	v_mfma_f32_16x16x32_f16 v[102:105], v[202:205], v[218:221], v[102:105]
	v_mfma_f32_16x16x32_f16 v[90:93], v[194:197], v[226:229], v[90:93]
	v_mfma_f32_16x16x32_f16 v[86:89], v[202:205], v[226:229], v[86:89]
	v_mfma_f32_16x16x32_f16 v[74:77], v[194:197], v[234:237], v[74:77]
	v_mfma_f32_16x16x32_f16 v[70:73], v[202:205], v[234:237], v[70:73]
	s_barrier
	ds_read_b128 v[206:209], v151 offset:49152
	ds_read_b128 v[210:213], v151 offset:50176
	ds_read_b128 v[214:217], v151 offset:51200
	ds_read_b128 v[218:221], v151 offset:52224
	ds_read_b128 v[222:225], v151 offset:53248
	ds_read_b128 v[226:229], v151 offset:54272
	ds_read_b128 v[230:233], v151 offset:55296
	ds_read_b128 v[234:237], v151 offset:56320
	global_load_lds_dwordx4 v[238:239], off
	s_add_i32 m0, s26, 0x2000
	s_add_u32 s22, s22, 0x40080
	v_lshl_add_u64 v[238:239], v[240:241], 0, s[36:37]
	s_addc_u32 s23, s23, 0
	s_add_i32 s26, s50, s30
	global_load_lds_dwordx4 v[238:239], off
	v_lshl_add_u64 v[238:239], s[22:23], 0, v[0:1]
	s_mov_b32 m0, s26
	s_nop 0
	global_load_lds_dwordx4 v[238:239], off
	v_lshl_add_u64 v[238:239], s[22:23], 0, v[2:3]
	s_add_i32 m0, s26, 0x2000
	s_nop 0
	global_load_lds_dwordx4 v[238:239], off
	v_lshl_add_u64 v[238:239], v[242:243], 0, s[36:37]
	s_mov_b32 m0, s40
	s_nop 0
	global_load_lds_dwordx4 v[238:239], off
	v_lshl_add_u64 v[238:239], v[244:245], 0, s[36:37]
	s_mov_b32 m0, s41
	s_nop 0
	global_load_lds_dwordx4 v[238:239], off
	s_waitcnt vmcnt(8) lgkmcnt(0)
	s_barrier
	v_mfma_f32_16x16x32_f16 v[66:69], v[152:155], v[206:209], v[66:69]
	v_mfma_f32_16x16x32_f16 v[62:65], v[182:185], v[206:209], v[62:65]
	v_mfma_f32_16x16x32_f16 v[50:53], v[152:155], v[214:217], v[50:53]
	v_mfma_f32_16x16x32_f16 v[46:49], v[182:185], v[214:217], v[46:49]
	v_mfma_f32_16x16x32_f16 v[34:37], v[152:155], v[222:225], v[34:37]
	v_mfma_f32_16x16x32_f16 v[30:33], v[182:185], v[222:225], v[30:33]
	v_mfma_f32_16x16x32_f16 v[18:21], v[152:155], v[230:233], v[18:21]
	v_mfma_f32_16x16x32_f16 v[14:17], v[182:185], v[230:233], v[14:17]
	v_mfma_f32_16x16x32_f16 v[66:69], v[178:181], v[210:213], v[66:69]
	v_mfma_f32_16x16x32_f16 v[62:65], v[186:189], v[210:213], v[62:65]
	v_mfma_f32_16x16x32_f16 v[50:53], v[178:181], v[218:221], v[50:53]
	v_mfma_f32_16x16x32_f16 v[46:49], v[186:189], v[218:221], v[46:49]
	v_mfma_f32_16x16x32_f16 v[34:37], v[178:181], v[226:229], v[34:37]
	v_mfma_f32_16x16x32_f16 v[30:33], v[186:189], v[226:229], v[30:33]
	v_mfma_f32_16x16x32_f16 v[18:21], v[178:181], v[234:237], v[18:21]
	v_mfma_f32_16x16x32_f16 v[14:17], v[186:189], v[234:237], v[14:17]
	v_mfma_f32_16x16x32_f16 v[58:61], v[190:193], v[206:209], v[58:61]
	v_mfma_f32_16x16x32_f16 v[54:57], v[198:201], v[206:209], v[54:57]
	v_mfma_f32_16x16x32_f16 v[42:45], v[190:193], v[214:217], v[42:45]
	v_mfma_f32_16x16x32_f16 v[38:41], v[198:201], v[214:217], v[38:41]
	v_mfma_f32_16x16x32_f16 v[26:29], v[190:193], v[222:225], v[26:29]
	v_mfma_f32_16x16x32_f16 v[22:25], v[198:201], v[222:225], v[22:25]
	v_mfma_f32_16x16x32_f16 v[10:13], v[190:193], v[230:233], v[10:13]
	v_mfma_f32_16x16x32_f16 v[6:9], v[198:201], v[230:233], v[6:9]
	v_mfma_f32_16x16x32_f16 v[58:61], v[194:197], v[210:213], v[58:61]
	v_mfma_f32_16x16x32_f16 v[54:57], v[202:205], v[210:213], v[54:57]
	v_mfma_f32_16x16x32_f16 v[42:45], v[194:197], v[218:221], v[42:45]
	v_mfma_f32_16x16x32_f16 v[38:41], v[202:205], v[218:221], v[38:41]
	v_mfma_f32_16x16x32_f16 v[26:29], v[194:197], v[226:229], v[26:29]
	v_mfma_f32_16x16x32_f16 v[22:25], v[202:205], v[226:229], v[22:25]
	v_mfma_f32_16x16x32_f16 v[10:13], v[194:197], v[234:237], v[10:13]
	v_mfma_f32_16x16x32_f16 v[6:9], v[202:205], v[234:237], v[6:9]
	s_barrier
	s_add_i32 s48, s48, 2
	s_add_u32 s20, s20, 0x100
	s_addc_u32 s21, s21, 0
	s_cmp_gt_u32 s48, 13
	s_cbranch_scc0 .LBB0_141
	s_and_b64 vcc, exec, s[4:5]
	s_cbranch_vccz .LBB0_144
	s_barrier

; #define STAGE(bufoff, gbase, voff) do { _Pragma("unroll") for (int _i = 0; _i < 2; ++_i) \
;     __builtin_amdgcn_global_load_lds((const unsigned*)((const char*)(gbase) + (voff)[_i]), (LAS unsigned*)(lds + (bufoff) + ldsw + _i * 8192), 16, 0, 0); } while (0)
; #define LDA(dst, b, h) do { _Pragma("unroll") for (int m = 0; m < 4; ++m) _Pragma("unroll") for (int k = 0; k < 2; ++k) dst[m][k] = *(const LAS half8*)(lds + SA(b, h) + aoff + m * 2048 + k * 1024); } while (0)
; #define LDB(dst, b, h) do { _Pragma("unroll") for (int n = 0; n < 2; ++n) _Pragma("unroll") for (int k = 0; k < 2; ++k) dst[n][k] = *(const LAS half8*)(lds + SB(b, h) + boff + n * 2048 + k * 1024); } while (0)
; #define MMA(ai, bj, At_, Bt_) do { __builtin_amdgcn_s_setprio(1); \
;     _Pragma("unroll") for (int m = 0; m < 4; ++m) _Pragma("unroll") for (int n = 0; n < 2; ++n) _Pragma("unroll") for (int k = 0; k < 2; ++k) \
;       acc[ai][bj][m][n] = MFMA16(Bt_[n][k], At_[m][k], acc[ai][bj][m][n]); \
;     __builtin_amdgcn_s_setprio(0); } while (0)
; #define WAIT_V(n) asm volatile("s_waitcnt vmcnt(" #n ")" ::: "memory")
; #define WAIT_L(n) asm volatile("s_waitcnt lgkmcnt(" #n ")" ::: "memory")
; #define BAR __builtin_amdgcn_s_barrier()
; template <int EPI>
; DI void gemm_phase(const int wid_s, const h16* __restrict__ A, const h16* __restrict__ Bt, const int N, const int K, const EpiArgs ea) {
;     ...
;     const int Ln = L + (int)gridDim.x;
;     const bool has_next = Ln < nwg;
;     int nbrow = brow, nbcol = bcol;
;     if (has_next) TILE_RC(Ln, nbrow, nbcol);
;     const char* nA = (const char*)A + (size_t)nbrow * K * 2;
;     const char* nB = (const char*)Bt + (size_t)nbcol * K * 2;
;     for (int t = 0; t < nt; t += 2) {
;       const bool last = (t == nt - 2);
;       const char* a1 = cA + (size_t)(t + 1) * kstep;
;       const char* a2 = last ? nA : cA + (size_t)(t + 2) * kstep; const char* b2 = last ? nB : cB + (size_t)(t + 2) * kstep;
;       const char* a3 = a2 + kstep; const char* b3 = b2 + kstep;
;       LDB(B0, 0, 0); LDB(B1, 0, 1); SCHED; LDA(At, 0, 0); STAGE(SA(1, 1), a1 + hstep, voffA);
;       WAIT_V(8); WAIT_L(0); BAR; MMA(0, 0, At, B0); MMA(0, 1, At, B1); BAR; SCHED;
;       LDA(At, 0, 1); STAGE(SB(0, 0), b2, voffB); STAGE(SB(0, 1), b2 + hstep, voffB); STAGE(SA(0, 0), a2, voffA);
;       WAIT_V(8); WAIT_L(0); BAR; MMA(1, 0, At, B0); MMA(1, 1, At, B1); BAR; SCHED;
.LBB0_174:
	s_ashr_i32 s9, s8, 31
	s_lshl_b64 s[12:13], s[8:9], 11
	v_readlane_b32 s14, v250, 46
	v_readlane_b32 s15, v250, 47
	s_add_u32 s12, s14, s12
	s_addc_u32 s13, s15, s13
	s_ashr_i32 s11, s10, 31
	s_lshl_b64 s[14:15], s[10:11], 11
	v_readlane_b32 s9, v249, 6
	s_add_u32 s9, s9, s14
	v_readlane_b32 s11, v249, 7
	s_addc_u32 s11, s11, s15
	v_readlane_b32 s26, v249, 27
	s_add_u32 s41, s26, s20
	v_readlane_b32 s20, v249, 28
	s_addc_u32 s42, s20, s21
	s_add_u32 s20, s22, 0x40080
	v_mov_b32_e32 v6, 0
	s_addc_u32 s21, s23, 0
	s_mov_b32 s43, -2
	s_add_u32 s22, s20, 0xfffc0080
	s_addc_u32 s23, s21, -1
	s_add_i32 s44, 0, 0x10000
	s_cmp_eq_u32 s43, 12
	s_cselect_b32 s27, s13, s23
	s_cselect_b32 s26, s12, s22
	v_add_u32_e32 v177, s44, v148
	s_cselect_b32 s23, s11, s42
	s_cselect_b32 s22, s9, s41
	s_add_i32 s46, 0, 0x14000
	ds_read_b128 v[144:147], v177
	ds_read_b128 v[152:155], v177 offset:1024
	ds_read_b128 v[178:181], v177 offset:2048
	ds_read_b128 v[182:185], v177 offset:3072
	v_add_u32_e32 v177, s46, v148
	ds_read_b128 v[186:189], v177
	ds_read_b128 v[190:193], v177 offset:1024
	ds_read_b128 v[194:197], v177 offset:2048
	ds_read_b128 v[198:201], v177 offset:3072
	v_lshl_add_u64 v[234:235], s[20:21], 0, v[142:143]
	s_add_i32 m0, s17, 0xc000
	ds_read_b128 v[202:205], v151
	ds_read_b128 v[206:209], v151 offset:1024
	ds_read_b128 v[210:213], v151 offset:2048
	ds_read_b128 v[214:217], v151 offset:3072
	ds_read_b128 v[218:221], v151 offset:4096
	ds_read_b128 v[222:225], v151 offset:5120
	ds_read_b128 v[226:229], v151 offset:6144
	ds_read_b128 v[230:233], v151 offset:7168
	global_load_lds_dwordx4 v[234:235], off
	v_lshl_add_u64 v[234:235], s[20:21], 0, v[140:141]
	s_add_i32 m0, s17, 0xe000
	s_nop 0
	global_load_lds_dwordx4 v[234:235], off
	s_waitcnt vmcnt(8) lgkmcnt(0)
	s_barrier
	v_mfma_f32_16x16x32_f16 v[130:133], v[144:147], v[202:205], 0
	v_mfma_f32_16x16x32_f16 v[126:129], v[178:181], v[202:205], 0
	v_mfma_f32_16x16x32_f16 v[114:117], v[144:147], v[210:213], 0
	v_mfma_f32_16x16x32_f16 v[110:113], v[178:181], v[210:213], 0
	v_mfma_f32_16x16x32_f16 v[98:101], v[144:147], v[218:221], 0
	v_mfma_f32_16x16x32_f16 v[94:97], v[178:181], v[218:221], 0
	v_mfma_f32_16x16x32_f16 v[82:85], v[144:147], v[226:229], 0
	v_mfma_f32_16x16x32_f16 v[78:81], v[178:181], v[226:229], 0
	v_mfma_f32_16x16x32_f16 v[130:133], v[152:155], v[206:209], v[130:133]
	v_mfma_f32_16x16x32_f16 v[126:129], v[182:185], v[206:209], v[126:129]
	v_mfma_f32_16x16x32_f16 v[114:117], v[152:155], v[214:217], v[114:117]
	v_mfma_f32_16x16x32_f16 v[110:113], v[182:185], v[214:217], v[110:113]
	v_mfma_f32_16x16x32_f16 v[98:101], v[152:155], v[222:225], v[98:101]
	v_mfma_f32_16x16x32_f16 v[94:97], v[182:185], v[222:225], v[94:97]
	v_mfma_f32_16x16x32_f16 v[82:85], v[152:155], v[230:233], v[82:85]
	v_mfma_f32_16x16x32_f16 v[78:81], v[182:185], v[230:233], v[78:81]
	s_add_i32 s44, s44, s30
	v_lshl_add_u64 v[234:235], s[22:23], 0, v[0:1]
	s_mov_b32 m0, s44
	v_mfma_f32_16x16x32_f16 v[122:125], v[186:189], v[202:205], 0
	v_mfma_f32_16x16x32_f16 v[118:121], v[194:197], v[202:205], 0
	v_mfma_f32_16x16x32_f16 v[106:109], v[186:189], v[210:213], 0
	v_mfma_f32_16x16x32_f16 v[102:105], v[194:197], v[210:213], 0
	v_mfma_f32_16x16x32_f16 v[90:93], v[186:189], v[218:221], 0
	v_mfma_f32_16x16x32_f16 v[86:89], v[194:197], v[218:221], 0
	v_mfma_f32_16x16x32_f16 v[74:77], v[186:189], v[226:229], 0
	v_mfma_f32_16x16x32_f16 v[70:73], v[194:197], v[226:229], 0
	v_mfma_f32_16x16x32_f16 v[122:125], v[190:193], v[206:209], v[122:125]
	v_mfma_f32_16x16x32_f16 v[118:121], v[198:201], v[206:209], v[118:121]
	v_mfma_f32_16x16x32_f16 v[106:109], v[190:193], v[214:217], v[106:109]
	v_mfma_f32_16x16x32_f16 v[102:105], v[198:201], v[214:217], v[102:105]
	v_mfma_f32_16x16x32_f16 v[90:93], v[190:193], v[222:225], v[90:93]
	v_mfma_f32_16x16x32_f16 v[86:89], v[198:201], v[222:225], v[86:89]
	v_mfma_f32_16x16x32_f16 v[74:77], v[190:193], v[230:233], v[74:77]
	v_mfma_f32_16x16x32_f16 v[70:73], v[198:201], v[230:233], v[70:73]
	s_barrier
	ds_read_b128 v[202:205], v151 offset:16384
	ds_read_b128 v[206:209], v151 offset:17408
	ds_read_b128 v[210:213], v151 offset:18432
	ds_read_b128 v[214:217], v151 offset:19456
	ds_read_b128 v[218:221], v151 offset:20480
	ds_read_b128 v[222:225], v151 offset:21504
	ds_read_b128 v[226:229], v151 offset:22528
	ds_read_b128 v[230:233], v151 offset:23552
	global_load_lds_dwordx4 v[234:235], off
	s_add_i32 m0, s44, 0x2000
	s_add_u32 s44, s22, 0x40000
	v_lshl_add_u64 v[236:237], s[22:23], 0, v[138:139]
	s_addc_u32 s45, s23, 0
	s_add_i32 s46, s46, s30
	global_load_lds_dwordx4 v[236:237], off
	v_lshl_add_u64 v[238:239], s[44:45], 0, v[0:1]
	s_mov_b32 m0, s46
	v_lshl_add_u64 v[240:241], s[26:27], 0, v[134:135]
	global_load_lds_dwordx4 v[238:239], off
	v_lshl_add_u64 v[238:239], s[44:45], 0, v[138:139]
	s_add_i32 m0, s46, 0x2000
	s_nop 0
	global_load_lds_dwordx4 v[238:239], off
	v_lshl_add_u64 v[238:239], s[26:27], 0, v[2:3]
	s_mov_b32 m0, s17
	s_nop 0
	global_load_lds_dwordx4 v[238:239], off
	s_mov_b32 m0, s19
	s_nop 0
	global_load_lds_dwordx4 v[240:241], off
	s_waitcnt vmcnt(8) lgkmcnt(0)
	s_barrier
; #define STAGE(bufoff, gbase, voff) do { _Pragma("unroll") for (int _i = 0; _i < 2; ++_i) \
;     __builtin_amdgcn_global_load_lds((const unsigned*)((const char*)(gbase) + (voff)[_i]), (LAS unsigned*)(lds + (bufoff) + ldsw + _i * 8192), 16, 0, 0); } while (0)
; #define LDA(dst, b, h) do { _Pragma("unroll") for (int m = 0; m < 4; ++m) _Pragma("unroll") for (int k = 0; k < 2; ++k) dst[m][k] = *(const LAS half8*)(lds + SA(b, h) + aoff + m * 2048 + k * 1024); } while (0)
; #define LDB(dst, b, h) do { _Pragma("unroll") for (int n = 0; n < 2; ++n) _Pragma("unroll") for (int k = 0; k < 2; ++k) dst[n][k] = *(const LAS half8*)(lds + SB(b, h) + boff + n * 2048 + k * 1024); } while (0)
; #define MMA(ai, bj, At_, Bt_) do { __builtin_amdgcn_s_setprio(1); \
;     _Pragma("unroll") for (int m = 0; m < 4; ++m) _Pragma("unroll") for (int n = 0; n < 2; ++n) _Pragma("unroll") for (int k = 0; k < 2; ++k) \
;       acc[ai][bj][m][n] = MFMA16(Bt_[n][k], At_[m][k], acc[ai][bj][m][n]); \
;     __builtin_amdgcn_s_setprio(0); } while (0)
; #define WAIT_V(n) asm volatile("s_waitcnt vmcnt(" #n ")" ::: "memory")
; #define WAIT_L(n) asm volatile("s_waitcnt lgkmcnt(" #n ")" ::: "memory")
; #define BAR __builtin_amdgcn_s_barrier()
; #define SCHED __builtin_amdgcn_sched_barrier(0)
; template <int EPI>
; DI void gemm_phase(const int wid_s, const h16* __restrict__ A, const h16* __restrict__ Bt, const int N, const int K, const EpiArgs ea) {
;     ...
;       LDB(B0, 0, 0); LDB(B1, 0, 1); SCHED; LDA(At, 0, 0); STAGE(SA(1, 1), a1 + hstep, voffA);
;       WAIT_V(8); WAIT_L(0); BAR; MMA(0, 0, At, B0); MMA(0, 1, At, B1); BAR; SCHED;
;       LDA(At, 0, 1); STAGE(SB(0, 0), b2, voffB); STAGE(SB(0, 1), b2 + hstep, voffB); STAGE(SA(0, 0), a2, voffA);
;       WAIT_V(8); WAIT_L(0); BAR; MMA(1, 0, At, B0); MMA(1, 1, At, B1); BAR; SCHED;
;       LDB(B0, 1, 0); LDB(B1, 1, 1); SCHED; LDA(At, 1, 0); STAGE(SA(0, 1), a2 + hstep, voffA);
;       WAIT_V(8); WAIT_L(0); BAR; MMA(0, 0, At, B0); MMA(0, 1, At, B1); BAR; SCHED;
	v_mfma_f32_16x16x32_f16 v[66:69], v[144:147], v[202:205], 0
	v_mfma_f32_16x16x32_f16 v[62:65], v[178:181], v[202:205], 0
	v_mfma_f32_16x16x32_f16 v[50:53], v[144:147], v[210:213], 0
	v_mfma_f32_16x16x32_f16 v[46:49], v[178:181], v[210:213], 0
	v_mfma_f32_16x16x32_f16 v[34:37], v[144:147], v[218:221], 0
	v_mfma_f32_16x16x32_f16 v[30:33], v[178:181], v[218:221], 0
	v_mfma_f32_16x16x32_f16 v[18:21], v[144:147], v[226:229], 0
	v_mfma_f32_16x16x32_f16 v[14:17], v[178:181], v[226:229], 0
	v_mfma_f32_16x16x32_f16 v[66:69], v[152:155], v[206:209], v[66:69]
	v_mfma_f32_16x16x32_f16 v[62:65], v[182:185], v[206:209], v[62:65]
	v_mfma_f32_16x16x32_f16 v[50:53], v[152:155], v[214:217], v[50:53]
	v_mfma_f32_16x16x32_f16 v[46:49], v[182:185], v[214:217], v[46:49]
	v_mfma_f32_16x16x32_f16 v[34:37], v[152:155], v[222:225], v[34:37]
	v_mfma_f32_16x16x32_f16 v[30:33], v[182:185], v[222:225], v[30:33]
	v_mfma_f32_16x16x32_f16 v[18:21], v[152:155], v[230:233], v[18:21]
	v_mfma_f32_16x16x32_f16 v[14:17], v[182:185], v[230:233], v[14:17]
	s_add_i32 s44, 0, 0x18000
	v_add_u32_e32 v177, s44, v148
	s_add_i32 s45, 0, 0x1c000
	v_mfma_f32_16x16x32_f16 v[58:61], v[186:189], v[202:205], 0
	v_mfma_f32_16x16x32_f16 v[54:57], v[194:197], v[202:205], 0
	v_mfma_f32_16x16x32_f16 v[42:45], v[186:189], v[210:213], 0
	v_mfma_f32_16x16x32_f16 v[38:41], v[194:197], v[210:213], 0
	v_mfma_f32_16x16x32_f16 v[26:29], v[186:189], v[218:221], 0
	v_mfma_f32_16x16x32_f16 v[22:25], v[194:197], v[218:221], 0
	v_mfma_f32_16x16x32_f16 v[10:13], v[186:189], v[226:229], 0
	v_mfma_f32_16x16x32_f16 v[6:9], v[194:197], v[226:229], 0
	v_mfma_f32_16x16x32_f16 v[58:61], v[190:193], v[206:209], v[58:61]
	v_mfma_f32_16x16x32_f16 v[54:57], v[198:201], v[206:209], v[54:57]
	v_mfma_f32_16x16x32_f16 v[42:45], v[190:193], v[214:217], v[42:45]
	v_mfma_f32_16x16x32_f16 v[38:41], v[198:201], v[214:217], v[38:41]
	v_mfma_f32_16x16x32_f16 v[26:29], v[190:193], v[222:225], v[26:29]
	v_mfma_f32_16x16x32_f16 v[22:25], v[198:201], v[222:225], v[22:25]
	v_mfma_f32_16x16x32_f16 v[10:13], v[190:193], v[230:233], v[10:13]
	v_mfma_f32_16x16x32_f16 v[6:9], v[198:201], v[230:233], v[6:9]
	s_barrier
	ds_read_b128 v[144:147], v177
	ds_read_b128 v[152:155], v177 offset:1024
	ds_read_b128 v[178:181], v177 offset:2048
	ds_read_b128 v[182:185], v177 offset:3072
	v_add_u32_e32 v177, s45, v148
	ds_read_b128 v[186:189], v177
	ds_read_b128 v[190:193], v177 offset:1024
	ds_read_b128 v[194:197], v177 offset:2048
	ds_read_b128 v[198:201], v177 offset:3072
	s_add_u32 s26, s26, 0x40000
	s_addc_u32 s27, s27, 0
	s_mov_b32 m0, s31
	v_lshl_add_u64 v[242:243], s[26:27], 0, v[2:3]
	ds_read_b128 v[202:205], v151 offset:32768
	ds_read_b128 v[206:209], v151 offset:33792
	ds_read_b128 v[210:213], v151 offset:34816
	ds_read_b128 v[214:217], v151 offset:35840
	ds_read_b128 v[218:221], v151 offset:36864
	ds_read_b128 v[222:225], v151 offset:37888
	ds_read_b128 v[226:229], v151 offset:38912
	ds_read_b128 v[230:233], v151 offset:39936
	global_load_lds_dwordx4 v[242:243], off
	v_lshl_add_u64 v[242:243], s[26:27], 0, v[134:135]
	s_mov_b32 m0, s38
	s_nop 0
	global_load_lds_dwordx4 v[242:243], off
	s_waitcnt vmcnt(8) lgkmcnt(0)
	s_barrier
	v_mfma_f32_16x16x32_f16 v[130:133], v[144:147], v[202:205], v[130:133]
	v_mfma_f32_16x16x32_f16 v[126:129], v[178:181], v[202:205], v[126:129]
	v_mfma_f32_16x16x32_f16 v[114:117], v[144:147], v[210:213], v[114:117]
	v_mfma_f32_16x16x32_f16 v[110:113], v[178:181], v[210:213], v[110:113]
	v_mfma_f32_16x16x32_f16 v[98:101], v[144:147], v[218:221], v[98:101]
	v_mfma_f32_16x16x32_f16 v[94:97], v[178:181], v[218:221], v[94:97]
	v_mfma_f32_16x16x32_f16 v[82:85], v[144:147], v[226:229], v[82:85]
	v_mfma_f32_16x16x32_f16 v[78:81], v[178:181], v[226:229], v[78:81]
	v_mfma_f32_16x16x32_f16 v[130:133], v[152:155], v[206:209], v[130:133]
	v_mfma_f32_16x16x32_f16 v[126:129], v[182:185], v[206:209], v[126:129]
	v_mfma_f32_16x16x32_f16 v[114:117], v[152:155], v[214:217], v[114:117]
	v_mfma_f32_16x16x32_f16 v[110:113], v[182:185], v[214:217], v[110:113]
	v_mfma_f32_16x16x32_f16 v[98:101], v[152:155], v[222:225], v[98:101]
	v_mfma_f32_16x16x32_f16 v[94:97], v[182:185], v[222:225], v[94:97]
	v_mfma_f32_16x16x32_f16 v[82:85], v[152:155], v[230:233], v[82:85]
	v_mfma_f32_16x16x32_f16 v[78:81], v[182:185], v[230:233], v[78:81]
	s_add_i32 s26, s44, s30
	v_lshl_add_u64 v[234:235], v[234:235], 0, s[36:37]
	s_mov_b32 m0, s26
	v_mfma_f32_16x16x32_f16 v[122:125], v[186:189], v[202:205], v[122:125]
	v_mfma_f32_16x16x32_f16 v[118:121], v[194:197], v[202:205], v[118:121]
	v_mfma_f32_16x16x32_f16 v[106:109], v[186:189], v[210:213], v[106:109]
	v_mfma_f32_16x16x32_f16 v[102:105], v[194:197], v[210:213], v[102:105]
	v_mfma_f32_16x16x32_f16 v[90:93], v[186:189], v[218:221], v[90:93]
	v_mfma_f32_16x16x32_f16 v[86:89], v[194:197], v[218:221], v[86:89]
	v_mfma_f32_16x16x32_f16 v[74:77], v[186:189], v[226:229], v[74:77]
	v_mfma_f32_16x16x32_f16 v[70:73], v[194:197], v[226:229], v[70:73]
	v_mfma_f32_16x16x32_f16 v[122:125], v[190:193], v[206:209], v[122:125]
	v_mfma_f32_16x16x32_f16 v[118:121], v[198:201], v[206:209], v[118:121]
	v_mfma_f32_16x16x32_f16 v[106:109], v[190:193], v[214:217], v[106:109]
	v_mfma_f32_16x16x32_f16 v[102:105], v[198:201], v[214:217], v[102:105]
	v_mfma_f32_16x16x32_f16 v[90:93], v[190:193], v[222:225], v[90:93]
	v_mfma_f32_16x16x32_f16 v[86:89], v[198:201], v[222:225], v[86:89]
	v_mfma_f32_16x16x32_f16 v[74:77], v[190:193], v[230:233], v[74:77]
	v_mfma_f32_16x16x32_f16 v[70:73], v[198:201], v[230:233], v[70:73]
	s_barrier
; #define STAGE(bufoff, gbase, voff) do { _Pragma("unroll") for (int _i = 0; _i < 2; ++_i) \
;     __builtin_amdgcn_global_load_lds((const unsigned*)((const char*)(gbase) + (voff)[_i]), (LAS unsigned*)(lds + (bufoff) + ldsw + _i * 8192), 16, 0, 0); } while (0)
; #define LDA(dst, b, h) do { _Pragma("unroll") for (int m = 0; m < 4; ++m) _Pragma("unroll") for (int k = 0; k < 2; ++k) dst[m][k] = *(const LAS half8*)(lds + SA(b, h) + aoff + m * 2048 + k * 1024); } while (0)
; #define LDB(dst, b, h) do { _Pragma("unroll") for (int n = 0; n < 2; ++n) _Pragma("unroll") for (int k = 0; k < 2; ++k) dst[n][k] = *(const LAS half8*)(lds + SB(b, h) + boff + n * 2048 + k * 1024); } while (0)
; #define MMA(ai, bj, At_, Bt_) do { __builtin_amdgcn_s_setprio(1); \
;     _Pragma("unroll") for (int m = 0; m < 4; ++m) _Pragma("unroll") for (int n = 0; n < 2; ++n) _Pragma("unroll") for (int k = 0; k < 2; ++k) \
;       acc[ai][bj][m][n] = MFMA16(Bt_[n][k], At_[m][k], acc[ai][bj][m][n]); \
;     __builtin_amdgcn_s_setprio(0); } while (0)
; #define WAIT_V(n) asm volatile("s_waitcnt vmcnt(" #n ")" ::: "memory")
; #define BAR __builtin_amdgcn_s_barrier()
; template <int EPI>
; DI void gemm_phase(const int wid_s, const h16* __restrict__ A, const h16* __restrict__ Bt, const int N, const int K, const EpiArgs ea) {
;     ...
;     for (int t = 0; t < nt; t += 2) {
;       const bool last = (t == nt - 2);
;       const char* a1 = cA + (size_t)(t + 1) * kstep;
;       const char* a2 = last ? nA : cA + (size_t)(t + 2) * kstep; const char* b2 = last ? nB : cB + (size_t)(t + 2) * kstep;
;       const char* a3 = a2 + kstep; const char* b3 = b2 + kstep;
;       LDB(B0, 0, 0); LDB(B1, 0, 1); SCHED; LDA(At, 0, 0); STAGE(SA(1, 1), a1 + hstep, voffA);
;       WAIT_V(8); WAIT_L(0); BAR; MMA(0, 0, At, B0); MMA(0, 1, At, B1); BAR; SCHED;
;       LDA(At, 0, 1); STAGE(SB(0, 0), b2, voffB); STAGE(SB(0, 1), b2 + hstep, voffB); STAGE(SA(0, 0), a2, voffA);
;       WAIT_V(8); WAIT_L(0); BAR; MMA(1, 0, At, B0); MMA(1, 1, At, B1); BAR; SCHED;
;       LDB(B0, 1, 0); LDB(B1, 1, 1); SCHED; LDA(At, 1, 0); STAGE(SA(0, 1), a2 + hstep, voffA);
;       WAIT_V(8); WAIT_L(0); BAR; MMA(0, 0, At, B0); MMA(0, 1, At, B1); BAR; SCHED;
;       LDA(At, 1, 1); STAGE(SB(1, 0), b3, voffB); STAGE(SB(1, 1), b3 + hstep, voffB); STAGE(SA(1, 0), a3, voffA);
;       WAIT_V(8); WAIT_L(0); BAR; MMA(1, 0, At, B0); MMA(1, 1, At, B1); BAR; SCHED;
	ds_read_b128 v[202:205], v151 offset:49152
	ds_read_b128 v[206:209], v151 offset:50176
	ds_read_b128 v[210:213], v151 offset:51200
	ds_read_b128 v[214:217], v151 offset:52224
	ds_read_b128 v[218:221], v151 offset:53248
	ds_read_b128 v[222:225], v151 offset:54272
	ds_read_b128 v[226:229], v151 offset:55296
	ds_read_b128 v[230:233], v151 offset:56320
	global_load_lds_dwordx4 v[234:235], off
	s_add_i32 m0, s26, 0x2000
	s_add_u32 s22, s22, 0x40080
	v_lshl_add_u64 v[234:235], v[236:237], 0, s[36:37]
	s_addc_u32 s23, s23, 0
	s_add_i32 s26, s45, s30
	global_load_lds_dwordx4 v[234:235], off
	v_lshl_add_u64 v[234:235], s[22:23], 0, v[0:1]
	s_mov_b32 m0, s26
	s_nop 0
	global_load_lds_dwordx4 v[234:235], off
	v_lshl_add_u64 v[234:235], s[22:23], 0, v[138:139]
	s_add_i32 m0, s26, 0x2000
	s_nop 0
	global_load_lds_dwordx4 v[234:235], off
	v_lshl_add_u64 v[234:235], v[238:239], 0, s[36:37]
	s_mov_b32 m0, s39
	s_nop 0
	global_load_lds_dwordx4 v[234:235], off
	v_lshl_add_u64 v[234:235], v[240:241], 0, s[36:37]
	s_mov_b32 m0, s40
	s_nop 0
	global_load_lds_dwordx4 v[234:235], off
	s_waitcnt vmcnt(8) lgkmcnt(0)
	s_barrier
	v_mfma_f32_16x16x32_f16 v[66:69], v[144:147], v[202:205], v[66:69]
	v_mfma_f32_16x16x32_f16 v[62:65], v[178:181], v[202:205], v[62:65]
	v_mfma_f32_16x16x32_f16 v[50:53], v[144:147], v[210:213], v[50:53]
	v_mfma_f32_16x16x32_f16 v[46:49], v[178:181], v[210:213], v[46:49]
	v_mfma_f32_16x16x32_f16 v[34:37], v[144:147], v[218:221], v[34:37]
	v_mfma_f32_16x16x32_f16 v[30:33], v[178:181], v[218:221], v[30:33]
	v_mfma_f32_16x16x32_f16 v[18:21], v[144:147], v[226:229], v[18:21]
	v_mfma_f32_16x16x32_f16 v[14:17], v[178:181], v[226:229], v[14:17]
	v_mfma_f32_16x16x32_f16 v[66:69], v[152:155], v[206:209], v[66:69]
	v_mfma_f32_16x16x32_f16 v[62:65], v[182:185], v[206:209], v[62:65]
	v_mfma_f32_16x16x32_f16 v[50:53], v[152:155], v[214:217], v[50:53]
	v_mfma_f32_16x16x32_f16 v[46:49], v[182:185], v[214:217], v[46:49]
	v_mfma_f32_16x16x32_f16 v[34:37], v[152:155], v[222:225], v[34:37]
	v_mfma_f32_16x16x32_f16 v[30:33], v[182:185], v[222:225], v[30:33]
	v_mfma_f32_16x16x32_f16 v[18:21], v[152:155], v[230:233], v[18:21]
	v_mfma_f32_16x16x32_f16 v[14:17], v[182:185], v[230:233], v[14:17]
	v_mfma_f32_16x16x32_f16 v[58:61], v[186:189], v[202:205], v[58:61]
	v_mfma_f32_16x16x32_f16 v[54:57], v[194:197], v[202:205], v[54:57]
	v_mfma_f32_16x16x32_f16 v[42:45], v[186:189], v[210:213], v[42:45]
	v_mfma_f32_16x16x32_f16 v[38:41], v[194:197], v[210:213], v[38:41]
	v_mfma_f32_16x16x32_f16 v[26:29], v[186:189], v[218:221], v[26:29]
	v_mfma_f32_16x16x32_f16 v[22:25], v[194:197], v[218:221], v[22:25]
	v_mfma_f32_16x16x32_f16 v[10:13], v[186:189], v[226:229], v[10:13]
	v_mfma_f32_16x16x32_f16 v[6:9], v[194:197], v[226:229], v[6:9]
	v_mfma_f32_16x16x32_f16 v[58:61], v[190:193], v[206:209], v[58:61]
	v_mfma_f32_16x16x32_f16 v[54:57], v[198:201], v[206:209], v[54:57]
	v_mfma_f32_16x16x32_f16 v[42:45], v[190:193], v[214:217], v[42:45]
	v_mfma_f32_16x16x32_f16 v[38:41], v[198:201], v[214:217], v[38:41]
	v_mfma_f32_16x16x32_f16 v[26:29], v[190:193], v[222:225], v[26:29]
	v_mfma_f32_16x16x32_f16 v[22:25], v[198:201], v[222:225], v[22:25]
	v_mfma_f32_16x16x32_f16 v[10:13], v[190:193], v[230:233], v[10:13]
	v_mfma_f32_16x16x32_f16 v[6:9], v[198:201], v[230:233], v[6:9]
	s_barrier
	s_add_i32 s43, s43, 2
	s_add_u32 s41, s41, 0x100
	s_addc_u32 s42, s42, 0
	s_add_u32 s20, s20, 0x100
	s_addc_u32 s21, s21, 0
	s_cmp_gt_u32 s43, 13
.LBB0_175:
	s_add_u32 s22, s20, 0xfffc0080
	s_addc_u32 s23, s21, -1
	s_add_i32 s44, 0, 0x10000
	s_cmp_eq_u32 s43, 12
	s_cselect_b32 s27, s13, s23
	s_cselect_b32 s26, s12, s22
	v_add_u32_e32 v177, s44, v148
	s_cselect_b32 s23, s11, s42
	s_cselect_b32 s22, s9, s41
	s_add_i32 s46, 0, 0x14000
	ds_read_b128 v[144:147], v177
	ds_read_b128 v[152:155], v177 offset:1024
	ds_read_b128 v[178:181], v177 offset:2048
	ds_read_b128 v[182:185], v177 offset:3072
	v_add_u32_e32 v177, s46, v148
	ds_read_b128 v[186:189], v177
	ds_read_b128 v[190:193], v177 offset:1024
	ds_read_b128 v[194:197], v177 offset:2048
	ds_read_b128 v[198:201], v177 offset:3072
	v_lshl_add_u64 v[234:235], s[20:21], 0, v[142:143]
	s_add_i32 m0, s17, 0xc000
	ds_read_b128 v[202:205], v151
	ds_read_b128 v[206:209], v151 offset:1024
	ds_read_b128 v[210:213], v151 offset:2048
	ds_read_b128 v[214:217], v151 offset:3072
	ds_read_b128 v[218:221], v151 offset:4096
	ds_read_b128 v[222:225], v151 offset:5120
	ds_read_b128 v[226:229], v151 offset:6144
	ds_read_b128 v[230:233], v151 offset:7168
	global_load_lds_dwordx4 v[234:235], off
	v_lshl_add_u64 v[234:235], s[20:21], 0, v[140:141]
	s_add_i32 m0, s17, 0xe000
	s_nop 0
	global_load_lds_dwordx4 v[234:235], off
	s_waitcnt vmcnt(8) lgkmcnt(0)
	s_barrier
; #define STAGE(bufoff, gbase, voff) do { _Pragma("unroll") for (int _i = 0; _i < 2; ++_i) \
;     __builtin_amdgcn_global_load_lds((const unsigned*)((const char*)(gbase) + (voff)[_i]), (LAS unsigned*)(lds + (bufoff) + ldsw + _i * 8192), 16, 0, 0); } while (0)
; #define LDA(dst, b, h) do { _Pragma("unroll") for (int m = 0; m < 4; ++m) _Pragma("unroll") for (int k = 0; k < 2; ++k) dst[m][k] = *(const LAS half8*)(lds + SA(b, h) + aoff + m * 2048 + k * 1024); } while (0)
; #define MMA(ai, bj, At_, Bt_) do { __builtin_amdgcn_s_setprio(1); \
;     _Pragma("unroll") for (int m = 0; m < 4; ++m) _Pragma("unroll") for (int n = 0; n < 2; ++n) _Pragma("unroll") for (int k = 0; k < 2; ++k) \
;       acc[ai][bj][m][n] = MFMA16(Bt_[n][k], At_[m][k], acc[ai][bj][m][n]); \
;     __builtin_amdgcn_s_setprio(0); } while (0)
; #define WAIT_V(n) asm volatile("s_waitcnt vmcnt(" #n ")" ::: "memory")
; #define WAIT_L(n) asm volatile("s_waitcnt lgkmcnt(" #n ")" ::: "memory")
; #define BAR __builtin_amdgcn_s_barrier()
; #define SCHED __builtin_amdgcn_sched_barrier(0)
; template <int EPI>
; DI void gemm_phase(const int wid_s, const h16* __restrict__ A, const h16* __restrict__ Bt, const int N, const int K, const EpiArgs ea) {
;     ...
;       WAIT_V(8); WAIT_L(0); BAR; MMA(0, 0, At, B0); MMA(0, 1, At, B1); BAR; SCHED;
;       LDA(At, 0, 1); STAGE(SB(0, 0), b2, voffB); STAGE(SB(0, 1), b2 + hstep, voffB); STAGE(SA(0, 0), a2, voffA);
;       WAIT_V(8); WAIT_L(0); BAR; MMA(1, 0, At, B0); MMA(1, 1, At, B1); BAR; SCHED;
	v_mfma_f32_16x16x32_f16 v[130:133], v[144:147], v[202:205], v[130:133]
	v_mfma_f32_16x16x32_f16 v[126:129], v[178:181], v[202:205], v[126:129]
	v_mfma_f32_16x16x32_f16 v[114:117], v[144:147], v[210:213], v[114:117]
	v_mfma_f32_16x16x32_f16 v[110:113], v[178:181], v[210:213], v[110:113]
	v_mfma_f32_16x16x32_f16 v[98:101], v[144:147], v[218:221], v[98:101]
	v_mfma_f32_16x16x32_f16 v[94:97], v[178:181], v[218:221], v[94:97]
	v_mfma_f32_16x16x32_f16 v[82:85], v[144:147], v[226:229], v[82:85]
	v_mfma_f32_16x16x32_f16 v[78:81], v[178:181], v[226:229], v[78:81]
	v_mfma_f32_16x16x32_f16 v[130:133], v[152:155], v[206:209], v[130:133]
	v_mfma_f32_16x16x32_f16 v[126:129], v[182:185], v[206:209], v[126:129]
	v_mfma_f32_16x16x32_f16 v[114:117], v[152:155], v[214:217], v[114:117]
	v_mfma_f32_16x16x32_f16 v[110:113], v[182:185], v[214:217], v[110:113]
	v_mfma_f32_16x16x32_f16 v[98:101], v[152:155], v[222:225], v[98:101]
	v_mfma_f32_16x16x32_f16 v[94:97], v[182:185], v[222:225], v[94:97]
	v_mfma_f32_16x16x32_f16 v[82:85], v[152:155], v[230:233], v[82:85]
	v_mfma_f32_16x16x32_f16 v[78:81], v[182:185], v[230:233], v[78:81]
	s_add_i32 s44, s44, s30
	v_lshl_add_u64 v[234:235], s[22:23], 0, v[0:1]
	s_mov_b32 m0, s44
	v_mfma_f32_16x16x32_f16 v[122:125], v[186:189], v[202:205], v[122:125]
	v_mfma_f32_16x16x32_f16 v[118:121], v[194:197], v[202:205], v[118:121]
	v_mfma_f32_16x16x32_f16 v[106:109], v[186:189], v[210:213], v[106:109]
	v_mfma_f32_16x16x32_f16 v[102:105], v[194:197], v[210:213], v[102:105]
	v_mfma_f32_16x16x32_f16 v[90:93], v[186:189], v[218:221], v[90:93]
	v_mfma_f32_16x16x32_f16 v[86:89], v[194:197], v[218:221], v[86:89]
	v_mfma_f32_16x16x32_f16 v[74:77], v[186:189], v[226:229], v[74:77]
	v_mfma_f32_16x16x32_f16 v[70:73], v[194:197], v[226:229], v[70:73]
	v_mfma_f32_16x16x32_f16 v[122:125], v[190:193], v[206:209], v[122:125]
	v_mfma_f32_16x16x32_f16 v[118:121], v[198:201], v[206:209], v[118:121]
	v_mfma_f32_16x16x32_f16 v[106:109], v[190:193], v[214:217], v[106:109]
	v_mfma_f32_16x16x32_f16 v[102:105], v[198:201], v[214:217], v[102:105]
	v_mfma_f32_16x16x32_f16 v[90:93], v[190:193], v[222:225], v[90:93]
	v_mfma_f32_16x16x32_f16 v[86:89], v[198:201], v[222:225], v[86:89]
	v_mfma_f32_16x16x32_f16 v[74:77], v[190:193], v[230:233], v[74:77]
	v_mfma_f32_16x16x32_f16 v[70:73], v[198:201], v[230:233], v[70:73]
	s_barrier
	ds_read_b128 v[202:205], v151 offset:16384
	ds_read_b128 v[206:209], v151 offset:17408
	ds_read_b128 v[210:213], v151 offset:18432
	ds_read_b128 v[214:217], v151 offset:19456
	ds_read_b128 v[218:221], v151 offset:20480
	ds_read_b128 v[222:225], v151 offset:21504
	ds_read_b128 v[226:229], v151 offset:22528
	ds_read_b128 v[230:233], v151 offset:23552
	global_load_lds_dwordx4 v[234:235], off
	s_add_i32 m0, s44, 0x2000
	s_add_u32 s44, s22, 0x40000
	v_lshl_add_u64 v[236:237], s[22:23], 0, v[138:139]
	s_addc_u32 s45, s23, 0
	s_add_i32 s46, s46, s30
	global_load_lds_dwordx4 v[236:237], off
	v_lshl_add_u64 v[238:239], s[44:45], 0, v[0:1]
	s_mov_b32 m0, s46
	v_lshl_add_u64 v[240:241], s[26:27], 0, v[134:135]
	global_load_lds_dwordx4 v[238:239], off
	v_lshl_add_u64 v[238:239], s[44:45], 0, v[138:139]
	s_add_i32 m0, s46, 0x2000
	s_nop 0
	global_load_lds_dwordx4 v[238:239], off
	v_lshl_add_u64 v[238:239], s[26:27], 0, v[2:3]
	s_mov_b32 m0, s17
	s_nop 0
	global_load_lds_dwordx4 v[238:239], off
	s_mov_b32 m0, s19
	s_nop 0
	global_load_lds_dwordx4 v[240:241], off
	s_waitcnt vmcnt(8) lgkmcnt(0)
	s_barrier
	v_mfma_f32_16x16x32_f16 v[66:69], v[144:147], v[202:205], v[66:69]
	v_mfma_f32_16x16x32_f16 v[62:65], v[178:181], v[202:205], v[62:65]
	v_mfma_f32_16x16x32_f16 v[50:53], v[144:147], v[210:213], v[50:53]
	v_mfma_f32_16x16x32_f16 v[46:49], v[178:181], v[210:213], v[46:49]
	v_mfma_f32_16x16x32_f16 v[34:37], v[144:147], v[218:221], v[34:37]
	v_mfma_f32_16x16x32_f16 v[30:33], v[178:181], v[218:221], v[30:33]
	v_mfma_f32_16x16x32_f16 v[18:21], v[144:147], v[226:229], v[18:21]
	v_mfma_f32_16x16x32_f16 v[14:17], v[178:181], v[226:229], v[14:17]
	v_mfma_f32_16x16x32_f16 v[66:69], v[152:155], v[206:209], v[66:69]
	v_mfma_f32_16x16x32_f16 v[62:65], v[182:185], v[206:209], v[62:65]
	v_mfma_f32_16x16x32_f16 v[50:53], v[152:155], v[214:217], v[50:53]
	v_mfma_f32_16x16x32_f16 v[46:49], v[182:185], v[214:217], v[46:49]
	v_mfma_f32_16x16x32_f16 v[34:37], v[152:155], v[222:225], v[34:37]
	v_mfma_f32_16x16x32_f16 v[30:33], v[182:185], v[222:225], v[30:33]
	v_mfma_f32_16x16x32_f16 v[18:21], v[152:155], v[230:233], v[18:21]
	v_mfma_f32_16x16x32_f16 v[14:17], v[182:185], v[230:233], v[14:17]
	s_add_i32 s44, 0, 0x18000
	v_add_u32_e32 v177, s44, v148
	s_add_i32 s45, 0, 0x1c000
	v_mfma_f32_16x16x32_f16 v[58:61], v[186:189], v[202:205], v[58:61]
	v_mfma_f32_16x16x32_f16 v[54:57], v[194:197], v[202:205], v[54:57]
	v_mfma_f32_16x16x32_f16 v[42:45], v[186:189], v[210:213], v[42:45]
	v_mfma_f32_16x16x32_f16 v[38:41], v[194:197], v[210:213], v[38:41]
	v_mfma_f32_16x16x32_f16 v[26:29], v[186:189], v[218:221], v[26:29]
	v_mfma_f32_16x16x32_f16 v[22:25], v[194:197], v[218:221], v[22:25]
	v_mfma_f32_16x16x32_f16 v[10:13], v[186:189], v[226:229], v[10:13]
	v_mfma_f32_16x16x32_f16 v[6:9], v[194:197], v[226:229], v[6:9]
	v_mfma_f32_16x16x32_f16 v[58:61], v[190:193], v[206:209], v[58:61]
	v_mfma_f32_16x16x32_f16 v[54:57], v[198:201], v[206:209], v[54:57]
	v_mfma_f32_16x16x32_f16 v[42:45], v[190:193], v[214:217], v[42:45]
	v_mfma_f32_16x16x32_f16 v[38:41], v[198:201], v[214:217], v[38:41]
	v_mfma_f32_16x16x32_f16 v[26:29], v[190:193], v[222:225], v[26:29]
	v_mfma_f32_16x16x32_f16 v[22:25], v[198:201], v[222:225], v[22:25]
	v_mfma_f32_16x16x32_f16 v[10:13], v[190:193], v[230:233], v[10:13]
	v_mfma_f32_16x16x32_f16 v[6:9], v[198:201], v[230:233], v[6:9]
	s_barrier
; #define STAGE(bufoff, gbase, voff) do { _Pragma("unroll") for (int _i = 0; _i < 2; ++_i) \
;     __builtin_amdgcn_global_load_lds((const unsigned*)((const char*)(gbase) + (voff)[_i]), (LAS unsigned*)(lds + (bufoff) + ldsw + _i * 8192), 16, 0, 0); } while (0)
; #define LDA(dst, b, h) do { _Pragma("unroll") for (int m = 0; m < 4; ++m) _Pragma("unroll") for (int k = 0; k < 2; ++k) dst[m][k] = *(const LAS half8*)(lds + SA(b, h) + aoff + m * 2048 + k * 1024); } while (0)
; #define LDB(dst, b, h) do { _Pragma("unroll") for (int n = 0; n < 2; ++n) _Pragma("unroll") for (int k = 0; k < 2; ++k) dst[n][k] = *(const LAS half8*)(lds + SB(b, h) + boff + n * 2048 + k * 1024); } while (0)
; #define MMA(ai, bj, At_, Bt_) do { __builtin_amdgcn_s_setprio(1); \
;     _Pragma("unroll") for (int m = 0; m < 4; ++m) _Pragma("unroll") for (int n = 0; n < 2; ++n) _Pragma("unroll") for (int k = 0; k < 2; ++k) \
;       acc[ai][bj][m][n] = MFMA16(Bt_[n][k], At_[m][k], acc[ai][bj][m][n]); \
;     __builtin_amdgcn_s_setprio(0); } while (0)
; #define WAIT_V(n) asm volatile("s_waitcnt vmcnt(" #n ")" ::: "memory")
; #define WAIT_L(n) asm volatile("s_waitcnt lgkmcnt(" #n ")" ::: "memory")
; #define BAR __builtin_amdgcn_s_barrier()
; #define SCHED __builtin_amdgcn_sched_barrier(0)
; template <int EPI>
; DI void gemm_phase(const int wid_s, const h16* __restrict__ A, const h16* __restrict__ Bt, const int N, const int K, const EpiArgs ea) {
;     ...
;       LDB(B0, 1, 0); LDB(B1, 1, 1); SCHED; LDA(At, 1, 0); STAGE(SA(0, 1), a2 + hstep, voffA);
;       WAIT_V(8); WAIT_L(0); BAR; MMA(0, 0, At, B0); MMA(0, 1, At, B1); BAR; SCHED;
;       LDA(At, 1, 1); STAGE(SB(1, 0), b3, voffB); STAGE(SB(1, 1), b3 + hstep, voffB); STAGE(SA(1, 0), a3, voffA);
;       WAIT_V(8); WAIT_L(0); BAR; MMA(1, 0, At, B0); MMA(1, 1, At, B1); BAR; SCHED;
;     }
;     if (wr == 0) BAR;
	ds_read_b128 v[144:147], v177
	ds_read_b128 v[152:155], v177 offset:1024
	ds_read_b128 v[178:181], v177 offset:2048
	ds_read_b128 v[182:185], v177 offset:3072
	v_add_u32_e32 v177, s45, v148
	ds_read_b128 v[186:189], v177
	ds_read_b128 v[190:193], v177 offset:1024
	ds_read_b128 v[194:197], v177 offset:2048
	ds_read_b128 v[198:201], v177 offset:3072
	s_add_u32 s26, s26, 0x40000
	s_addc_u32 s27, s27, 0
	s_mov_b32 m0, s31
	v_lshl_add_u64 v[242:243], s[26:27], 0, v[2:3]
	ds_read_b128 v[202:205], v151 offset:32768
	ds_read_b128 v[206:209], v151 offset:33792
	ds_read_b128 v[210:213], v151 offset:34816
	ds_read_b128 v[214:217], v151 offset:35840
	ds_read_b128 v[218:221], v151 offset:36864
	ds_read_b128 v[222:225], v151 offset:37888
	ds_read_b128 v[226:229], v151 offset:38912
	ds_read_b128 v[230:233], v151 offset:39936
	global_load_lds_dwordx4 v[242:243], off
	v_lshl_add_u64 v[242:243], s[26:27], 0, v[134:135]
	s_mov_b32 m0, s38
	s_nop 0
	global_load_lds_dwordx4 v[242:243], off
	s_waitcnt vmcnt(8) lgkmcnt(0)
	s_barrier
	v_mfma_f32_16x16x32_f16 v[130:133], v[144:147], v[202:205], v[130:133]
	v_mfma_f32_16x16x32_f16 v[126:129], v[178:181], v[202:205], v[126:129]
	v_mfma_f32_16x16x32_f16 v[114:117], v[144:147], v[210:213], v[114:117]
	v_mfma_f32_16x16x32_f16 v[110:113], v[178:181], v[210:213], v[110:113]
	v_mfma_f32_16x16x32_f16 v[98:101], v[144:147], v[218:221], v[98:101]
	v_mfma_f32_16x16x32_f16 v[94:97], v[178:181], v[218:221], v[94:97]
	v_mfma_f32_16x16x32_f16 v[82:85], v[144:147], v[226:229], v[82:85]
	v_mfma_f32_16x16x32_f16 v[78:81], v[178:181], v[226:229], v[78:81]
	v_mfma_f32_16x16x32_f16 v[130:133], v[152:155], v[206:209], v[130:133]
	v_mfma_f32_16x16x32_f16 v[126:129], v[182:185], v[206:209], v[126:129]
	v_mfma_f32_16x16x32_f16 v[114:117], v[152:155], v[214:217], v[114:117]
	v_mfma_f32_16x16x32_f16 v[110:113], v[182:185], v[214:217], v[110:113]
	v_mfma_f32_16x16x32_f16 v[98:101], v[152:155], v[222:225], v[98:101]
	v_mfma_f32_16x16x32_f16 v[94:97], v[182:185], v[222:225], v[94:97]
	v_mfma_f32_16x16x32_f16 v[82:85], v[152:155], v[230:233], v[82:85]
	v_mfma_f32_16x16x32_f16 v[78:81], v[182:185], v[230:233], v[78:81]
	s_add_i32 s26, s44, s30
	v_lshl_add_u64 v[234:235], v[234:235], 0, s[36:37]
	s_mov_b32 m0, s26
	v_mfma_f32_16x16x32_f16 v[122:125], v[186:189], v[202:205], v[122:125]
	v_mfma_f32_16x16x32_f16 v[118:121], v[194:197], v[202:205], v[118:121]
	v_mfma_f32_16x16x32_f16 v[106:109], v[186:189], v[210:213], v[106:109]
	v_mfma_f32_16x16x32_f16 v[102:105], v[194:197], v[210:213], v[102:105]
	v_mfma_f32_16x16x32_f16 v[90:93], v[186:189], v[218:221], v[90:93]
	v_mfma_f32_16x16x32_f16 v[86:89], v[194:197], v[218:221], v[86:89]
	v_mfma_f32_16x16x32_f16 v[74:77], v[186:189], v[226:229], v[74:77]
	v_mfma_f32_16x16x32_f16 v[70:73], v[194:197], v[226:229], v[70:73]
	v_mfma_f32_16x16x32_f16 v[122:125], v[190:193], v[206:209], v[122:125]
	v_mfma_f32_16x16x32_f16 v[118:121], v[198:201], v[206:209], v[118:121]
	v_mfma_f32_16x16x32_f16 v[106:109], v[190:193], v[214:217], v[106:109]
	v_mfma_f32_16x16x32_f16 v[102:105], v[198:201], v[214:217], v[102:105]
	v_mfma_f32_16x16x32_f16 v[90:93], v[190:193], v[222:225], v[90:93]
	v_mfma_f32_16x16x32_f16 v[86:89], v[198:201], v[222:225], v[86:89]
	v_mfma_f32_16x16x32_f16 v[74:77], v[190:193], v[230:233], v[74:77]
	v_mfma_f32_16x16x32_f16 v[70:73], v[198:201], v[230:233], v[70:73]
	s_barrier
	ds_read_b128 v[202:205], v151 offset:49152
	ds_read_b128 v[206:209], v151 offset:50176
	ds_read_b128 v[210:213], v151 offset:51200
	ds_read_b128 v[214:217], v151 offset:52224
	ds_read_b128 v[218:221], v151 offset:53248
	ds_read_b128 v[222:225], v151 offset:54272
	ds_read_b128 v[226:229], v151 offset:55296
	ds_read_b128 v[230:233], v151 offset:56320
	global_load_lds_dwordx4 v[234:235], off
	s_add_i32 m0, s26, 0x2000
	s_add_u32 s22, s22, 0x40080
	v_lshl_add_u64 v[234:235], v[236:237], 0, s[36:37]
	s_addc_u32 s23, s23, 0
	s_add_i32 s26, s45, s30
	global_load_lds_dwordx4 v[234:235], off
	v_lshl_add_u64 v[234:235], s[22:23], 0, v[0:1]
	s_mov_b32 m0, s26
	s_nop 0
	global_load_lds_dwordx4 v[234:235], off
	v_lshl_add_u64 v[234:235], s[22:23], 0, v[138:139]
	s_add_i32 m0, s26, 0x2000
	s_nop 0
	global_load_lds_dwordx4 v[234:235], off
	v_lshl_add_u64 v[234:235], v[238:239], 0, s[36:37]
	s_mov_b32 m0, s39
	s_nop 0
	global_load_lds_dwordx4 v[234:235], off
	v_lshl_add_u64 v[234:235], v[240:241], 0, s[36:37]
	s_mov_b32 m0, s40
	s_nop 0
	global_load_lds_dwordx4 v[234:235], off
	s_waitcnt vmcnt(8) lgkmcnt(0)
	s_barrier
	v_mfma_f32_16x16x32_f16 v[66:69], v[144:147], v[202:205], v[66:69]
	v_mfma_f32_16x16x32_f16 v[62:65], v[178:181], v[202:205], v[62:65]
	v_mfma_f32_16x16x32_f16 v[50:53], v[144:147], v[210:213], v[50:53]
	v_mfma_f32_16x16x32_f16 v[46:49], v[178:181], v[210:213], v[46:49]
	v_mfma_f32_16x16x32_f16 v[34:37], v[144:147], v[218:221], v[34:37]
	v_mfma_f32_16x16x32_f16 v[30:33], v[178:181], v[218:221], v[30:33]
	v_mfma_f32_16x16x32_f16 v[18:21], v[144:147], v[226:229], v[18:21]
	v_mfma_f32_16x16x32_f16 v[14:17], v[178:181], v[226:229], v[14:17]
	v_mfma_f32_16x16x32_f16 v[66:69], v[152:155], v[206:209], v[66:69]
	v_mfma_f32_16x16x32_f16 v[62:65], v[182:185], v[206:209], v[62:65]
	v_mfma_f32_16x16x32_f16 v[50:53], v[152:155], v[214:217], v[50:53]
	v_mfma_f32_16x16x32_f16 v[46:49], v[182:185], v[214:217], v[46:49]
	v_mfma_f32_16x16x32_f16 v[34:37], v[152:155], v[222:225], v[34:37]
	v_mfma_f32_16x16x32_f16 v[30:33], v[182:185], v[222:225], v[30:33]
	v_mfma_f32_16x16x32_f16 v[18:21], v[152:155], v[230:233], v[18:21]
	v_mfma_f32_16x16x32_f16 v[14:17], v[182:185], v[230:233], v[14:17]
	v_mfma_f32_16x16x32_f16 v[58:61], v[186:189], v[202:205], v[58:61]
	v_mfma_f32_16x16x32_f16 v[54:57], v[194:197], v[202:205], v[54:57]
	v_mfma_f32_16x16x32_f16 v[42:45], v[186:189], v[210:213], v[42:45]
	v_mfma_f32_16x16x32_f16 v[38:41], v[194:197], v[210:213], v[38:41]
	v_mfma_f32_16x16x32_f16 v[26:29], v[186:189], v[218:221], v[26:29]
	v_mfma_f32_16x16x32_f16 v[22:25], v[194:197], v[218:221], v[22:25]
	v_mfma_f32_16x16x32_f16 v[10:13], v[186:189], v[226:229], v[10:13]
	v_mfma_f32_16x16x32_f16 v[6:9], v[194:197], v[226:229], v[6:9]
	v_mfma_f32_16x16x32_f16 v[58:61], v[190:193], v[206:209], v[58:61]
	v_mfma_f32_16x16x32_f16 v[54:57], v[198:201], v[206:209], v[54:57]
	v_mfma_f32_16x16x32_f16 v[42:45], v[190:193], v[214:217], v[42:45]
	v_mfma_f32_16x16x32_f16 v[38:41], v[198:201], v[214:217], v[38:41]
	v_mfma_f32_16x16x32_f16 v[26:29], v[190:193], v[222:225], v[26:29]
	v_mfma_f32_16x16x32_f16 v[22:25], v[198:201], v[222:225], v[22:25]
	v_mfma_f32_16x16x32_f16 v[10:13], v[190:193], v[230:233], v[10:13]
	v_mfma_f32_16x16x32_f16 v[6:9], v[198:201], v[230:233], v[6:9]
	s_barrier
	s_add_i32 s43, s43, 2
	s_add_u32 s41, s41, 0x100
	s_addc_u32 s42, s42, 0
	s_add_u32 s20, s20, 0x100
	s_addc_u32 s21, s21, 0
	s_cmp_gt_u32 s43, 13
	s_cbranch_scc0 .LBB0_175
	s_and_b64 vcc, exec, s[4:5]
	s_cbranch_vccz .LBB0_178
	s_barrier

; #define STAGE(bufoff, gbase, voff) do { _Pragma("unroll") for (int _i = 0; _i < 2; ++_i) \
;     __builtin_amdgcn_global_load_lds((const unsigned*)((const char*)(gbase) + (voff)[_i]), (LAS unsigned*)(lds + (bufoff) + ldsw + _i * 8192), 16, 0, 0); } while (0)
; #define LDA(dst, b, h) do { _Pragma("unroll") for (int m = 0; m < 4; ++m) _Pragma("unroll") for (int k = 0; k < 2; ++k) dst[m][k] = *(const LAS half8*)(lds + SA(b, h) + aoff + m * 2048 + k * 1024); } while (0)
; #define LDB(dst, b, h) do { _Pragma("unroll") for (int n = 0; n < 2; ++n) _Pragma("unroll") for (int k = 0; k < 2; ++k) dst[n][k] = *(const LAS half8*)(lds + SB(b, h) + boff + n * 2048 + k * 1024); } while (0)
; #define MMA(ai, bj, At_, Bt_) do { __builtin_amdgcn_s_setprio(1); \
;     _Pragma("unroll") for (int m = 0; m < 4; ++m) _Pragma("unroll") for (int n = 0; n < 2; ++n) _Pragma("unroll") for (int k = 0; k < 2; ++k) \
;       acc[ai][bj][m][n] = MFMA16(Bt_[n][k], At_[m][k], acc[ai][bj][m][n]); \
;     __builtin_amdgcn_s_setprio(0); } while (0)
; #define WAIT_V(n) asm volatile("s_waitcnt vmcnt(" #n ")" ::: "memory")
; #define WAIT_L(n) asm volatile("s_waitcnt lgkmcnt(" #n ")" ::: "memory")
; #define BAR __builtin_amdgcn_s_barrier()
; #define SCHED __builtin_amdgcn_sched_barrier(0)
; template <int EPI>
; DI void gemm_phase(const int wid_s, const h16* __restrict__ A, const h16* __restrict__ Bt, const int N, const int K, const EpiArgs ea) {
;     ...
;     const char* nA = (const char*)A + (size_t)nbrow * K * 2;
;     const char* nB = (const char*)Bt + (size_t)nbcol * K * 2;
;     for (int t = 0; t < nt; t += 2) {
;       const bool last = (t == nt - 2);
;       const char* a1 = cA + (size_t)(t + 1) * kstep;
;       const char* a2 = last ? nA : cA + (size_t)(t + 2) * kstep; const char* b2 = last ? nB : cB + (size_t)(t + 2) * kstep;
;       const char* a3 = a2 + kstep; const char* b3 = b2 + kstep;
;       LDB(B0, 0, 0); LDB(B1, 0, 1); SCHED; LDA(At, 0, 0); STAGE(SA(1, 1), a1 + hstep, voffA);
;       WAIT_V(8); WAIT_L(0); BAR; MMA(0, 0, At, B0); MMA(0, 1, At, B1); BAR; SCHED;
;       LDA(At, 0, 1); STAGE(SB(0, 0), b2, voffB); STAGE(SB(0, 1), b2 + hstep, voffB); STAGE(SA(0, 0), a2, voffA);
;       WAIT_V(8); WAIT_L(0); BAR; MMA(1, 0, At, B0); MMA(1, 1, At, B1); BAR; SCHED;
.LBB0_385:
	s_ashr_i32 s9, s8, 31
	s_lshl_b64 s[16:17], s[8:9], 11
	s_add_u32 s9, s92, s16
	s_addc_u32 s41, s93, s17
	s_ashr_i32 s11, s10, 31
	s_lshl_b64 s[18:19], s[10:11], 11
	v_readlane_b32 s11, v249, 29
	s_add_u32 s11, s11, s18
	v_readlane_b32 s26, v249, 31
	s_addc_u32 s42, s26, s19
	v_readlane_b32 s26, v249, 30
	s_add_u32 s43, s26, s22
	v_readlane_b32 s22, v249, 32
	s_addc_u32 s44, s22, s23
	s_add_u32 s45, s86, s20
	v_mov_b32_e32 v6, 0
	v_lshl_add_u64 v[144:145], v[140:141], 0, s[20:21]
	v_lshl_add_u64 v[146:147], v[142:143], 0, s[20:21]
	s_addc_u32 s46, s87, s21
	s_mov_b32 s47, -2
	s_mov_b64 s[20:21], 0
	s_add_u32 s22, s45, s20
	s_addc_u32 s23, s46, s21
	s_add_u32 s22, s22, 0x520e100
	s_addc_u32 s23, s23, 0
	s_add_u32 s48, s43, s20
	s_addc_u32 s49, s44, s21
	s_add_i32 s50, 0, 0x10000
	s_cmpk_eq_i32 s20, 0x700
	s_cselect_b32 s27, s41, s23
	s_cselect_b32 s26, s9, s22
	v_add_u32_e32 v177, s50, v148
	s_cselect_b32 s23, s42, s49
	s_cselect_b32 s22, s11, s48
	s_add_i32 s51, 0, 0x14000
	ds_read_b128 v[152:155], v177
	ds_read_b128 v[178:181], v177 offset:1024
	ds_read_b128 v[182:185], v177 offset:2048
	ds_read_b128 v[186:189], v177 offset:3072
	v_add_u32_e32 v177, s51, v148
	ds_read_b128 v[190:193], v177
	ds_read_b128 v[194:197], v177 offset:1024
	ds_read_b128 v[198:201], v177 offset:2048
	ds_read_b128 v[202:205], v177 offset:3072
	v_lshl_add_u64 v[238:239], v[146:147], 0, s[20:21]
	s_add_i32 m0, s13, 0xc000
	ds_read_b128 v[206:209], v151
	ds_read_b128 v[210:213], v151 offset:1024
	ds_read_b128 v[214:217], v151 offset:2048
	ds_read_b128 v[218:221], v151 offset:3072
	ds_read_b128 v[222:225], v151 offset:4096
	ds_read_b128 v[226:229], v151 offset:5120
	ds_read_b128 v[230:233], v151 offset:6144
	ds_read_b128 v[234:237], v151 offset:7168
	global_load_lds_dwordx4 v[238:239], off
	v_lshl_add_u64 v[238:239], v[144:145], 0, s[20:21]
	s_add_i32 m0, s13, 0xe000
	s_nop 0
	global_load_lds_dwordx4 v[238:239], off
	s_waitcnt vmcnt(8) lgkmcnt(0)
	s_barrier
	v_mfma_f32_16x16x32_f16 v[130:133], v[152:155], v[206:209], 0
	v_mfma_f32_16x16x32_f16 v[126:129], v[182:185], v[206:209], 0
	v_mfma_f32_16x16x32_f16 v[122:125], v[152:155], v[214:217], 0
	v_mfma_f32_16x16x32_f16 v[118:121], v[182:185], v[214:217], 0
	v_mfma_f32_16x16x32_f16 v[106:109], v[152:155], v[222:225], 0
	v_mfma_f32_16x16x32_f16 v[102:105], v[182:185], v[222:225], 0
	v_mfma_f32_16x16x32_f16 v[90:93], v[152:155], v[230:233], 0
	v_mfma_f32_16x16x32_f16 v[86:89], v[182:185], v[230:233], 0
	v_mfma_f32_16x16x32_f16 v[130:133], v[178:181], v[210:213], v[130:133]
	v_mfma_f32_16x16x32_f16 v[126:129], v[186:189], v[210:213], v[126:129]
	v_mfma_f32_16x16x32_f16 v[122:125], v[178:181], v[218:221], v[122:125]
	v_mfma_f32_16x16x32_f16 v[118:121], v[186:189], v[218:221], v[118:121]
	v_mfma_f32_16x16x32_f16 v[106:109], v[178:181], v[226:229], v[106:109]
	v_mfma_f32_16x16x32_f16 v[102:105], v[186:189], v[226:229], v[102:105]
	v_mfma_f32_16x16x32_f16 v[90:93], v[178:181], v[234:237], v[90:93]
	v_mfma_f32_16x16x32_f16 v[86:89], v[186:189], v[234:237], v[86:89]
	s_add_i32 s48, s50, s30
	v_lshl_add_u64 v[238:239], s[22:23], 0, v[0:1]
	s_mov_b32 m0, s48
	v_mfma_f32_16x16x32_f16 v[114:117], v[190:193], v[206:209], 0
	v_mfma_f32_16x16x32_f16 v[110:113], v[198:201], v[206:209], 0
	v_mfma_f32_16x16x32_f16 v[98:101], v[190:193], v[214:217], 0
	v_mfma_f32_16x16x32_f16 v[94:97], v[198:201], v[214:217], 0
	v_mfma_f32_16x16x32_f16 v[82:85], v[190:193], v[222:225], 0
	v_mfma_f32_16x16x32_f16 v[78:81], v[198:201], v[222:225], 0
	v_mfma_f32_16x16x32_f16 v[74:77], v[190:193], v[230:233], 0
	v_mfma_f32_16x16x32_f16 v[70:73], v[198:201], v[230:233], 0
	v_mfma_f32_16x16x32_f16 v[114:117], v[194:197], v[210:213], v[114:117]
	v_mfma_f32_16x16x32_f16 v[110:113], v[202:205], v[210:213], v[110:113]
	v_mfma_f32_16x16x32_f16 v[98:101], v[194:197], v[218:221], v[98:101]
	v_mfma_f32_16x16x32_f16 v[94:97], v[202:205], v[218:221], v[94:97]
	v_mfma_f32_16x16x32_f16 v[82:85], v[194:197], v[226:229], v[82:85]
	v_mfma_f32_16x16x32_f16 v[78:81], v[202:205], v[226:229], v[78:81]
	v_mfma_f32_16x16x32_f16 v[74:77], v[194:197], v[234:237], v[74:77]
	v_mfma_f32_16x16x32_f16 v[70:73], v[202:205], v[234:237], v[70:73]
	s_barrier
	ds_read_b128 v[206:209], v151 offset:16384
	ds_read_b128 v[210:213], v151 offset:17408
	ds_read_b128 v[214:217], v151 offset:18432
	ds_read_b128 v[218:221], v151 offset:19456
	ds_read_b128 v[222:225], v151 offset:20480
	ds_read_b128 v[226:229], v151 offset:21504
	ds_read_b128 v[230:233], v151 offset:22528
	ds_read_b128 v[234:237], v151 offset:23552
	global_load_lds_dwordx4 v[238:239], off
	s_add_i32 m0, s48, 0x2000
	s_add_u32 s48, s22, 0x40000
	v_lshl_add_u64 v[240:241], s[22:23], 0, v[2:3]
	s_addc_u32 s49, s23, 0
	s_add_i32 s50, s51, s30
	global_load_lds_dwordx4 v[240:241], off
	v_lshl_add_u64 v[242:243], s[48:49], 0, v[0:1]
	s_mov_b32 m0, s50
	v_lshl_add_u64 v[244:245], s[26:27], 0, v[134:135]
	global_load_lds_dwordx4 v[242:243], off
	v_lshl_add_u64 v[242:243], s[48:49], 0, v[2:3]
	s_add_i32 m0, s50, 0x2000
	s_nop 0
	global_load_lds_dwordx4 v[242:243], off
	v_lshl_add_u64 v[242:243], s[26:27], 0, v[138:139]
	s_mov_b32 m0, s13
	s_nop 0
	global_load_lds_dwordx4 v[242:243], off
	s_mov_b32 m0, s15
	s_nop 0
	global_load_lds_dwordx4 v[244:245], off
	s_waitcnt vmcnt(8) lgkmcnt(0)
	s_barrier
; #define STAGE(bufoff, gbase, voff) do { _Pragma("unroll") for (int _i = 0; _i < 2; ++_i) \
;     __builtin_amdgcn_global_load_lds((const unsigned*)((const char*)(gbase) + (voff)[_i]), (LAS unsigned*)(lds + (bufoff) + ldsw + _i * 8192), 16, 0, 0); } while (0)
; #define LDA(dst, b, h) do { _Pragma("unroll") for (int m = 0; m < 4; ++m) _Pragma("unroll") for (int k = 0; k < 2; ++k) dst[m][k] = *(const LAS half8*)(lds + SA(b, h) + aoff + m * 2048 + k * 1024); } while (0)
; #define LDB(dst, b, h) do { _Pragma("unroll") for (int n = 0; n < 2; ++n) _Pragma("unroll") for (int k = 0; k < 2; ++k) dst[n][k] = *(const LAS half8*)(lds + SB(b, h) + boff + n * 2048 + k * 1024); } while (0)
; #define MMA(ai, bj, At_, Bt_) do { __builtin_amdgcn_s_setprio(1); \
;     _Pragma("unroll") for (int m = 0; m < 4; ++m) _Pragma("unroll") for (int n = 0; n < 2; ++n) _Pragma("unroll") for (int k = 0; k < 2; ++k) \
;       acc[ai][bj][m][n] = MFMA16(Bt_[n][k], At_[m][k], acc[ai][bj][m][n]); \
;     __builtin_amdgcn_s_setprio(0); } while (0)
; #define WAIT_V(n) asm volatile("s_waitcnt vmcnt(" #n ")" ::: "memory")
; #define WAIT_L(n) asm volatile("s_waitcnt lgkmcnt(" #n ")" ::: "memory")
; #define BAR __builtin_amdgcn_s_barrier()
; #define SCHED __builtin_amdgcn_sched_barrier(0)
; template <int EPI>
; DI void gemm_phase(const int wid_s, const h16* __restrict__ A, const h16* __restrict__ Bt, const int N, const int K, const EpiArgs ea) {
;     ...
;       WAIT_V(8); WAIT_L(0); BAR; MMA(0, 0, At, B0); MMA(0, 1, At, B1); BAR; SCHED;
;       LDA(At, 0, 1); STAGE(SB(0, 0), b2, voffB); STAGE(SB(0, 1), b2 + hstep, voffB); STAGE(SA(0, 0), a2, voffA);
;       WAIT_V(8); WAIT_L(0); BAR; MMA(1, 0, At, B0); MMA(1, 1, At, B1); BAR; SCHED;
;       LDB(B0, 1, 0); LDB(B1, 1, 1); SCHED; LDA(At, 1, 0); STAGE(SA(0, 1), a2 + hstep, voffA);
;       WAIT_V(8); WAIT_L(0); BAR; MMA(0, 0, At, B0); MMA(0, 1, At, B1); BAR; SCHED;
	v_mfma_f32_16x16x32_f16 v[66:69], v[152:155], v[206:209], 0
	v_mfma_f32_16x16x32_f16 v[62:65], v[182:185], v[206:209], 0
	v_mfma_f32_16x16x32_f16 v[58:61], v[152:155], v[214:217], 0
	v_mfma_f32_16x16x32_f16 v[54:57], v[182:185], v[214:217], 0
	v_mfma_f32_16x16x32_f16 v[42:45], v[152:155], v[222:225], 0
	v_mfma_f32_16x16x32_f16 v[38:41], v[182:185], v[222:225], 0
	v_mfma_f32_16x16x32_f16 v[26:29], v[152:155], v[230:233], 0
	v_mfma_f32_16x16x32_f16 v[22:25], v[182:185], v[230:233], 0
	v_mfma_f32_16x16x32_f16 v[66:69], v[178:181], v[210:213], v[66:69]
	v_mfma_f32_16x16x32_f16 v[62:65], v[186:189], v[210:213], v[62:65]
	v_mfma_f32_16x16x32_f16 v[58:61], v[178:181], v[218:221], v[58:61]
	v_mfma_f32_16x16x32_f16 v[54:57], v[186:189], v[218:221], v[54:57]
	v_mfma_f32_16x16x32_f16 v[42:45], v[178:181], v[226:229], v[42:45]
	v_mfma_f32_16x16x32_f16 v[38:41], v[186:189], v[226:229], v[38:41]
	v_mfma_f32_16x16x32_f16 v[26:29], v[178:181], v[234:237], v[26:29]
	v_mfma_f32_16x16x32_f16 v[22:25], v[186:189], v[234:237], v[22:25]
	s_add_i32 s48, 0, 0x18000
	v_add_u32_e32 v177, s48, v148
	s_add_i32 s49, 0, 0x1c000
	v_mfma_f32_16x16x32_f16 v[50:53], v[190:193], v[206:209], 0
	v_mfma_f32_16x16x32_f16 v[46:49], v[198:201], v[206:209], 0
	v_mfma_f32_16x16x32_f16 v[34:37], v[190:193], v[214:217], 0
	v_mfma_f32_16x16x32_f16 v[30:33], v[198:201], v[214:217], 0
	v_mfma_f32_16x16x32_f16 v[18:21], v[190:193], v[222:225], 0
	v_mfma_f32_16x16x32_f16 v[14:17], v[198:201], v[222:225], 0
	v_mfma_f32_16x16x32_f16 v[10:13], v[190:193], v[230:233], 0
	v_mfma_f32_16x16x32_f16 v[6:9], v[198:201], v[230:233], 0
	v_mfma_f32_16x16x32_f16 v[50:53], v[194:197], v[210:213], v[50:53]
	v_mfma_f32_16x16x32_f16 v[46:49], v[202:205], v[210:213], v[46:49]
	v_mfma_f32_16x16x32_f16 v[34:37], v[194:197], v[218:221], v[34:37]
	v_mfma_f32_16x16x32_f16 v[30:33], v[202:205], v[218:221], v[30:33]
	v_mfma_f32_16x16x32_f16 v[18:21], v[194:197], v[226:229], v[18:21]
	v_mfma_f32_16x16x32_f16 v[14:17], v[202:205], v[226:229], v[14:17]
	v_mfma_f32_16x16x32_f16 v[10:13], v[194:197], v[234:237], v[10:13]
	v_mfma_f32_16x16x32_f16 v[6:9], v[202:205], v[234:237], v[6:9]
	s_barrier
	ds_read_b128 v[152:155], v177
	ds_read_b128 v[178:181], v177 offset:1024
	ds_read_b128 v[182:185], v177 offset:2048
	ds_read_b128 v[186:189], v177 offset:3072
	v_add_u32_e32 v177, s49, v148
	ds_read_b128 v[190:193], v177
	ds_read_b128 v[194:197], v177 offset:1024
	ds_read_b128 v[198:201], v177 offset:2048
	ds_read_b128 v[202:205], v177 offset:3072
	s_add_u32 s26, s26, 0x40000
	s_addc_u32 s27, s27, 0
	s_mov_b32 m0, s31
	v_lshl_add_u64 v[246:247], s[26:27], 0, v[138:139]
	ds_read_b128 v[206:209], v151 offset:32768
	ds_read_b128 v[210:213], v151 offset:33792
	ds_read_b128 v[214:217], v151 offset:34816
	ds_read_b128 v[218:221], v151 offset:35840
	ds_read_b128 v[222:225], v151 offset:36864
	ds_read_b128 v[226:229], v151 offset:37888
	ds_read_b128 v[230:233], v151 offset:38912
	ds_read_b128 v[234:237], v151 offset:39936
	global_load_lds_dwordx4 v[246:247], off
	v_lshl_add_u64 v[246:247], s[26:27], 0, v[134:135]
	s_mov_b32 m0, s38
	s_nop 0
	global_load_lds_dwordx4 v[246:247], off
	s_waitcnt vmcnt(8) lgkmcnt(0)
	s_barrier
	v_mfma_f32_16x16x32_f16 v[130:133], v[152:155], v[206:209], v[130:133]
	v_mfma_f32_16x16x32_f16 v[126:129], v[182:185], v[206:209], v[126:129]
	v_mfma_f32_16x16x32_f16 v[122:125], v[152:155], v[214:217], v[122:125]
	v_mfma_f32_16x16x32_f16 v[118:121], v[182:185], v[214:217], v[118:121]
	v_mfma_f32_16x16x32_f16 v[106:109], v[152:155], v[222:225], v[106:109]
	v_mfma_f32_16x16x32_f16 v[102:105], v[182:185], v[222:225], v[102:105]
	v_mfma_f32_16x16x32_f16 v[90:93], v[152:155], v[230:233], v[90:93]
	v_mfma_f32_16x16x32_f16 v[86:89], v[182:185], v[230:233], v[86:89]
	v_mfma_f32_16x16x32_f16 v[130:133], v[178:181], v[210:213], v[130:133]
	v_mfma_f32_16x16x32_f16 v[126:129], v[186:189], v[210:213], v[126:129]
	v_mfma_f32_16x16x32_f16 v[122:125], v[178:181], v[218:221], v[122:125]
	v_mfma_f32_16x16x32_f16 v[118:121], v[186:189], v[218:221], v[118:121]
	v_mfma_f32_16x16x32_f16 v[106:109], v[178:181], v[226:229], v[106:109]
	v_mfma_f32_16x16x32_f16 v[102:105], v[186:189], v[226:229], v[102:105]
	v_mfma_f32_16x16x32_f16 v[90:93], v[178:181], v[234:237], v[90:93]
	v_mfma_f32_16x16x32_f16 v[86:89], v[186:189], v[234:237], v[86:89]
	s_add_i32 s26, s48, s30
	v_lshl_add_u64 v[238:239], v[238:239], 0, s[36:37]
	s_mov_b32 m0, s26
	v_mfma_f32_16x16x32_f16 v[114:117], v[190:193], v[206:209], v[114:117]
	v_mfma_f32_16x16x32_f16 v[110:113], v[198:201], v[206:209], v[110:113]
	v_mfma_f32_16x16x32_f16 v[98:101], v[190:193], v[214:217], v[98:101]
	v_mfma_f32_16x16x32_f16 v[94:97], v[198:201], v[214:217], v[94:97]
	v_mfma_f32_16x16x32_f16 v[82:85], v[190:193], v[222:225], v[82:85]
	v_mfma_f32_16x16x32_f16 v[78:81], v[198:201], v[222:225], v[78:81]
	v_mfma_f32_16x16x32_f16 v[74:77], v[190:193], v[230:233], v[74:77]
	v_mfma_f32_16x16x32_f16 v[70:73], v[198:201], v[230:233], v[70:73]
	v_mfma_f32_16x16x32_f16 v[114:117], v[194:197], v[210:213], v[114:117]
	v_mfma_f32_16x16x32_f16 v[110:113], v[202:205], v[210:213], v[110:113]
	v_mfma_f32_16x16x32_f16 v[98:101], v[194:197], v[218:221], v[98:101]
	v_mfma_f32_16x16x32_f16 v[94:97], v[202:205], v[218:221], v[94:97]
	v_mfma_f32_16x16x32_f16 v[82:85], v[194:197], v[226:229], v[82:85]
	v_mfma_f32_16x16x32_f16 v[78:81], v[202:205], v[226:229], v[78:81]
	v_mfma_f32_16x16x32_f16 v[74:77], v[194:197], v[234:237], v[74:77]
	v_mfma_f32_16x16x32_f16 v[70:73], v[202:205], v[234:237], v[70:73]
	s_barrier
; #define STAGE(bufoff, gbase, voff) do { _Pragma("unroll") for (int _i = 0; _i < 2; ++_i) \
;     __builtin_amdgcn_global_load_lds((const unsigned*)((const char*)(gbase) + (voff)[_i]), (LAS unsigned*)(lds + (bufoff) + ldsw + _i * 8192), 16, 0, 0); } while (0)
; #define LDA(dst, b, h) do { _Pragma("unroll") for (int m = 0; m < 4; ++m) _Pragma("unroll") for (int k = 0; k < 2; ++k) dst[m][k] = *(const LAS half8*)(lds + SA(b, h) + aoff + m * 2048 + k * 1024); } while (0)
; #define LDB(dst, b, h) do { _Pragma("unroll") for (int n = 0; n < 2; ++n) _Pragma("unroll") for (int k = 0; k < 2; ++k) dst[n][k] = *(const LAS half8*)(lds + SB(b, h) + boff + n * 2048 + k * 1024); } while (0)
; #define MMA(ai, bj, At_, Bt_) do { __builtin_amdgcn_s_setprio(1); \
;     _Pragma("unroll") for (int m = 0; m < 4; ++m) _Pragma("unroll") for (int n = 0; n < 2; ++n) _Pragma("unroll") for (int k = 0; k < 2; ++k) \
;       acc[ai][bj][m][n] = MFMA16(Bt_[n][k], At_[m][k], acc[ai][bj][m][n]); \
;     __builtin_amdgcn_s_setprio(0); } while (0)
; #define WAIT_V(n) asm volatile("s_waitcnt vmcnt(" #n ")" ::: "memory")
; #define WAIT_L(n) asm volatile("s_waitcnt lgkmcnt(" #n ")" ::: "memory")
; #define BAR __builtin_amdgcn_s_barrier()
; #define SCHED __builtin_amdgcn_sched_barrier(0)
; template <int EPI>
; DI void gemm_phase(const int wid_s, const h16* __restrict__ A, const h16* __restrict__ Bt, const int N, const int K, const EpiArgs ea) {
;     ...
;     for (int t = 0; t < nt; t += 2) {
;       const bool last = (t == nt - 2);
;       const char* a1 = cA + (size_t)(t + 1) * kstep;
;       const char* a2 = last ? nA : cA + (size_t)(t + 2) * kstep; const char* b2 = last ? nB : cB + (size_t)(t + 2) * kstep;
;       const char* a3 = a2 + kstep; const char* b3 = b2 + kstep;
;       LDB(B0, 0, 0); LDB(B1, 0, 1); SCHED; LDA(At, 0, 0); STAGE(SA(1, 1), a1 + hstep, voffA);
;       WAIT_V(8); WAIT_L(0); BAR; MMA(0, 0, At, B0); MMA(0, 1, At, B1); BAR; SCHED;
;     ...
;       LDA(At, 1, 1); STAGE(SB(1, 0), b3, voffB); STAGE(SB(1, 1), b3 + hstep, voffB); STAGE(SA(1, 0), a3, voffA);
;       WAIT_V(8); WAIT_L(0); BAR; MMA(1, 0, At, B0); MMA(1, 1, At, B1); BAR; SCHED;
	ds_read_b128 v[206:209], v151 offset:49152
	ds_read_b128 v[210:213], v151 offset:50176
	ds_read_b128 v[214:217], v151 offset:51200
	ds_read_b128 v[218:221], v151 offset:52224
	ds_read_b128 v[222:225], v151 offset:53248
	ds_read_b128 v[226:229], v151 offset:54272
	ds_read_b128 v[230:233], v151 offset:55296
	ds_read_b128 v[234:237], v151 offset:56320
	global_load_lds_dwordx4 v[238:239], off
	s_add_i32 m0, s26, 0x2000
	s_add_u32 s22, s22, 0x40080
	v_lshl_add_u64 v[238:239], v[240:241], 0, s[36:37]
	s_addc_u32 s23, s23, 0
	s_add_i32 s26, s49, s30
	global_load_lds_dwordx4 v[238:239], off
	v_lshl_add_u64 v[238:239], s[22:23], 0, v[0:1]
	s_mov_b32 m0, s26
	s_nop 0
	global_load_lds_dwordx4 v[238:239], off
	v_lshl_add_u64 v[238:239], s[22:23], 0, v[2:3]
	s_add_i32 m0, s26, 0x2000
	s_nop 0
	global_load_lds_dwordx4 v[238:239], off
	v_lshl_add_u64 v[238:239], v[242:243], 0, s[36:37]
	s_mov_b32 m0, s39
	s_nop 0
	global_load_lds_dwordx4 v[238:239], off
	v_lshl_add_u64 v[238:239], v[244:245], 0, s[36:37]
	s_mov_b32 m0, s40
	s_nop 0
	global_load_lds_dwordx4 v[238:239], off
	s_waitcnt vmcnt(8) lgkmcnt(0)
	s_barrier
	v_mfma_f32_16x16x32_f16 v[66:69], v[152:155], v[206:209], v[66:69]
	v_mfma_f32_16x16x32_f16 v[62:65], v[182:185], v[206:209], v[62:65]
	v_mfma_f32_16x16x32_f16 v[58:61], v[152:155], v[214:217], v[58:61]
	v_mfma_f32_16x16x32_f16 v[54:57], v[182:185], v[214:217], v[54:57]
	v_mfma_f32_16x16x32_f16 v[42:45], v[152:155], v[222:225], v[42:45]
	v_mfma_f32_16x16x32_f16 v[38:41], v[182:185], v[222:225], v[38:41]
	v_mfma_f32_16x16x32_f16 v[26:29], v[152:155], v[230:233], v[26:29]
	v_mfma_f32_16x16x32_f16 v[22:25], v[182:185], v[230:233], v[22:25]
	v_mfma_f32_16x16x32_f16 v[66:69], v[178:181], v[210:213], v[66:69]
	v_mfma_f32_16x16x32_f16 v[62:65], v[186:189], v[210:213], v[62:65]
	v_mfma_f32_16x16x32_f16 v[58:61], v[178:181], v[218:221], v[58:61]
	v_mfma_f32_16x16x32_f16 v[54:57], v[186:189], v[218:221], v[54:57]
	v_mfma_f32_16x16x32_f16 v[42:45], v[178:181], v[226:229], v[42:45]
	v_mfma_f32_16x16x32_f16 v[38:41], v[186:189], v[226:229], v[38:41]
	v_mfma_f32_16x16x32_f16 v[26:29], v[178:181], v[234:237], v[26:29]
	v_mfma_f32_16x16x32_f16 v[22:25], v[186:189], v[234:237], v[22:25]
	v_mfma_f32_16x16x32_f16 v[50:53], v[190:193], v[206:209], v[50:53]
	v_mfma_f32_16x16x32_f16 v[46:49], v[198:201], v[206:209], v[46:49]
	v_mfma_f32_16x16x32_f16 v[34:37], v[190:193], v[214:217], v[34:37]
	v_mfma_f32_16x16x32_f16 v[30:33], v[198:201], v[214:217], v[30:33]
	v_mfma_f32_16x16x32_f16 v[18:21], v[190:193], v[222:225], v[18:21]
	v_mfma_f32_16x16x32_f16 v[14:17], v[198:201], v[222:225], v[14:17]
	v_mfma_f32_16x16x32_f16 v[10:13], v[190:193], v[230:233], v[10:13]
	v_mfma_f32_16x16x32_f16 v[6:9], v[198:201], v[230:233], v[6:9]
	v_mfma_f32_16x16x32_f16 v[50:53], v[194:197], v[210:213], v[50:53]
	v_mfma_f32_16x16x32_f16 v[46:49], v[202:205], v[210:213], v[46:49]
	v_mfma_f32_16x16x32_f16 v[34:37], v[194:197], v[218:221], v[34:37]
	v_mfma_f32_16x16x32_f16 v[30:33], v[202:205], v[218:221], v[30:33]
	v_mfma_f32_16x16x32_f16 v[18:21], v[194:197], v[226:229], v[18:21]
	v_mfma_f32_16x16x32_f16 v[14:17], v[202:205], v[226:229], v[14:17]
	v_mfma_f32_16x16x32_f16 v[10:13], v[194:197], v[234:237], v[10:13]
	v_mfma_f32_16x16x32_f16 v[6:9], v[202:205], v[234:237], v[6:9]
	s_barrier
	s_add_i32 s47, s47, 2
	s_add_u32 s20, s20, 0x100
	s_addc_u32 s21, s21, 0
	s_cmp_gt_u32 s47, 13
.LBB0_386:
	s_add_u32 s22, s45, s20
	s_addc_u32 s23, s46, s21
	s_add_u32 s22, s22, 0x520e100
	s_addc_u32 s23, s23, 0
	s_add_u32 s48, s43, s20
	s_addc_u32 s49, s44, s21
	s_add_i32 s50, 0, 0x10000
	s_cmpk_eq_i32 s20, 0x700
	s_cselect_b32 s27, s41, s23
	s_cselect_b32 s26, s9, s22
	v_add_u32_e32 v177, s50, v148
	s_cselect_b32 s23, s42, s49
	s_cselect_b32 s22, s11, s48
	s_add_i32 s51, 0, 0x14000
	ds_read_b128 v[152:155], v177
	ds_read_b128 v[178:181], v177 offset:1024
	ds_read_b128 v[182:185], v177 offset:2048
	ds_read_b128 v[186:189], v177 offset:3072
	v_add_u32_e32 v177, s51, v148
	ds_read_b128 v[190:193], v177
	ds_read_b128 v[194:197], v177 offset:1024
	ds_read_b128 v[198:201], v177 offset:2048
	ds_read_b128 v[202:205], v177 offset:3072
	v_lshl_add_u64 v[238:239], v[146:147], 0, s[20:21]
	s_add_i32 m0, s13, 0xc000
	ds_read_b128 v[206:209], v151
	ds_read_b128 v[210:213], v151 offset:1024
	ds_read_b128 v[214:217], v151 offset:2048
	ds_read_b128 v[218:221], v151 offset:3072
	ds_read_b128 v[222:225], v151 offset:4096
	ds_read_b128 v[226:229], v151 offset:5120
	ds_read_b128 v[230:233], v151 offset:6144
	ds_read_b128 v[234:237], v151 offset:7168
	global_load_lds_dwordx4 v[238:239], off
	v_lshl_add_u64 v[238:239], v[144:145], 0, s[20:21]
	s_add_i32 m0, s13, 0xe000
	s_nop 0
	global_load_lds_dwordx4 v[238:239], off
	s_waitcnt vmcnt(8) lgkmcnt(0)
	s_barrier
; #define STAGE(bufoff, gbase, voff) do { _Pragma("unroll") for (int _i = 0; _i < 2; ++_i) \
;     __builtin_amdgcn_global_load_lds((const unsigned*)((const char*)(gbase) + (voff)[_i]), (LAS unsigned*)(lds + (bufoff) + ldsw + _i * 8192), 16, 0, 0); } while (0)
; #define LDA(dst, b, h) do { _Pragma("unroll") for (int m = 0; m < 4; ++m) _Pragma("unroll") for (int k = 0; k < 2; ++k) dst[m][k] = *(const LAS half8*)(lds + SA(b, h) + aoff + m * 2048 + k * 1024); } while (0)
; #define LDB(dst, b, h) do { _Pragma("unroll") for (int n = 0; n < 2; ++n) _Pragma("unroll") for (int k = 0; k < 2; ++k) dst[n][k] = *(const LAS half8*)(lds + SB(b, h) + boff + n * 2048 + k * 1024); } while (0)
; #define MMA(ai, bj, At_, Bt_) do { __builtin_amdgcn_s_setprio(1); \
;     _Pragma("unroll") for (int m = 0; m < 4; ++m) _Pragma("unroll") for (int n = 0; n < 2; ++n) _Pragma("unroll") for (int k = 0; k < 2; ++k) \
;       acc[ai][bj][m][n] = MFMA16(Bt_[n][k], At_[m][k], acc[ai][bj][m][n]); \
;     __builtin_amdgcn_s_setprio(0); } while (0)
; #define WAIT_V(n) asm volatile("s_waitcnt vmcnt(" #n ")" ::: "memory")
; #define WAIT_L(n) asm volatile("s_waitcnt lgkmcnt(" #n ")" ::: "memory")
; #define BAR __builtin_amdgcn_s_barrier()
; #define SCHED __builtin_amdgcn_sched_barrier(0)
; template <int EPI>
; DI void gemm_phase(const int wid_s, const h16* __restrict__ A, const h16* __restrict__ Bt, const int N, const int K, const EpiArgs ea) {
;     ...
;       WAIT_V(8); WAIT_L(0); BAR; MMA(0, 0, At, B0); MMA(0, 1, At, B1); BAR; SCHED;
;       LDA(At, 0, 1); STAGE(SB(0, 0), b2, voffB); STAGE(SB(0, 1), b2 + hstep, voffB); STAGE(SA(0, 0), a2, voffA);
;       WAIT_V(8); WAIT_L(0); BAR; MMA(1, 0, At, B0); MMA(1, 1, At, B1); BAR; SCHED;
;       LDB(B0, 1, 0); LDB(B1, 1, 1); SCHED; LDA(At, 1, 0); STAGE(SA(0, 1), a2 + hstep, voffA);
;       WAIT_V(8); WAIT_L(0); BAR; MMA(0, 0, At, B0); MMA(0, 1, At, B1); BAR; SCHED;
	v_mfma_f32_16x16x32_f16 v[130:133], v[152:155], v[206:209], v[130:133]
	v_mfma_f32_16x16x32_f16 v[126:129], v[182:185], v[206:209], v[126:129]
	v_mfma_f32_16x16x32_f16 v[122:125], v[152:155], v[214:217], v[122:125]
	v_mfma_f32_16x16x32_f16 v[118:121], v[182:185], v[214:217], v[118:121]
	v_mfma_f32_16x16x32_f16 v[106:109], v[152:155], v[222:225], v[106:109]
	v_mfma_f32_16x16x32_f16 v[102:105], v[182:185], v[222:225], v[102:105]
	v_mfma_f32_16x16x32_f16 v[90:93], v[152:155], v[230:233], v[90:93]
	v_mfma_f32_16x16x32_f16 v[86:89], v[182:185], v[230:233], v[86:89]
	v_mfma_f32_16x16x32_f16 v[130:133], v[178:181], v[210:213], v[130:133]
	v_mfma_f32_16x16x32_f16 v[126:129], v[186:189], v[210:213], v[126:129]
	v_mfma_f32_16x16x32_f16 v[122:125], v[178:181], v[218:221], v[122:125]
	v_mfma_f32_16x16x32_f16 v[118:121], v[186:189], v[218:221], v[118:121]
	v_mfma_f32_16x16x32_f16 v[106:109], v[178:181], v[226:229], v[106:109]
	v_mfma_f32_16x16x32_f16 v[102:105], v[186:189], v[226:229], v[102:105]
	v_mfma_f32_16x16x32_f16 v[90:93], v[178:181], v[234:237], v[90:93]
	v_mfma_f32_16x16x32_f16 v[86:89], v[186:189], v[234:237], v[86:89]
	s_add_i32 s48, s50, s30
	v_lshl_add_u64 v[238:239], s[22:23], 0, v[0:1]
	s_mov_b32 m0, s48
	v_mfma_f32_16x16x32_f16 v[114:117], v[190:193], v[206:209], v[114:117]
	v_mfma_f32_16x16x32_f16 v[110:113], v[198:201], v[206:209], v[110:113]
	v_mfma_f32_16x16x32_f16 v[98:101], v[190:193], v[214:217], v[98:101]
	v_mfma_f32_16x16x32_f16 v[94:97], v[198:201], v[214:217], v[94:97]
	v_mfma_f32_16x16x32_f16 v[82:85], v[190:193], v[222:225], v[82:85]
	v_mfma_f32_16x16x32_f16 v[78:81], v[198:201], v[222:225], v[78:81]
	v_mfma_f32_16x16x32_f16 v[74:77], v[190:193], v[230:233], v[74:77]
	v_mfma_f32_16x16x32_f16 v[70:73], v[198:201], v[230:233], v[70:73]
	v_mfma_f32_16x16x32_f16 v[114:117], v[194:197], v[210:213], v[114:117]
	v_mfma_f32_16x16x32_f16 v[110:113], v[202:205], v[210:213], v[110:113]
	v_mfma_f32_16x16x32_f16 v[98:101], v[194:197], v[218:221], v[98:101]
	v_mfma_f32_16x16x32_f16 v[94:97], v[202:205], v[218:221], v[94:97]
	v_mfma_f32_16x16x32_f16 v[82:85], v[194:197], v[226:229], v[82:85]
	v_mfma_f32_16x16x32_f16 v[78:81], v[202:205], v[226:229], v[78:81]
	v_mfma_f32_16x16x32_f16 v[74:77], v[194:197], v[234:237], v[74:77]
	v_mfma_f32_16x16x32_f16 v[70:73], v[202:205], v[234:237], v[70:73]
	s_barrier
	ds_read_b128 v[206:209], v151 offset:16384
	ds_read_b128 v[210:213], v151 offset:17408
	ds_read_b128 v[214:217], v151 offset:18432
	ds_read_b128 v[218:221], v151 offset:19456
	ds_read_b128 v[222:225], v151 offset:20480
	ds_read_b128 v[226:229], v151 offset:21504
	ds_read_b128 v[230:233], v151 offset:22528
	ds_read_b128 v[234:237], v151 offset:23552
	global_load_lds_dwordx4 v[238:239], off
	s_add_i32 m0, s48, 0x2000
	s_add_u32 s48, s22, 0x40000
	v_lshl_add_u64 v[240:241], s[22:23], 0, v[2:3]
	s_addc_u32 s49, s23, 0
	s_add_i32 s50, s51, s30
	global_load_lds_dwordx4 v[240:241], off
	v_lshl_add_u64 v[242:243], s[48:49], 0, v[0:1]
	s_mov_b32 m0, s50
	v_lshl_add_u64 v[244:245], s[26:27], 0, v[134:135]
	global_load_lds_dwordx4 v[242:243], off
	v_lshl_add_u64 v[242:243], s[48:49], 0, v[2:3]
	s_add_i32 m0, s50, 0x2000
	s_nop 0
	global_load_lds_dwordx4 v[242:243], off
	v_lshl_add_u64 v[242:243], s[26:27], 0, v[138:139]
	s_mov_b32 m0, s13
	s_nop 0
	global_load_lds_dwordx4 v[242:243], off
	s_mov_b32 m0, s15
	s_nop 0
	global_load_lds_dwordx4 v[244:245], off
	s_waitcnt vmcnt(8) lgkmcnt(0)
	s_barrier
	v_mfma_f32_16x16x32_f16 v[66:69], v[152:155], v[206:209], v[66:69]
	v_mfma_f32_16x16x32_f16 v[62:65], v[182:185], v[206:209], v[62:65]
	v_mfma_f32_16x16x32_f16 v[58:61], v[152:155], v[214:217], v[58:61]
	v_mfma_f32_16x16x32_f16 v[54:57], v[182:185], v[214:217], v[54:57]
	v_mfma_f32_16x16x32_f16 v[42:45], v[152:155], v[222:225], v[42:45]
	v_mfma_f32_16x16x32_f16 v[38:41], v[182:185], v[222:225], v[38:41]
	v_mfma_f32_16x16x32_f16 v[26:29], v[152:155], v[230:233], v[26:29]
	v_mfma_f32_16x16x32_f16 v[22:25], v[182:185], v[230:233], v[22:25]
	v_mfma_f32_16x16x32_f16 v[66:69], v[178:181], v[210:213], v[66:69]
	v_mfma_f32_16x16x32_f16 v[62:65], v[186:189], v[210:213], v[62:65]
	v_mfma_f32_16x16x32_f16 v[58:61], v[178:181], v[218:221], v[58:61]
	v_mfma_f32_16x16x32_f16 v[54:57], v[186:189], v[218:221], v[54:57]
	v_mfma_f32_16x16x32_f16 v[42:45], v[178:181], v[226:229], v[42:45]
	v_mfma_f32_16x16x32_f16 v[38:41], v[186:189], v[226:229], v[38:41]
	v_mfma_f32_16x16x32_f16 v[26:29], v[178:181], v[234:237], v[26:29]
	v_mfma_f32_16x16x32_f16 v[22:25], v[186:189], v[234:237], v[22:25]
	s_add_i32 s48, 0, 0x18000
	v_add_u32_e32 v177, s48, v148
	s_add_i32 s49, 0, 0x1c000
	v_mfma_f32_16x16x32_f16 v[50:53], v[190:193], v[206:209], v[50:53]
	v_mfma_f32_16x16x32_f16 v[46:49], v[198:201], v[206:209], v[46:49]
	v_mfma_f32_16x16x32_f16 v[34:37], v[190:193], v[214:217], v[34:37]
	v_mfma_f32_16x16x32_f16 v[30:33], v[198:201], v[214:217], v[30:33]
	v_mfma_f32_16x16x32_f16 v[18:21], v[190:193], v[222:225], v[18:21]
	v_mfma_f32_16x16x32_f16 v[14:17], v[198:201], v[222:225], v[14:17]
	v_mfma_f32_16x16x32_f16 v[10:13], v[190:193], v[230:233], v[10:13]
	v_mfma_f32_16x16x32_f16 v[6:9], v[198:201], v[230:233], v[6:9]
	v_mfma_f32_16x16x32_f16 v[50:53], v[194:197], v[210:213], v[50:53]
	v_mfma_f32_16x16x32_f16 v[46:49], v[202:205], v[210:213], v[46:49]
	v_mfma_f32_16x16x32_f16 v[34:37], v[194:197], v[218:221], v[34:37]
	v_mfma_f32_16x16x32_f16 v[30:33], v[202:205], v[218:221], v[30:33]
	v_mfma_f32_16x16x32_f16 v[18:21], v[194:197], v[226:229], v[18:21]
	v_mfma_f32_16x16x32_f16 v[14:17], v[202:205], v[226:229], v[14:17]
	v_mfma_f32_16x16x32_f16 v[10:13], v[194:197], v[234:237], v[10:13]
	v_mfma_f32_16x16x32_f16 v[6:9], v[202:205], v[234:237], v[6:9]
	s_barrier
; #define STAGE(bufoff, gbase, voff) do { _Pragma("unroll") for (int _i = 0; _i < 2; ++_i) \
;     __builtin_amdgcn_global_load_lds((const unsigned*)((const char*)(gbase) + (voff)[_i]), (LAS unsigned*)(lds + (bufoff) + ldsw + _i * 8192), 16, 0, 0); } while (0)
; #define LDA(dst, b, h) do { _Pragma("unroll") for (int m = 0; m < 4; ++m) _Pragma("unroll") for (int k = 0; k < 2; ++k) dst[m][k] = *(const LAS half8*)(lds + SA(b, h) + aoff + m * 2048 + k * 1024); } while (0)
; #define LDB(dst, b, h) do { _Pragma("unroll") for (int n = 0; n < 2; ++n) _Pragma("unroll") for (int k = 0; k < 2; ++k) dst[n][k] = *(const LAS half8*)(lds + SB(b, h) + boff + n * 2048 + k * 1024); } while (0)
; #define MMA(ai, bj, At_, Bt_) do { __builtin_amdgcn_s_setprio(1); \
;     _Pragma("unroll") for (int m = 0; m < 4; ++m) _Pragma("unroll") for (int n = 0; n < 2; ++n) _Pragma("unroll") for (int k = 0; k < 2; ++k) \
;       acc[ai][bj][m][n] = MFMA16(Bt_[n][k], At_[m][k], acc[ai][bj][m][n]); \
;     __builtin_amdgcn_s_setprio(0); } while (0)
; #define WAIT_V(n) asm volatile("s_waitcnt vmcnt(" #n ")" ::: "memory")
; #define WAIT_L(n) asm volatile("s_waitcnt lgkmcnt(" #n ")" ::: "memory")
; #define BAR __builtin_amdgcn_s_barrier()
; #define SCHED __builtin_amdgcn_sched_barrier(0)
; template <int EPI>
; DI void gemm_phase(const int wid_s, const h16* __restrict__ A, const h16* __restrict__ Bt, const int N, const int K, const EpiArgs ea) {
;     ...
;       LDB(B0, 1, 0); LDB(B1, 1, 1); SCHED; LDA(At, 1, 0); STAGE(SA(0, 1), a2 + hstep, voffA);
;       WAIT_V(8); WAIT_L(0); BAR; MMA(0, 0, At, B0); MMA(0, 1, At, B1); BAR; SCHED;
;       LDA(At, 1, 1); STAGE(SB(1, 0), b3, voffB); STAGE(SB(1, 1), b3 + hstep, voffB); STAGE(SA(1, 0), a3, voffA);
;       WAIT_V(8); WAIT_L(0); BAR; MMA(1, 0, At, B0); MMA(1, 1, At, B1); BAR; SCHED;
;     }
;     if (wr == 0) BAR;
	ds_read_b128 v[152:155], v177
	ds_read_b128 v[178:181], v177 offset:1024
	ds_read_b128 v[182:185], v177 offset:2048
	ds_read_b128 v[186:189], v177 offset:3072
	v_add_u32_e32 v177, s49, v148
	ds_read_b128 v[190:193], v177
	ds_read_b128 v[194:197], v177 offset:1024
	ds_read_b128 v[198:201], v177 offset:2048
	ds_read_b128 v[202:205], v177 offset:3072
	s_add_u32 s26, s26, 0x40000
	s_addc_u32 s27, s27, 0
	s_mov_b32 m0, s31
	v_lshl_add_u64 v[246:247], s[26:27], 0, v[138:139]
	ds_read_b128 v[206:209], v151 offset:32768
	ds_read_b128 v[210:213], v151 offset:33792
	ds_read_b128 v[214:217], v151 offset:34816
	ds_read_b128 v[218:221], v151 offset:35840
	ds_read_b128 v[222:225], v151 offset:36864
	ds_read_b128 v[226:229], v151 offset:37888
	ds_read_b128 v[230:233], v151 offset:38912
	ds_read_b128 v[234:237], v151 offset:39936
	global_load_lds_dwordx4 v[246:247], off
	v_lshl_add_u64 v[246:247], s[26:27], 0, v[134:135]
	s_mov_b32 m0, s38
	s_nop 0
	global_load_lds_dwordx4 v[246:247], off
	s_waitcnt vmcnt(8) lgkmcnt(0)
	s_barrier
	v_mfma_f32_16x16x32_f16 v[130:133], v[152:155], v[206:209], v[130:133]
	v_mfma_f32_16x16x32_f16 v[126:129], v[182:185], v[206:209], v[126:129]
	v_mfma_f32_16x16x32_f16 v[122:125], v[152:155], v[214:217], v[122:125]
	v_mfma_f32_16x16x32_f16 v[118:121], v[182:185], v[214:217], v[118:121]
	v_mfma_f32_16x16x32_f16 v[106:109], v[152:155], v[222:225], v[106:109]
	v_mfma_f32_16x16x32_f16 v[102:105], v[182:185], v[222:225], v[102:105]
	v_mfma_f32_16x16x32_f16 v[90:93], v[152:155], v[230:233], v[90:93]
	v_mfma_f32_16x16x32_f16 v[86:89], v[182:185], v[230:233], v[86:89]
	v_mfma_f32_16x16x32_f16 v[130:133], v[178:181], v[210:213], v[130:133]
	v_mfma_f32_16x16x32_f16 v[126:129], v[186:189], v[210:213], v[126:129]
	v_mfma_f32_16x16x32_f16 v[122:125], v[178:181], v[218:221], v[122:125]
	v_mfma_f32_16x16x32_f16 v[118:121], v[186:189], v[218:221], v[118:121]
	v_mfma_f32_16x16x32_f16 v[106:109], v[178:181], v[226:229], v[106:109]
	v_mfma_f32_16x16x32_f16 v[102:105], v[186:189], v[226:229], v[102:105]
	v_mfma_f32_16x16x32_f16 v[90:93], v[178:181], v[234:237], v[90:93]
	v_mfma_f32_16x16x32_f16 v[86:89], v[186:189], v[234:237], v[86:89]
	s_add_i32 s26, s48, s30
	v_lshl_add_u64 v[238:239], v[238:239], 0, s[36:37]
	s_mov_b32 m0, s26
	v_mfma_f32_16x16x32_f16 v[114:117], v[190:193], v[206:209], v[114:117]
	v_mfma_f32_16x16x32_f16 v[110:113], v[198:201], v[206:209], v[110:113]
	v_mfma_f32_16x16x32_f16 v[98:101], v[190:193], v[214:217], v[98:101]
	v_mfma_f32_16x16x32_f16 v[94:97], v[198:201], v[214:217], v[94:97]
	v_mfma_f32_16x16x32_f16 v[82:85], v[190:193], v[222:225], v[82:85]
	v_mfma_f32_16x16x32_f16 v[78:81], v[198:201], v[222:225], v[78:81]
	v_mfma_f32_16x16x32_f16 v[74:77], v[190:193], v[230:233], v[74:77]
	v_mfma_f32_16x16x32_f16 v[70:73], v[198:201], v[230:233], v[70:73]
	v_mfma_f32_16x16x32_f16 v[114:117], v[194:197], v[210:213], v[114:117]
	v_mfma_f32_16x16x32_f16 v[110:113], v[202:205], v[210:213], v[110:113]
	v_mfma_f32_16x16x32_f16 v[98:101], v[194:197], v[218:221], v[98:101]
	v_mfma_f32_16x16x32_f16 v[94:97], v[202:205], v[218:221], v[94:97]
	v_mfma_f32_16x16x32_f16 v[82:85], v[194:197], v[226:229], v[82:85]
	v_mfma_f32_16x16x32_f16 v[78:81], v[202:205], v[226:229], v[78:81]
	v_mfma_f32_16x16x32_f16 v[74:77], v[194:197], v[234:237], v[74:77]
	v_mfma_f32_16x16x32_f16 v[70:73], v[202:205], v[234:237], v[70:73]
	s_barrier
	ds_read_b128 v[206:209], v151 offset:49152
	ds_read_b128 v[210:213], v151 offset:50176
	ds_read_b128 v[214:217], v151 offset:51200
	ds_read_b128 v[218:221], v151 offset:52224
	ds_read_b128 v[222:225], v151 offset:53248
	ds_read_b128 v[226:229], v151 offset:54272
	ds_read_b128 v[230:233], v151 offset:55296
	ds_read_b128 v[234:237], v151 offset:56320
	global_load_lds_dwordx4 v[238:239], off
	s_add_i32 m0, s26, 0x2000
	s_add_u32 s22, s22, 0x40080
	v_lshl_add_u64 v[238:239], v[240:241], 0, s[36:37]
	s_addc_u32 s23, s23, 0
	s_add_i32 s26, s49, s30
	global_load_lds_dwordx4 v[238:239], off
	v_lshl_add_u64 v[238:239], s[22:23], 0, v[0:1]
	s_mov_b32 m0, s26
	s_nop 0
	global_load_lds_dwordx4 v[238:239], off
	v_lshl_add_u64 v[238:239], s[22:23], 0, v[2:3]
	s_add_i32 m0, s26, 0x2000
	s_nop 0
	global_load_lds_dwordx4 v[238:239], off
	v_lshl_add_u64 v[238:239], v[242:243], 0, s[36:37]
	s_mov_b32 m0, s39
	s_nop 0
	global_load_lds_dwordx4 v[238:239], off
	v_lshl_add_u64 v[238:239], v[244:245], 0, s[36:37]
	s_mov_b32 m0, s40
	s_nop 0
	global_load_lds_dwordx4 v[238:239], off
	s_waitcnt vmcnt(8) lgkmcnt(0)
	s_barrier
	v_mfma_f32_16x16x32_f16 v[66:69], v[152:155], v[206:209], v[66:69]
	v_mfma_f32_16x16x32_f16 v[62:65], v[182:185], v[206:209], v[62:65]
	v_mfma_f32_16x16x32_f16 v[58:61], v[152:155], v[214:217], v[58:61]
	v_mfma_f32_16x16x32_f16 v[54:57], v[182:185], v[214:217], v[54:57]
	v_mfma_f32_16x16x32_f16 v[42:45], v[152:155], v[222:225], v[42:45]
	v_mfma_f32_16x16x32_f16 v[38:41], v[182:185], v[222:225], v[38:41]
	v_mfma_f32_16x16x32_f16 v[26:29], v[152:155], v[230:233], v[26:29]
	v_mfma_f32_16x16x32_f16 v[22:25], v[182:185], v[230:233], v[22:25]
	v_mfma_f32_16x16x32_f16 v[66:69], v[178:181], v[210:213], v[66:69]
	v_mfma_f32_16x16x32_f16 v[62:65], v[186:189], v[210:213], v[62:65]
	v_mfma_f32_16x16x32_f16 v[58:61], v[178:181], v[218:221], v[58:61]
	v_mfma_f32_16x16x32_f16 v[54:57], v[186:189], v[218:221], v[54:57]
	v_mfma_f32_16x16x32_f16 v[42:45], v[178:181], v[226:229], v[42:45]
	v_mfma_f32_16x16x32_f16 v[38:41], v[186:189], v[226:229], v[38:41]
	v_mfma_f32_16x16x32_f16 v[26:29], v[178:181], v[234:237], v[26:29]
	v_mfma_f32_16x16x32_f16 v[22:25], v[186:189], v[234:237], v[22:25]
	v_mfma_f32_16x16x32_f16 v[50:53], v[190:193], v[206:209], v[50:53]
	v_mfma_f32_16x16x32_f16 v[46:49], v[198:201], v[206:209], v[46:49]
	v_mfma_f32_16x16x32_f16 v[34:37], v[190:193], v[214:217], v[34:37]
	v_mfma_f32_16x16x32_f16 v[30:33], v[198:201], v[214:217], v[30:33]
	v_mfma_f32_16x16x32_f16 v[18:21], v[190:193], v[222:225], v[18:21]
	v_mfma_f32_16x16x32_f16 v[14:17], v[198:201], v[222:225], v[14:17]
	v_mfma_f32_16x16x32_f16 v[10:13], v[190:193], v[230:233], v[10:13]
	v_mfma_f32_16x16x32_f16 v[6:9], v[198:201], v[230:233], v[6:9]
	v_mfma_f32_16x16x32_f16 v[50:53], v[194:197], v[210:213], v[50:53]
	v_mfma_f32_16x16x32_f16 v[46:49], v[202:205], v[210:213], v[46:49]
	v_mfma_f32_16x16x32_f16 v[34:37], v[194:197], v[218:221], v[34:37]
	v_mfma_f32_16x16x32_f16 v[30:33], v[202:205], v[218:221], v[30:33]
	v_mfma_f32_16x16x32_f16 v[18:21], v[194:197], v[226:229], v[18:21]
	v_mfma_f32_16x16x32_f16 v[14:17], v[202:205], v[226:229], v[14:17]
	v_mfma_f32_16x16x32_f16 v[10:13], v[194:197], v[234:237], v[10:13]
	v_mfma_f32_16x16x32_f16 v[6:9], v[202:205], v[234:237], v[6:9]
	s_barrier
	s_add_i32 s47, s47, 2
	s_add_u32 s20, s20, 0x100
	s_addc_u32 s21, s21, 0
	s_cmp_gt_u32 s47, 13
	s_cbranch_scc0 .LBB0_386
	s_and_b64 vcc, exec, s[4:5]
	s_cbranch_vccz .LBB0_389
	s_barrier
